# GEMM K-loops: s_setprio 1 for the wave half in its load segment (after the post-MFMA barrier), s_setprio 0 before its pre-MFMA wait; replaces hipcc's MFMA-block raise
# speedup vs baseline: 1.0039x; 1.0039x over previous
.LBB0_103:
	s_add_u32 s8, s4, 0xfffc0080
	s_addc_u32 s9, s5, -1
	s_add_i32 s20, 0, 0x10000
	s_cmp_eq_u32 s88, 12
	s_cselect_b32 s55, s51, s9
	s_cselect_b32 s54, s50, s8
	v_add_u32_e32 v150, s20, v154
	s_cselect_b32 s9, s7, s87
	s_cselect_b32 s8, s49, s57
	s_add_i32 s37, 0, 0x14000
	ds_read_b128 v[142:145], v150
	ds_read_b128 v[146:149], v150 offset:1024
	ds_read_b128 v[156:159], v150 offset:2048
	ds_read_b128 v[160:163], v150 offset:3072
	v_add_u32_e32 v150, s37, v154
	ds_read_b128 v[164:167], v150
	ds_read_b128 v[168:171], v150 offset:1024
	ds_read_b128 v[172:175], v150 offset:2048
	ds_read_b128 v[202:205], v150 offset:3072
	s_add_i32 m0, s62, 0xc000
	ds_read_b128 v[206:209], v155
	ds_read_b128 v[222:225], v155 offset:1024
	ds_read_b128 v[226:229], v155 offset:2048
	ds_read_b128 v[230:233], v155 offset:3072
	ds_read_b128 v[234:237], v155 offset:4096
	ds_read_b128 v[238:241], v155 offset:5120
	ds_read_b128 v[242:245], v155 offset:6144
	ds_read_b128 v[246:249], v155 offset:7168
	global_load_lds_dwordx4 v136, s[4:5]
	s_add_i32 m0, s62, 0xe000
	s_nop 0
	global_load_lds_dwordx4 v138, s[4:5]
	s_setprio 0
	s_waitcnt vmcnt(8)
	s_waitcnt lgkmcnt(0)
	s_barrier
	s_waitcnt lgkmcnt(0)
	v_mfma_f32_16x16x32_bf16 v[126:129], v[142:145], v[206:209], v[126:129]
	v_mfma_f32_16x16x32_bf16 v[122:125], v[156:159], v[206:209], v[122:125]
	v_mfma_f32_16x16x32_bf16 v[110:113], v[142:145], v[226:229], v[110:113]
	v_mfma_f32_16x16x32_bf16 v[106:109], v[156:159], v[226:229], v[106:109]
	v_mfma_f32_16x16x32_bf16 v[94:97], v[142:145], v[234:237], v[94:97]
	v_mfma_f32_16x16x32_bf16 v[90:93], v[156:159], v[234:237], v[90:93]
	v_mfma_f32_16x16x32_bf16 v[78:81], v[142:145], v[242:245], v[78:81]
	v_mfma_f32_16x16x32_bf16 v[74:77], v[156:159], v[242:245], v[74:77]
	v_mfma_f32_16x16x32_bf16 v[126:129], v[146:149], v[222:225], v[126:129]
	v_mfma_f32_16x16x32_bf16 v[122:125], v[160:163], v[222:225], v[122:125]
	v_mfma_f32_16x16x32_bf16 v[110:113], v[146:149], v[230:233], v[110:113]
	v_mfma_f32_16x16x32_bf16 v[106:109], v[160:163], v[230:233], v[106:109]
	v_mfma_f32_16x16x32_bf16 v[94:97], v[146:149], v[238:241], v[94:97]
	v_mfma_f32_16x16x32_bf16 v[90:93], v[160:163], v[238:241], v[90:93]
	v_mfma_f32_16x16x32_bf16 v[78:81], v[146:149], v[246:249], v[78:81]
	v_mfma_f32_16x16x32_bf16 v[74:77], v[160:163], v[246:249], v[74:77]
	v_mfma_f32_16x16x32_bf16 v[118:121], v[164:167], v[206:209], v[118:121]
	v_mfma_f32_16x16x32_bf16 v[114:117], v[172:175], v[206:209], v[114:117]
	v_mfma_f32_16x16x32_bf16 v[102:105], v[164:167], v[226:229], v[102:105]
	v_mfma_f32_16x16x32_bf16 v[98:101], v[172:175], v[226:229], v[98:101]
	v_mfma_f32_16x16x32_bf16 v[86:89], v[164:167], v[234:237], v[86:89]
	v_mfma_f32_16x16x32_bf16 v[82:85], v[172:175], v[234:237], v[82:85]
	v_mfma_f32_16x16x32_bf16 v[70:73], v[164:167], v[242:245], v[70:73]
	v_mfma_f32_16x16x32_bf16 v[66:69], v[172:175], v[242:245], v[66:69]
	v_mfma_f32_16x16x32_bf16 v[118:121], v[168:171], v[222:225], v[118:121]
	v_mfma_f32_16x16x32_bf16 v[114:117], v[202:205], v[222:225], v[114:117]
	v_mfma_f32_16x16x32_bf16 v[102:105], v[168:171], v[230:233], v[102:105]
	v_mfma_f32_16x16x32_bf16 v[98:101], v[202:205], v[230:233], v[98:101]
	v_mfma_f32_16x16x32_bf16 v[86:89], v[168:171], v[238:241], v[86:89]
	v_mfma_f32_16x16x32_bf16 v[82:85], v[202:205], v[238:241], v[82:85]
	v_mfma_f32_16x16x32_bf16 v[70:73], v[168:171], v[246:249], v[70:73]
	v_mfma_f32_16x16x32_bf16 v[66:69], v[202:205], v[246:249], v[66:69]
	s_barrier
	s_setprio 1
	s_add_i32 s20, s20, s61
	v_lshl_add_u64 v[150:151], s[8:9], 0, v[0:1]
	s_mov_b32 m0, s20
	ds_read_b128 v[206:209], v155 offset:16384
	ds_read_b128 v[222:225], v155 offset:17408
	ds_read_b128 v[226:229], v155 offset:18432
	ds_read_b128 v[230:233], v155 offset:19456
	ds_read_b128 v[234:237], v155 offset:20480
	ds_read_b128 v[238:241], v155 offset:21504
	ds_read_b128 v[242:245], v155 offset:22528
	ds_read_b128 v[246:249], v155 offset:23552
	global_load_lds_dwordx4 v[150:151], off
	s_add_i32 m0, s20, 0x2000
	s_add_u32 s20, s8, 0x40000
	v_lshl_add_u64 v[176:177], s[8:9], 0, v[134:135]
	s_addc_u32 s21, s9, 0
	s_add_i32 s37, s37, s61
	global_load_lds_dwordx4 v[176:177], off
	s_mov_b32 m0, s37
	v_lshl_add_u64 v[180:181], s[54:55], 0, v[132:133]
	global_load_lds_dwordx4 v0, s[20:21]
	s_add_i32 m0, s37, 0x2000
	s_nop 0
	global_load_lds_dwordx4 v134, s[20:21]
	v_lshl_add_u64 v[178:179], s[54:55], 0, v[130:131]
	s_mov_b32 m0, s62
	s_nop 0
	global_load_lds_dwordx4 v[178:179], off
	s_mov_b32 m0, s63
	s_nop 0
	global_load_lds_dwordx4 v[180:181], off
	s_setprio 0
	s_waitcnt vmcnt(8)
	s_waitcnt lgkmcnt(0)
	s_barrier
	s_waitcnt lgkmcnt(0)
	v_mfma_f32_16x16x32_bf16 v[62:65], v[142:145], v[206:209], v[62:65]
	v_mfma_f32_16x16x32_bf16 v[58:61], v[156:159], v[206:209], v[58:61]
	v_mfma_f32_16x16x32_bf16 v[46:49], v[142:145], v[226:229], v[46:49]
	v_mfma_f32_16x16x32_bf16 v[42:45], v[156:159], v[226:229], v[42:45]
	v_mfma_f32_16x16x32_bf16 v[30:33], v[142:145], v[234:237], v[30:33]
	v_mfma_f32_16x16x32_bf16 v[26:29], v[156:159], v[234:237], v[26:29]
	v_mfma_f32_16x16x32_bf16 v[14:17], v[142:145], v[242:245], v[14:17]
	v_mfma_f32_16x16x32_bf16 v[10:13], v[156:159], v[242:245], v[10:13]
	v_mfma_f32_16x16x32_bf16 v[62:65], v[146:149], v[222:225], v[62:65]
	v_mfma_f32_16x16x32_bf16 v[58:61], v[160:163], v[222:225], v[58:61]
	v_mfma_f32_16x16x32_bf16 v[46:49], v[146:149], v[230:233], v[46:49]
	v_mfma_f32_16x16x32_bf16 v[42:45], v[160:163], v[230:233], v[42:45]
	v_mfma_f32_16x16x32_bf16 v[30:33], v[146:149], v[238:241], v[30:33]
	v_mfma_f32_16x16x32_bf16 v[26:29], v[160:163], v[238:241], v[26:29]
	v_mfma_f32_16x16x32_bf16 v[14:17], v[146:149], v[246:249], v[14:17]
	v_mfma_f32_16x16x32_bf16 v[10:13], v[160:163], v[246:249], v[10:13]
	v_mfma_f32_16x16x32_bf16 v[54:57], v[164:167], v[206:209], v[54:57]
	v_mfma_f32_16x16x32_bf16 v[50:53], v[172:175], v[206:209], v[50:53]
	v_mfma_f32_16x16x32_bf16 v[38:41], v[164:167], v[226:229], v[38:41]
	v_mfma_f32_16x16x32_bf16 v[34:37], v[172:175], v[226:229], v[34:37]
	v_mfma_f32_16x16x32_bf16 v[22:25], v[164:167], v[234:237], v[22:25]
	v_mfma_f32_16x16x32_bf16 v[18:21], v[172:175], v[234:237], v[18:21]
	v_mfma_f32_16x16x32_bf16 v[6:9], v[164:167], v[242:245], v[6:9]
	v_mfma_f32_16x16x32_bf16 v[2:5], v[172:175], v[242:245], v[2:5]
	v_mfma_f32_16x16x32_bf16 v[54:57], v[168:171], v[222:225], v[54:57]
	v_mfma_f32_16x16x32_bf16 v[50:53], v[202:205], v[222:225], v[50:53]
	v_mfma_f32_16x16x32_bf16 v[38:41], v[168:171], v[230:233], v[38:41]
	v_mfma_f32_16x16x32_bf16 v[34:37], v[202:205], v[230:233], v[34:37]
	v_mfma_f32_16x16x32_bf16 v[22:25], v[168:171], v[238:241], v[22:25]
	v_mfma_f32_16x16x32_bf16 v[18:21], v[202:205], v[238:241], v[18:21]
	v_mfma_f32_16x16x32_bf16 v[6:9], v[168:171], v[246:249], v[6:9]
	v_mfma_f32_16x16x32_bf16 v[2:5], v[202:205], v[246:249], v[2:5]
	s_barrier
	s_setprio 1
	s_add_i32 s37, 0, 0x18000
	s_add_i32 s77, 0, 0x1c000
	v_add_u32_e32 v160, s37, v154
	v_add_u32_e32 v182, s77, v154
	ds_read_b128 v[142:145], v160
	ds_read_b128 v[146:149], v160 offset:1024
	ds_read_b128 v[156:159], v160 offset:2048
	ds_read_b128 v[160:163], v160 offset:3072
	ds_read_b128 v[164:167], v182
	ds_read_b128 v[168:171], v182 offset:1024
	ds_read_b128 v[172:175], v182 offset:2048
	ds_read_b128 v[202:205], v182 offset:3072
	s_add_u32 s20, s54, 0x40000
	s_addc_u32 s21, s55, 0
	s_mov_b32 m0, s64
	ds_read_b128 v[206:209], v155 offset:32768
	ds_read_b128 v[222:225], v155 offset:33792
	ds_read_b128 v[226:229], v155 offset:34816
	ds_read_b128 v[230:233], v155 offset:35840
	ds_read_b128 v[234:237], v155 offset:36864
	ds_read_b128 v[238:241], v155 offset:37888
	ds_read_b128 v[242:245], v155 offset:38912
	ds_read_b128 v[246:249], v155 offset:39936
	global_load_lds_dwordx4 v130, s[20:21]
	v_lshl_add_u64 v[182:183], s[20:21], 0, v[132:133]
	s_mov_b32 m0, s65
	s_nop 0
	global_load_lds_dwordx4 v[182:183], off
	s_setprio 0
	s_waitcnt vmcnt(8)
	s_waitcnt lgkmcnt(0)
	s_barrier
	s_waitcnt lgkmcnt(0)
	v_mfma_f32_16x16x32_bf16 v[126:129], v[142:145], v[206:209], v[126:129]
	v_mfma_f32_16x16x32_bf16 v[122:125], v[156:159], v[206:209], v[122:125]
	v_mfma_f32_16x16x32_bf16 v[110:113], v[142:145], v[226:229], v[110:113]
	v_mfma_f32_16x16x32_bf16 v[106:109], v[156:159], v[226:229], v[106:109]
	v_mfma_f32_16x16x32_bf16 v[94:97], v[142:145], v[234:237], v[94:97]
	v_mfma_f32_16x16x32_bf16 v[90:93], v[156:159], v[234:237], v[90:93]
	v_mfma_f32_16x16x32_bf16 v[78:81], v[142:145], v[242:245], v[78:81]
	v_mfma_f32_16x16x32_bf16 v[74:77], v[156:159], v[242:245], v[74:77]
	v_mfma_f32_16x16x32_bf16 v[126:129], v[146:149], v[222:225], v[126:129]
	v_mfma_f32_16x16x32_bf16 v[122:125], v[160:163], v[222:225], v[122:125]
	v_mfma_f32_16x16x32_bf16 v[110:113], v[146:149], v[230:233], v[110:113]
	v_mfma_f32_16x16x32_bf16 v[106:109], v[160:163], v[230:233], v[106:109]
	v_mfma_f32_16x16x32_bf16 v[94:97], v[146:149], v[238:241], v[94:97]
	v_mfma_f32_16x16x32_bf16 v[90:93], v[160:163], v[238:241], v[90:93]
	v_mfma_f32_16x16x32_bf16 v[78:81], v[146:149], v[246:249], v[78:81]
	v_mfma_f32_16x16x32_bf16 v[74:77], v[160:163], v[246:249], v[74:77]
	v_mfma_f32_16x16x32_bf16 v[118:121], v[164:167], v[206:209], v[118:121]
	v_mfma_f32_16x16x32_bf16 v[114:117], v[172:175], v[206:209], v[114:117]
	v_mfma_f32_16x16x32_bf16 v[102:105], v[164:167], v[226:229], v[102:105]
	v_mfma_f32_16x16x32_bf16 v[98:101], v[172:175], v[226:229], v[98:101]
	v_mfma_f32_16x16x32_bf16 v[86:89], v[164:167], v[234:237], v[86:89]
	v_mfma_f32_16x16x32_bf16 v[82:85], v[172:175], v[234:237], v[82:85]
	v_mfma_f32_16x16x32_bf16 v[70:73], v[164:167], v[242:245], v[70:73]
	v_mfma_f32_16x16x32_bf16 v[66:69], v[172:175], v[242:245], v[66:69]
	v_mfma_f32_16x16x32_bf16 v[118:121], v[168:171], v[222:225], v[118:121]
	v_mfma_f32_16x16x32_bf16 v[114:117], v[202:205], v[222:225], v[114:117]
	v_mfma_f32_16x16x32_bf16 v[102:105], v[168:171], v[230:233], v[102:105]
	v_mfma_f32_16x16x32_bf16 v[98:101], v[202:205], v[230:233], v[98:101]
	v_mfma_f32_16x16x32_bf16 v[86:89], v[168:171], v[238:241], v[86:89]
	v_mfma_f32_16x16x32_bf16 v[82:85], v[202:205], v[238:241], v[82:85]
	v_mfma_f32_16x16x32_bf16 v[70:73], v[168:171], v[246:249], v[70:73]
	v_mfma_f32_16x16x32_bf16 v[66:69], v[202:205], v[246:249], v[66:69]
	s_barrier
	s_setprio 1
	s_add_i32 s20, s37, s61
	v_lshl_add_u64 v[150:151], v[150:151], 0, s[24:25]
	s_mov_b32 m0, s20
	ds_read_b128 v[206:209], v155 offset:49152
	ds_read_b128 v[222:225], v155 offset:50176
	ds_read_b128 v[226:229], v155 offset:51200
	ds_read_b128 v[230:233], v155 offset:52224
	ds_read_b128 v[234:237], v155 offset:53248
	ds_read_b128 v[238:241], v155 offset:54272
	ds_read_b128 v[242:245], v155 offset:55296
	ds_read_b128 v[246:249], v155 offset:56320
	global_load_lds_dwordx4 v[150:151], off
	s_add_i32 m0, s20, 0x2000
	s_add_u32 s8, s8, 0x40080
	v_lshl_add_u64 v[150:151], v[176:177], 0, s[24:25]
	s_addc_u32 s9, s9, 0
	s_add_i32 s20, s77, s61
	global_load_lds_dwordx4 v[150:151], off
	s_mov_b32 m0, s20
	s_nop 0
	global_load_lds_dwordx4 v0, s[8:9]
	s_add_i32 m0, s20, 0x2000
	s_nop 0
	global_load_lds_dwordx4 v134, s[8:9]
	v_lshl_add_u64 v[150:151], v[178:179], 0, s[24:25]
	s_mov_b32 m0, s67
	s_nop 0
	global_load_lds_dwordx4 v[150:151], off
	v_lshl_add_u64 v[150:151], v[180:181], 0, s[24:25]
	s_mov_b32 m0, s68
	s_nop 0
	global_load_lds_dwordx4 v[150:151], off
	s_setprio 0
	s_waitcnt vmcnt(8)
	s_waitcnt lgkmcnt(0)
	s_barrier
	s_waitcnt lgkmcnt(0)
	v_mfma_f32_16x16x32_bf16 v[62:65], v[142:145], v[206:209], v[62:65]
	v_mfma_f32_16x16x32_bf16 v[58:61], v[156:159], v[206:209], v[58:61]
	v_mfma_f32_16x16x32_bf16 v[46:49], v[142:145], v[226:229], v[46:49]
	v_mfma_f32_16x16x32_bf16 v[42:45], v[156:159], v[226:229], v[42:45]
	v_mfma_f32_16x16x32_bf16 v[30:33], v[142:145], v[234:237], v[30:33]
	v_mfma_f32_16x16x32_bf16 v[26:29], v[156:159], v[234:237], v[26:29]
	v_mfma_f32_16x16x32_bf16 v[14:17], v[142:145], v[242:245], v[14:17]
	v_mfma_f32_16x16x32_bf16 v[10:13], v[156:159], v[242:245], v[10:13]
	v_mfma_f32_16x16x32_bf16 v[62:65], v[146:149], v[222:225], v[62:65]
	v_mfma_f32_16x16x32_bf16 v[58:61], v[160:163], v[222:225], v[58:61]
	v_mfma_f32_16x16x32_bf16 v[46:49], v[146:149], v[230:233], v[46:49]
	v_mfma_f32_16x16x32_bf16 v[42:45], v[160:163], v[230:233], v[42:45]
	v_mfma_f32_16x16x32_bf16 v[30:33], v[146:149], v[238:241], v[30:33]
	v_mfma_f32_16x16x32_bf16 v[26:29], v[160:163], v[238:241], v[26:29]
	v_mfma_f32_16x16x32_bf16 v[14:17], v[146:149], v[246:249], v[14:17]
	v_mfma_f32_16x16x32_bf16 v[10:13], v[160:163], v[246:249], v[10:13]
	v_mfma_f32_16x16x32_bf16 v[54:57], v[164:167], v[206:209], v[54:57]
	v_mfma_f32_16x16x32_bf16 v[50:53], v[172:175], v[206:209], v[50:53]
	v_mfma_f32_16x16x32_bf16 v[38:41], v[164:167], v[226:229], v[38:41]
	v_mfma_f32_16x16x32_bf16 v[34:37], v[172:175], v[226:229], v[34:37]
	v_mfma_f32_16x16x32_bf16 v[22:25], v[164:167], v[234:237], v[22:25]
	v_mfma_f32_16x16x32_bf16 v[18:21], v[172:175], v[234:237], v[18:21]
	v_mfma_f32_16x16x32_bf16 v[6:9], v[164:167], v[242:245], v[6:9]
	v_mfma_f32_16x16x32_bf16 v[2:5], v[172:175], v[242:245], v[2:5]
	v_mfma_f32_16x16x32_bf16 v[54:57], v[168:171], v[222:225], v[54:57]
	v_mfma_f32_16x16x32_bf16 v[50:53], v[202:205], v[222:225], v[50:53]
	v_mfma_f32_16x16x32_bf16 v[38:41], v[168:171], v[230:233], v[38:41]
	v_mfma_f32_16x16x32_bf16 v[34:37], v[202:205], v[230:233], v[34:37]
	v_mfma_f32_16x16x32_bf16 v[22:25], v[168:171], v[238:241], v[22:25]
	v_mfma_f32_16x16x32_bf16 v[18:21], v[202:205], v[238:241], v[18:21]
	v_mfma_f32_16x16x32_bf16 v[6:9], v[168:171], v[246:249], v[6:9]
	v_mfma_f32_16x16x32_bf16 v[2:5], v[202:205], v[246:249], v[2:5]
	s_barrier
	s_setprio 1
	s_add_i32 s88, s88, 2
	s_add_u32 s4, s4, 0x100
	s_addc_u32 s5, s5, 0
	s_add_u32 s57, s57, 0x100
	s_addc_u32 s87, s87, 0
	s_cmp_gt_u32 s88, 13
	s_cbranch_scc0 .LBB0_103
	s_and_b64 vcc, exec, s[46:47]
	s_cbranch_vccz .LBB0_106
	s_barrier

.LBB0_436:
	s_add_u32 s37, s52, s56
	s_addc_u32 s57, s53, 0
	s_add_u32 s58, s37, 0x100
	s_addc_u32 s59, s57, 0
	s_and_b64 s[20:21], s[54:55], exec
	s_cselect_b32 s59, s45, s59
	s_cselect_b32 s58, s44, s58
	s_add_u32 s20, s50, s56
	s_addc_u32 s21, s51, 0
	s_add_u32 s56, s20, 0x100
	s_addc_u32 s60, s21, 0
	s_add_i32 s78, 0, 0x10000
	s_and_b64 s[20:21], s[54:55], exec
	s_cselect_b32 s61, s19, s60
	s_cselect_b32 s60, s49, s56
	s_add_i32 s20, 0, 0x14000
	s_add_u32 s64, s37, 0x10080
	s_addc_u32 s65, s57, 0
	s_add_i32 s37, s78, s70
	s_add_i32 m0, s71, 0xc000
	s_add_i32 s21, s71, 0xe000
	s_add_i32 s77, s37, 0x2000
	v_add_u32_e32 v0, s78, v142
	s_add_u32 s62, s60, 0x10000
	ds_read_b128 v[138:141], v0
	ds_read_b128 v[144:147], v0 offset:1024
	ds_read_b128 v[148:151], v0 offset:2048
	ds_read_b128 v[152:155], v0 offset:3072
	v_add_u32_e32 v0, s20, v142
	s_addc_u32 s63, s61, 0
	s_add_i32 s82, s20, s70
	ds_read_b128 v[156:159], v0
	ds_read_b128 v[160:163], v0 offset:1024
	ds_read_b128 v[164:167], v0 offset:2048
	ds_read_b128 v[168:171], v0 offset:3072
	s_add_i32 s83, s82, 0x2000
	s_add_i32 vcc_hi, 0, 0x18000
	s_add_i32 vcc_lo, 0, 0x1c000
	s_add_u32 s56, s58, 0x10000
	s_addc_u32 s57, s59, 0
	s_add_i32 s97, vcc_hi, s70
	s_add_i32 s96, s97, 0x2000
	s_add_u32 s54, s60, 0x10080
	s_addc_u32 s55, s61, 0
	s_add_i32 s78, vcc_lo, s70
	s_add_i32 s20, s78, 0x2000
	ds_read_b128 v[172:175], v143
	ds_read_b128 v[202:205], v143 offset:1024
	ds_read_b128 v[206:209], v143 offset:2048
	ds_read_b128 v[222:225], v143 offset:3072
	ds_read_b128 v[226:229], v143 offset:4096
	ds_read_b128 v[230:233], v143 offset:5120
	ds_read_b128 v[234:237], v143 offset:6144
	ds_read_b128 v[238:241], v143 offset:7168
	global_load_lds_dwordx4 v130, s[64:65]
	s_mov_b32 m0, s21
	s_nop 0
	global_load_lds_dwordx4 v132, s[64:65]
	s_setprio 0
	s_waitcnt vmcnt(8)
	s_waitcnt lgkmcnt(0)
	s_barrier
	s_waitcnt lgkmcnt(0)
	v_mfma_f32_16x16x32_bf16 v[126:129], v[138:141], v[172:175], v[126:129]
	v_mfma_f32_16x16x32_bf16 v[122:125], v[148:151], v[172:175], v[122:125]
	v_mfma_f32_16x16x32_bf16 v[118:121], v[138:141], v[206:209], v[118:121]
	v_mfma_f32_16x16x32_bf16 v[114:117], v[148:151], v[206:209], v[114:117]
	v_mfma_f32_16x16x32_bf16 v[110:113], v[138:141], v[226:229], v[110:113]
	v_mfma_f32_16x16x32_bf16 v[106:109], v[148:151], v[226:229], v[106:109]
	v_mfma_f32_16x16x32_bf16 v[102:105], v[138:141], v[234:237], v[102:105]
	v_mfma_f32_16x16x32_bf16 v[98:101], v[148:151], v[234:237], v[98:101]
	v_mfma_f32_16x16x32_bf16 v[126:129], v[144:147], v[202:205], v[126:129]
	v_mfma_f32_16x16x32_bf16 v[122:125], v[152:155], v[202:205], v[122:125]
	v_mfma_f32_16x16x32_bf16 v[118:121], v[144:147], v[222:225], v[118:121]
	v_mfma_f32_16x16x32_bf16 v[114:117], v[152:155], v[222:225], v[114:117]
	v_mfma_f32_16x16x32_bf16 v[110:113], v[144:147], v[230:233], v[110:113]
	v_mfma_f32_16x16x32_bf16 v[106:109], v[152:155], v[230:233], v[106:109]
	v_mfma_f32_16x16x32_bf16 v[102:105], v[144:147], v[238:241], v[102:105]
	v_mfma_f32_16x16x32_bf16 v[98:101], v[152:155], v[238:241], v[98:101]
	v_mfma_f32_16x16x32_bf16 v[62:65], v[156:159], v[172:175], v[62:65]
	v_mfma_f32_16x16x32_bf16 v[58:61], v[164:167], v[172:175], v[58:61]
	v_mfma_f32_16x16x32_bf16 v[54:57], v[156:159], v[206:209], v[54:57]
	v_mfma_f32_16x16x32_bf16 v[50:53], v[164:167], v[206:209], v[50:53]
	v_mfma_f32_16x16x32_bf16 v[46:49], v[156:159], v[226:229], v[46:49]
	v_mfma_f32_16x16x32_bf16 v[42:45], v[164:167], v[226:229], v[42:45]
	v_mfma_f32_16x16x32_bf16 v[38:41], v[156:159], v[234:237], v[38:41]
	v_mfma_f32_16x16x32_bf16 v[34:37], v[164:167], v[234:237], v[34:37]
	v_mfma_f32_16x16x32_bf16 v[62:65], v[160:163], v[202:205], v[62:65]
	v_mfma_f32_16x16x32_bf16 v[58:61], v[168:171], v[202:205], v[58:61]
	v_mfma_f32_16x16x32_bf16 v[54:57], v[160:163], v[222:225], v[54:57]
	v_mfma_f32_16x16x32_bf16 v[50:53], v[168:171], v[222:225], v[50:53]
	v_mfma_f32_16x16x32_bf16 v[46:49], v[160:163], v[230:233], v[46:49]
	v_mfma_f32_16x16x32_bf16 v[42:45], v[168:171], v[230:233], v[42:45]
	v_mfma_f32_16x16x32_bf16 v[38:41], v[160:163], v[238:241], v[38:41]
	v_mfma_f32_16x16x32_bf16 v[34:37], v[168:171], v[238:241], v[34:37]
	s_barrier
	s_setprio 1
	s_mov_b32 m0, s37
	v_lshl_add_u64 v[176:177], s[60:61], 0, v[130:131]
	ds_read_b128 v[172:175], v143 offset:16384
	ds_read_b128 v[202:205], v143 offset:17408
	ds_read_b128 v[206:209], v143 offset:18432
	ds_read_b128 v[222:225], v143 offset:19456
	ds_read_b128 v[226:229], v143 offset:20480
	ds_read_b128 v[230:233], v143 offset:21504
	ds_read_b128 v[234:237], v143 offset:22528
	ds_read_b128 v[238:241], v143 offset:23552
	global_load_lds_dwordx4 v[176:177], off
	v_lshl_add_u64 v[178:179], s[60:61], 0, v[132:133]
	s_mov_b32 m0, s77
	global_load_lds_dwordx4 v[178:179], off
	s_mov_b32 m0, s82
	v_lshl_add_u64 v[182:183], s[58:59], 0, v[132:133]
	global_load_lds_dwordx4 v130, s[62:63]
	s_mov_b32 m0, s83
	s_nop 0
	global_load_lds_dwordx4 v132, s[62:63]
	v_lshl_add_u64 v[180:181], s[58:59], 0, v[130:131]
	s_mov_b32 m0, s71
	s_nop 0
	global_load_lds_dwordx4 v[180:181], off
	s_mov_b32 m0, s72
	s_nop 0
	global_load_lds_dwordx4 v[182:183], off
	s_setprio 0
	s_waitcnt vmcnt(8)
	s_waitcnt lgkmcnt(0)
	s_barrier
	s_waitcnt lgkmcnt(0)
	v_mfma_f32_16x16x32_bf16 v[90:93], v[138:141], v[172:175], v[90:93]
	v_mfma_f32_16x16x32_bf16 v[94:97], v[148:151], v[172:175], v[94:97]
	v_mfma_f32_16x16x32_bf16 v[86:89], v[138:141], v[206:209], v[86:89]
	v_mfma_f32_16x16x32_bf16 v[82:85], v[148:151], v[206:209], v[82:85]
	v_mfma_f32_16x16x32_bf16 v[78:81], v[138:141], v[226:229], v[78:81]
	v_mfma_f32_16x16x32_bf16 v[74:77], v[148:151], v[226:229], v[74:77]
	v_mfma_f32_16x16x32_bf16 v[70:73], v[138:141], v[234:237], v[70:73]
	v_mfma_f32_16x16x32_bf16 v[66:69], v[148:151], v[234:237], v[66:69]
	v_mfma_f32_16x16x32_bf16 v[90:93], v[144:147], v[202:205], v[90:93]
	v_mfma_f32_16x16x32_bf16 v[94:97], v[152:155], v[202:205], v[94:97]
	v_mfma_f32_16x16x32_bf16 v[86:89], v[144:147], v[222:225], v[86:89]
	v_mfma_f32_16x16x32_bf16 v[82:85], v[152:155], v[222:225], v[82:85]
	v_mfma_f32_16x16x32_bf16 v[78:81], v[144:147], v[230:233], v[78:81]
	v_mfma_f32_16x16x32_bf16 v[74:77], v[152:155], v[230:233], v[74:77]
	v_mfma_f32_16x16x32_bf16 v[70:73], v[144:147], v[238:241], v[70:73]
	v_mfma_f32_16x16x32_bf16 v[66:69], v[152:155], v[238:241], v[66:69]
	v_mfma_f32_16x16x32_bf16 v[30:33], v[156:159], v[172:175], v[30:33]
	v_mfma_f32_16x16x32_bf16 v[26:29], v[164:167], v[172:175], v[26:29]
	v_mfma_f32_16x16x32_bf16 v[22:25], v[156:159], v[206:209], v[22:25]
	v_mfma_f32_16x16x32_bf16 v[18:21], v[164:167], v[206:209], v[18:21]
	v_mfma_f32_16x16x32_bf16 v[14:17], v[156:159], v[226:229], v[14:17]
	v_mfma_f32_16x16x32_bf16 v[10:13], v[164:167], v[226:229], v[10:13]
	v_mfma_f32_16x16x32_bf16 v[6:9], v[156:159], v[234:237], v[6:9]
	v_mfma_f32_16x16x32_bf16 v[2:5], v[164:167], v[234:237], v[2:5]
	v_mfma_f32_16x16x32_bf16 v[30:33], v[160:163], v[202:205], v[30:33]
	v_mfma_f32_16x16x32_bf16 v[26:29], v[168:171], v[202:205], v[26:29]
	v_mfma_f32_16x16x32_bf16 v[22:25], v[160:163], v[222:225], v[22:25]
	v_mfma_f32_16x16x32_bf16 v[18:21], v[168:171], v[222:225], v[18:21]
	v_mfma_f32_16x16x32_bf16 v[14:17], v[160:163], v[230:233], v[14:17]
	v_mfma_f32_16x16x32_bf16 v[10:13], v[168:171], v[230:233], v[10:13]
	v_mfma_f32_16x16x32_bf16 v[6:9], v[160:163], v[238:241], v[6:9]
	v_mfma_f32_16x16x32_bf16 v[2:5], v[168:171], v[238:241], v[2:5]
	s_barrier
	s_setprio 1
	v_add_u32_e32 v0, vcc_hi, v142
	ds_read_b128 v[138:141], v0
	ds_read_b128 v[144:147], v0 offset:1024
	ds_read_b128 v[148:151], v0 offset:2048
	ds_read_b128 v[152:155], v0 offset:3072
	v_add_u32_e32 v0, vcc_lo, v142
	ds_read_b128 v[156:159], v0
	ds_read_b128 v[160:163], v0 offset:1024
	ds_read_b128 v[164:167], v0 offset:2048
	ds_read_b128 v[168:171], v0 offset:3072
	s_mov_b32 m0, s73
	ds_read_b128 v[172:175], v143 offset:32768
	ds_read_b128 v[202:205], v143 offset:33792
	ds_read_b128 v[206:209], v143 offset:34816
	ds_read_b128 v[222:225], v143 offset:35840
	ds_read_b128 v[226:229], v143 offset:36864
	ds_read_b128 v[230:233], v143 offset:37888
	ds_read_b128 v[234:237], v143 offset:38912
	ds_read_b128 v[238:241], v143 offset:39936
	global_load_lds_dwordx4 v130, s[56:57]
	v_lshl_add_u64 v[184:185], s[56:57], 0, v[132:133]
	s_mov_b32 m0, s81
	s_nop 0
	global_load_lds_dwordx4 v[184:185], off
	s_setprio 0
	s_waitcnt vmcnt(8)
	s_waitcnt lgkmcnt(0)
	s_barrier
	s_waitcnt lgkmcnt(0)
	v_mfma_f32_16x16x32_bf16 v[126:129], v[138:141], v[172:175], v[126:129]
	v_mfma_f32_16x16x32_bf16 v[122:125], v[148:151], v[172:175], v[122:125]
	v_mfma_f32_16x16x32_bf16 v[118:121], v[138:141], v[206:209], v[118:121]
	v_mfma_f32_16x16x32_bf16 v[114:117], v[148:151], v[206:209], v[114:117]
	v_mfma_f32_16x16x32_bf16 v[110:113], v[138:141], v[226:229], v[110:113]
	v_mfma_f32_16x16x32_bf16 v[106:109], v[148:151], v[226:229], v[106:109]
	v_mfma_f32_16x16x32_bf16 v[102:105], v[138:141], v[234:237], v[102:105]
	v_mfma_f32_16x16x32_bf16 v[98:101], v[148:151], v[234:237], v[98:101]
	v_mfma_f32_16x16x32_bf16 v[126:129], v[144:147], v[202:205], v[126:129]
	v_mfma_f32_16x16x32_bf16 v[122:125], v[152:155], v[202:205], v[122:125]
	v_mfma_f32_16x16x32_bf16 v[118:121], v[144:147], v[222:225], v[118:121]
	v_mfma_f32_16x16x32_bf16 v[114:117], v[152:155], v[222:225], v[114:117]
	v_mfma_f32_16x16x32_bf16 v[110:113], v[144:147], v[230:233], v[110:113]
	v_mfma_f32_16x16x32_bf16 v[106:109], v[152:155], v[230:233], v[106:109]
	v_mfma_f32_16x16x32_bf16 v[102:105], v[144:147], v[238:241], v[102:105]
	v_mfma_f32_16x16x32_bf16 v[98:101], v[152:155], v[238:241], v[98:101]
	v_mfma_f32_16x16x32_bf16 v[62:65], v[156:159], v[172:175], v[62:65]
	v_mfma_f32_16x16x32_bf16 v[58:61], v[164:167], v[172:175], v[58:61]
	v_mfma_f32_16x16x32_bf16 v[54:57], v[156:159], v[206:209], v[54:57]
	v_mfma_f32_16x16x32_bf16 v[50:53], v[164:167], v[206:209], v[50:53]
	v_mfma_f32_16x16x32_bf16 v[46:49], v[156:159], v[226:229], v[46:49]
	v_mfma_f32_16x16x32_bf16 v[42:45], v[164:167], v[226:229], v[42:45]
	v_mfma_f32_16x16x32_bf16 v[38:41], v[156:159], v[234:237], v[38:41]
	v_mfma_f32_16x16x32_bf16 v[34:37], v[164:167], v[234:237], v[34:37]
	v_mfma_f32_16x16x32_bf16 v[62:65], v[160:163], v[202:205], v[62:65]
	v_mfma_f32_16x16x32_bf16 v[58:61], v[168:171], v[202:205], v[58:61]
	v_mfma_f32_16x16x32_bf16 v[54:57], v[160:163], v[222:225], v[54:57]
	v_mfma_f32_16x16x32_bf16 v[50:53], v[168:171], v[222:225], v[50:53]
	v_mfma_f32_16x16x32_bf16 v[46:49], v[160:163], v[230:233], v[46:49]
	v_mfma_f32_16x16x32_bf16 v[42:45], v[168:171], v[230:233], v[42:45]
	v_mfma_f32_16x16x32_bf16 v[38:41], v[160:163], v[238:241], v[38:41]
	v_mfma_f32_16x16x32_bf16 v[34:37], v[168:171], v[238:241], v[34:37]
	s_barrier
	s_setprio 1
	s_mov_b32 m0, s97
	v_lshl_add_u64 v[176:177], v[176:177], 0, s[24:25]
	ds_read_b128 v[172:175], v143 offset:49152
	ds_read_b128 v[202:205], v143 offset:50176
	ds_read_b128 v[206:209], v143 offset:51200
	ds_read_b128 v[222:225], v143 offset:52224
	ds_read_b128 v[226:229], v143 offset:53248
	ds_read_b128 v[230:233], v143 offset:54272
	ds_read_b128 v[234:237], v143 offset:55296
	ds_read_b128 v[238:241], v143 offset:56320
	global_load_lds_dwordx4 v[176:177], off
	v_lshl_add_u64 v[176:177], v[178:179], 0, s[24:25]
	s_mov_b32 m0, s96
	s_nop 0
	global_load_lds_dwordx4 v[176:177], off
	s_mov_b32 m0, s78
	s_nop 0
	global_load_lds_dwordx4 v130, s[54:55]
	s_mov_b32 m0, s20
	s_nop 0
	global_load_lds_dwordx4 v132, s[54:55]
	v_lshl_add_u64 v[176:177], v[180:181], 0, s[24:25]
	s_mov_b32 m0, s86
	s_nop 0
	global_load_lds_dwordx4 v[176:177], off
	v_lshl_add_u64 v[176:177], v[182:183], 0, s[24:25]
	s_mov_b32 m0, s88
	s_nop 0
	global_load_lds_dwordx4 v[176:177], off
	s_setprio 0
	s_waitcnt vmcnt(8)
	s_waitcnt lgkmcnt(0)
	s_barrier
	s_waitcnt lgkmcnt(0)
	v_mfma_f32_16x16x32_bf16 v[90:93], v[138:141], v[172:175], v[90:93]
	v_mfma_f32_16x16x32_bf16 v[94:97], v[148:151], v[172:175], v[94:97]
	v_mfma_f32_16x16x32_bf16 v[86:89], v[138:141], v[206:209], v[86:89]
	v_mfma_f32_16x16x32_bf16 v[82:85], v[148:151], v[206:209], v[82:85]
	v_mfma_f32_16x16x32_bf16 v[78:81], v[138:141], v[226:229], v[78:81]
	v_mfma_f32_16x16x32_bf16 v[74:77], v[148:151], v[226:229], v[74:77]
	v_mfma_f32_16x16x32_bf16 v[70:73], v[138:141], v[234:237], v[70:73]
	v_mfma_f32_16x16x32_bf16 v[66:69], v[148:151], v[234:237], v[66:69]
	v_mfma_f32_16x16x32_bf16 v[90:93], v[144:147], v[202:205], v[90:93]
	v_mfma_f32_16x16x32_bf16 v[94:97], v[152:155], v[202:205], v[94:97]
	v_mfma_f32_16x16x32_bf16 v[86:89], v[144:147], v[222:225], v[86:89]
	v_mfma_f32_16x16x32_bf16 v[82:85], v[152:155], v[222:225], v[82:85]
	v_mfma_f32_16x16x32_bf16 v[78:81], v[144:147], v[230:233], v[78:81]
	v_mfma_f32_16x16x32_bf16 v[74:77], v[152:155], v[230:233], v[74:77]
	v_mfma_f32_16x16x32_bf16 v[70:73], v[144:147], v[238:241], v[70:73]
	v_mfma_f32_16x16x32_bf16 v[66:69], v[152:155], v[238:241], v[66:69]
	v_mfma_f32_16x16x32_bf16 v[30:33], v[156:159], v[172:175], v[30:33]
	v_mfma_f32_16x16x32_bf16 v[26:29], v[164:167], v[172:175], v[26:29]
	v_mfma_f32_16x16x32_bf16 v[22:25], v[156:159], v[206:209], v[22:25]
	v_mfma_f32_16x16x32_bf16 v[18:21], v[164:167], v[206:209], v[18:21]
	v_mfma_f32_16x16x32_bf16 v[14:17], v[156:159], v[226:229], v[14:17]
	v_mfma_f32_16x16x32_bf16 v[10:13], v[164:167], v[226:229], v[10:13]
	v_mfma_f32_16x16x32_bf16 v[6:9], v[156:159], v[234:237], v[6:9]
	v_mfma_f32_16x16x32_bf16 v[2:5], v[164:167], v[234:237], v[2:5]
	v_mfma_f32_16x16x32_bf16 v[30:33], v[160:163], v[202:205], v[30:33]
	v_mfma_f32_16x16x32_bf16 v[26:29], v[168:171], v[202:205], v[26:29]
	v_mfma_f32_16x16x32_bf16 v[22:25], v[160:163], v[222:225], v[22:25]
	v_mfma_f32_16x16x32_bf16 v[18:21], v[168:171], v[222:225], v[18:21]
	v_mfma_f32_16x16x32_bf16 v[14:17], v[160:163], v[230:233], v[14:17]
	v_mfma_f32_16x16x32_bf16 v[10:13], v[168:171], v[230:233], v[10:13]
	v_mfma_f32_16x16x32_bf16 v[6:9], v[160:163], v[238:241], v[6:9]
	v_mfma_f32_16x16x32_bf16 v[2:5], v[168:171], v[238:241], v[2:5]
	s_barrier
	s_setprio 1
	s_movk_i32 s56, 0x100
	s_andn2_b64 vcc, exec, s[4:5]
	s_mov_b64 s[54:55], -1
	s_mov_b64 s[4:5], 0
	s_cbranch_vccz .LBB0_436
	s_and_b64 vcc, exec, s[16:17]
	s_cbranch_vccz .LBB0_439
	s_barrier

.LBB0_495:
	s_ashr_i32 s19, s18, 31
	s_lshl_b64 s[20:21], s[18:19], 16
	s_add_u32 s46, s55, s20
	s_addc_u32 s47, s56, s21
	s_and_b64 s[4:5], s[4:5], exec
	s_cselect_b32 s5, s47, s53
	s_cselect_b32 s4, s46, s52
	s_add_i32 s19, 0, 0x10000
	s_add_i32 s37, 0, 0x14000
	v_add_u32_e32 v14, s19, v141
	v_add_u32_e32 v30, s37, v141
	ds_read_b128 v[2:5], v14
	ds_read_b128 v[6:9], v14 offset:1024
	ds_read_b128 v[10:13], v14 offset:2048
	ds_read_b128 v[14:17], v14 offset:3072
	ds_read_b128 v[18:21], v30
	ds_read_b128 v[22:25], v30 offset:1024
	ds_read_b128 v[26:29], v30 offset:2048
	ds_read_b128 v[30:33], v30 offset:3072
	s_add_u32 s20, s50, 0x8080
	s_addc_u32 s21, s51, 0
	s_add_i32 m0, s58, 0xc000
	ds_read_b128 v[34:37], v143
	ds_read_b128 v[38:41], v143 offset:1024
	ds_read_b128 v[42:45], v143 offset:2048
	ds_read_b128 v[46:49], v143 offset:3072
	ds_read_b128 v[50:53], v143 offset:4096
	ds_read_b128 v[54:57], v143 offset:5120
	ds_read_b128 v[58:61], v143 offset:6144
	ds_read_b128 v[62:65], v143 offset:7168
	global_load_lds_dwordx4 v130, s[20:21]
	s_add_i32 m0, s58, 0xe000
	s_nop 0
	global_load_lds_dwordx4 v132, s[20:21]
	s_setprio 0
	s_waitcnt vmcnt(8)
	s_waitcnt lgkmcnt(0)
	s_barrier
	s_waitcnt lgkmcnt(0)
	v_mfma_f32_16x16x32_bf16 v[90:93], v[2:5], v[58:61], 0
	v_mfma_f32_16x16x32_bf16 v[66:69], v[2:5], v[34:37], 0
	v_mfma_f32_16x16x32_bf16 v[70:73], v[10:13], v[34:37], 0
	v_mfma_f32_16x16x32_bf16 v[74:77], v[2:5], v[42:45], 0
	v_mfma_f32_16x16x32_bf16 v[78:81], v[10:13], v[42:45], 0
	v_mfma_f32_16x16x32_bf16 v[82:85], v[2:5], v[50:53], 0
	v_mfma_f32_16x16x32_bf16 v[86:89], v[10:13], v[50:53], 0
	v_mfma_f32_16x16x32_bf16 v[98:101], v[6:9], v[62:65], v[90:93]
	v_mfma_f32_16x16x32_bf16 v[90:93], v[10:13], v[58:61], 0
	v_mfma_f32_16x16x32_bf16 v[66:69], v[6:9], v[38:41], v[66:69]
	v_mfma_f32_16x16x32_bf16 v[70:73], v[14:17], v[38:41], v[70:73]
	v_mfma_f32_16x16x32_bf16 v[74:77], v[6:9], v[46:49], v[74:77]
	v_mfma_f32_16x16x32_bf16 v[78:81], v[14:17], v[46:49], v[78:81]
	v_mfma_f32_16x16x32_bf16 v[82:85], v[6:9], v[54:57], v[82:85]
	v_mfma_f32_16x16x32_bf16 v[86:89], v[14:17], v[54:57], v[86:89]
	v_mfma_f32_16x16x32_bf16 v[102:105], v[14:17], v[62:65], v[90:93]
	v_mfma_f32_16x16x32_bf16 v[90:93], v[18:21], v[34:37], 0
	v_mfma_f32_16x16x32_bf16 v[34:37], v[26:29], v[34:37], 0
	v_mfma_f32_16x16x32_bf16 v[114:117], v[22:25], v[38:41], v[90:93]
	v_mfma_f32_16x16x32_bf16 v[34:37], v[30:33], v[38:41], v[34:37]
	v_mfma_f32_16x16x32_bf16 v[38:41], v[18:21], v[42:45], 0
	v_mfma_f32_16x16x32_bf16 v[42:45], v[26:29], v[42:45], 0
	v_mfma_f32_16x16x32_bf16 v[38:41], v[22:25], v[46:49], v[38:41]
	v_mfma_f32_16x16x32_bf16 v[42:45], v[30:33], v[46:49], v[42:45]
	v_mfma_f32_16x16x32_bf16 v[46:49], v[18:21], v[50:53], 0
	v_mfma_f32_16x16x32_bf16 v[50:53], v[26:29], v[50:53], 0
	v_mfma_f32_16x16x32_bf16 v[46:49], v[22:25], v[54:57], v[46:49]
	v_mfma_f32_16x16x32_bf16 v[50:53], v[30:33], v[54:57], v[50:53]
	v_mfma_f32_16x16x32_bf16 v[54:57], v[18:21], v[58:61], 0
	v_mfma_f32_16x16x32_bf16 v[58:61], v[26:29], v[58:61], 0
	v_mfma_f32_16x16x32_bf16 v[54:57], v[22:25], v[62:65], v[54:57]
	v_mfma_f32_16x16x32_bf16 v[62:65], v[30:33], v[62:65], v[58:61]
	s_barrier
	s_setprio 1
	s_add_i32 s19, s19, s57
	v_lshl_add_u64 v[184:185], s[4:5], 0, v[0:1]
	s_mov_b32 m0, s19
	s_nop 0
	ds_read_b128 v[58:61], v143 offset:16384
	ds_read_b128 v[90:93], v143 offset:17408
	ds_read_b128 v[94:97], v143 offset:18432
	ds_read_b128 v[106:109], v143 offset:19456
	ds_read_b128 v[110:113], v143 offset:20480
	ds_read_b128 v[118:121], v143 offset:21504
	ds_read_b128 v[122:125], v143 offset:22528
	ds_read_b128 v[126:129], v143 offset:23552
	global_load_lds_dwordx4 v[184:185], off
	s_add_i32 m0, s19, 0x2000
	s_add_u32 s20, s4, 0x8000
	v_lshl_add_u64 v[190:191], s[4:5], 0, v[134:135]
	s_addc_u32 s21, s5, 0
	s_add_i32 s19, s37, s57
	global_load_lds_dwordx4 v[190:191], off
	s_mov_b32 m0, s19
	v_lshl_add_u64 v[192:193], s[44:45], 0, v[130:131]
	global_load_lds_dwordx4 v0, s[20:21]
	s_add_i32 m0, s19, 0x2000
	v_lshl_add_u64 v[194:195], s[44:45], 0, v[132:133]
	global_load_lds_dwordx4 v134, s[20:21]
	s_mov_b32 m0, s58
	s_nop 0
	global_load_lds_dwordx4 v[192:193], off
	s_mov_b32 m0, s59
	s_nop 0
	global_load_lds_dwordx4 v[194:195], off
	s_setprio 0
	s_waitcnt vmcnt(8)
	s_waitcnt lgkmcnt(0)
	s_barrier
	s_waitcnt lgkmcnt(0)
	v_mfma_f32_16x16x32_bf16 v[136:139], v[2:5], v[58:61], 0
	v_mfma_f32_16x16x32_bf16 v[148:151], v[2:5], v[94:97], 0
	v_mfma_f32_16x16x32_bf16 v[156:159], v[2:5], v[110:113], 0
	v_mfma_f32_16x16x32_bf16 v[2:5], v[2:5], v[122:125], 0
	v_mfma_f32_16x16x32_bf16 v[136:139], v[6:9], v[90:93], v[136:139]
	v_mfma_f32_16x16x32_bf16 v[148:151], v[6:9], v[106:109], v[148:151]
	v_mfma_f32_16x16x32_bf16 v[156:159], v[6:9], v[118:121], v[156:159]
	v_mfma_f32_16x16x32_bf16 v[2:5], v[6:9], v[126:129], v[2:5]
	v_mfma_f32_16x16x32_bf16 v[6:9], v[10:13], v[122:125], 0
	v_mfma_f32_16x16x32_bf16 v[144:147], v[10:13], v[58:61], 0
	v_mfma_f32_16x16x32_bf16 v[152:155], v[10:13], v[94:97], 0
	v_mfma_f32_16x16x32_bf16 v[160:163], v[10:13], v[110:113], 0
	v_mfma_f32_16x16x32_bf16 v[6:9], v[14:17], v[126:129], v[6:9]
	v_mfma_f32_16x16x32_bf16 v[144:147], v[14:17], v[90:93], v[144:147]
	v_mfma_f32_16x16x32_bf16 v[152:155], v[14:17], v[106:109], v[152:155]
	v_mfma_f32_16x16x32_bf16 v[160:163], v[14:17], v[118:121], v[160:163]
	v_mfma_f32_16x16x32_bf16 v[10:13], v[18:21], v[58:61], 0
	v_mfma_f32_16x16x32_bf16 v[164:167], v[22:25], v[90:93], v[10:13]
	v_mfma_f32_16x16x32_bf16 v[10:13], v[26:29], v[58:61], 0
	v_mfma_f32_16x16x32_bf16 v[168:171], v[30:33], v[90:93], v[10:13]
	v_mfma_f32_16x16x32_bf16 v[10:13], v[18:21], v[94:97], 0
	v_mfma_f32_16x16x32_bf16 v[172:175], v[22:25], v[106:109], v[10:13]
	v_mfma_f32_16x16x32_bf16 v[10:13], v[26:29], v[94:97], 0
	v_mfma_f32_16x16x32_bf16 v[202:205], v[30:33], v[106:109], v[10:13]
	v_mfma_f32_16x16x32_bf16 v[10:13], v[18:21], v[110:113], 0
	v_mfma_f32_16x16x32_bf16 v[206:209], v[22:25], v[118:121], v[10:13]
	v_mfma_f32_16x16x32_bf16 v[10:13], v[26:29], v[110:113], 0
	v_mfma_f32_16x16x32_bf16 v[222:225], v[30:33], v[118:121], v[10:13]
	v_mfma_f32_16x16x32_bf16 v[10:13], v[18:21], v[122:125], 0
	v_mfma_f32_16x16x32_bf16 v[226:229], v[22:25], v[126:129], v[10:13]
	v_mfma_f32_16x16x32_bf16 v[10:13], v[26:29], v[122:125], 0
	v_mfma_f32_16x16x32_bf16 v[230:233], v[30:33], v[126:129], v[10:13]
	s_barrier
	s_setprio 1
	s_add_i32 s19, 0, 0x18000
	s_add_i32 s37, 0, 0x1c000
	v_add_u32_e32 v22, s19, v141
	v_add_u32_e32 v26, s37, v141
	s_nop 0
	ds_read_b128 v[10:13], v22
	ds_read_b128 v[14:17], v22 offset:1024
	ds_read_b128 v[18:21], v22 offset:2048
	ds_read_b128 v[22:25], v22 offset:3072
	ds_read_b128 v[234:237], v26
	ds_read_b128 v[238:241], v26 offset:1024
	ds_read_b128 v[242:245], v26 offset:2048
	ds_read_b128 v[246:249], v26 offset:3072
	s_add_u32 s20, s44, 0x8000
	s_addc_u32 s21, s45, 0
	s_mov_b32 m0, s60
	ds_read_b128 v[26:29], v143 offset:32768
	ds_read_b128 v[30:33], v143 offset:33792
	ds_read_b128 v[58:61], v143 offset:34816
	ds_read_b128 v[250:253], v143 offset:35840
	ds_read_b128 v[176:179], v143 offset:36864
	ds_read_b128 v[186:189], v143 offset:37888
	ds_read_b128 v[198:201], v143 offset:38912
	ds_read_b128 v[218:221], v143 offset:39936
	global_load_lds_dwordx4 v130, s[20:21]
	s_mov_b32 m0, s61
	s_nop 0
	global_load_lds_dwordx4 v132, s[20:21]
	s_setprio 0
	s_waitcnt vmcnt(8)
	s_waitcnt lgkmcnt(0)
	s_barrier
	s_waitcnt lgkmcnt(0)
	v_mfma_f32_16x16x32_bf16 v[66:69], v[10:13], v[26:29], v[66:69]
	v_mfma_f32_16x16x32_bf16 v[126:129], v[14:17], v[30:33], v[66:69]
	v_mfma_f32_16x16x32_bf16 v[66:69], v[18:21], v[26:29], v[70:73]
	v_mfma_f32_16x16x32_bf16 v[122:125], v[22:25], v[30:33], v[66:69]
	v_mfma_f32_16x16x32_bf16 v[66:69], v[10:13], v[58:61], v[74:77]
	v_mfma_f32_16x16x32_bf16 v[110:113], v[14:17], v[250:253], v[66:69]
	v_mfma_f32_16x16x32_bf16 v[66:69], v[18:21], v[58:61], v[78:81]
	v_mfma_f32_16x16x32_bf16 v[106:109], v[22:25], v[250:253], v[66:69]
	v_mfma_f32_16x16x32_bf16 v[66:69], v[10:13], v[176:179], v[82:85]
	v_mfma_f32_16x16x32_bf16 v[94:97], v[14:17], v[186:189], v[66:69]
	v_mfma_f32_16x16x32_bf16 v[66:69], v[18:21], v[176:179], v[86:89]
	v_mfma_f32_16x16x32_bf16 v[90:93], v[22:25], v[186:189], v[66:69]
	v_mfma_f32_16x16x32_bf16 v[66:69], v[10:13], v[198:201], v[98:101]
	v_mfma_f32_16x16x32_bf16 v[74:77], v[14:17], v[218:221], v[66:69]
	v_mfma_f32_16x16x32_bf16 v[66:69], v[18:21], v[198:201], v[102:105]
	v_mfma_f32_16x16x32_bf16 v[66:69], v[22:25], v[218:221], v[66:69]
	v_mfma_f32_16x16x32_bf16 v[70:73], v[234:237], v[26:29], v[114:117]
	v_mfma_f32_16x16x32_bf16 v[26:29], v[242:245], v[26:29], v[34:37]
	v_mfma_f32_16x16x32_bf16 v[114:117], v[246:249], v[30:33], v[26:29]
	v_mfma_f32_16x16x32_bf16 v[26:29], v[234:237], v[58:61], v[38:41]
	v_mfma_f32_16x16x32_bf16 v[102:105], v[238:241], v[250:253], v[26:29]
	v_mfma_f32_16x16x32_bf16 v[26:29], v[242:245], v[58:61], v[42:45]
	v_mfma_f32_16x16x32_bf16 v[98:101], v[246:249], v[250:253], v[26:29]
	v_mfma_f32_16x16x32_bf16 v[26:29], v[234:237], v[176:179], v[46:49]
	v_mfma_f32_16x16x32_bf16 v[86:89], v[238:241], v[186:189], v[26:29]
	v_mfma_f32_16x16x32_bf16 v[26:29], v[242:245], v[176:179], v[50:53]
	v_mfma_f32_16x16x32_bf16 v[82:85], v[246:249], v[186:189], v[26:29]
	v_mfma_f32_16x16x32_bf16 v[26:29], v[234:237], v[198:201], v[54:57]
	v_mfma_f32_16x16x32_bf16 v[58:61], v[238:241], v[218:221], v[26:29]
	v_mfma_f32_16x16x32_bf16 v[26:29], v[242:245], v[198:201], v[62:65]
	v_mfma_f32_16x16x32_bf16 v[118:121], v[238:241], v[30:33], v[70:73]
	v_mfma_f32_16x16x32_bf16 v[50:53], v[246:249], v[218:221], v[26:29]
	s_barrier
	s_setprio 1
	s_add_i32 s19, s19, s57
	s_nop 2
	v_lshl_add_u64 v[26:27], v[184:185], 0, s[24:25]
	s_mov_b32 m0, s19
	ds_read_b128 v[34:37], v143 offset:49152
	ds_read_b128 v[38:41], v143 offset:50176
	ds_read_b128 v[176:179], v143 offset:51200
	ds_read_b128 v[186:189], v143 offset:52224
	ds_read_b128 v[198:201], v143 offset:53248
	ds_read_b128 v[218:221], v143 offset:54272
	ds_read_b128 v[250:253], v143 offset:55296
	ds_read_b128 v[180:183], v143 offset:56320
	global_load_lds_dwordx4 v[26:27], off
	s_add_i32 m0, s19, 0x2000
	s_add_u32 s4, s4, 0x8080
	v_lshl_add_u64 v[26:27], v[190:191], 0, s[24:25]
	s_addc_u32 s5, s5, 0
	s_add_i32 s19, s37, s57
	global_load_lds_dwordx4 v[26:27], off
	s_mov_b32 m0, s19
	s_nop 0
	global_load_lds_dwordx4 v0, s[4:5]
	s_add_i32 m0, s19, 0x2000
	s_nop 0
	global_load_lds_dwordx4 v134, s[4:5]
	v_lshl_add_u64 v[26:27], v[192:193], 0, s[24:25]
	s_mov_b32 m0, s62
	s_nop 0
	global_load_lds_dwordx4 v[26:27], off
	v_lshl_add_u64 v[26:27], v[194:195], 0, s[24:25]
	s_mov_b32 m0, s63
	s_nop 0
	global_load_lds_dwordx4 v[26:27], off
	s_setprio 0
	s_waitcnt vmcnt(8)
	s_waitcnt lgkmcnt(0)
	s_barrier
	s_waitcnt lgkmcnt(0)
	v_mfma_f32_16x16x32_bf16 v[26:29], v[10:13], v[34:37], v[136:139]
	v_mfma_f32_16x16x32_bf16 v[78:81], v[14:17], v[38:41], v[26:29]
	v_mfma_f32_16x16x32_bf16 v[26:29], v[18:21], v[34:37], v[144:147]
	v_mfma_f32_16x16x32_bf16 v[70:73], v[22:25], v[38:41], v[26:29]
	v_mfma_f32_16x16x32_bf16 v[26:29], v[10:13], v[176:179], v[148:151]
	v_mfma_f32_16x16x32_bf16 v[46:49], v[14:17], v[186:189], v[26:29]
	v_mfma_f32_16x16x32_bf16 v[26:29], v[18:21], v[176:179], v[152:155]
	v_mfma_f32_16x16x32_bf16 v[42:45], v[22:25], v[186:189], v[26:29]
	v_mfma_f32_16x16x32_bf16 v[26:29], v[10:13], v[198:201], v[156:159]
	v_mfma_f32_16x16x32_bf16 v[2:5], v[10:13], v[250:253], v[2:5]
	v_mfma_f32_16x16x32_bf16 v[30:33], v[14:17], v[218:221], v[26:29]
	v_mfma_f32_16x16x32_bf16 v[26:29], v[18:21], v[198:201], v[160:163]
	v_mfma_f32_16x16x32_bf16 v[14:17], v[14:17], v[180:183], v[2:5]
	v_mfma_f32_16x16x32_bf16 v[2:5], v[18:21], v[250:253], v[6:9]
	v_mfma_f32_16x16x32_bf16 v[26:29], v[22:25], v[218:221], v[26:29]
	v_mfma_f32_16x16x32_bf16 v[10:13], v[22:25], v[180:183], v[2:5]
	v_mfma_f32_16x16x32_bf16 v[2:5], v[234:237], v[34:37], v[164:167]
	v_mfma_f32_16x16x32_bf16 v[62:65], v[238:241], v[38:41], v[2:5]
	v_mfma_f32_16x16x32_bf16 v[2:5], v[242:245], v[34:37], v[168:171]
	v_mfma_f32_16x16x32_bf16 v[54:57], v[246:249], v[38:41], v[2:5]
	v_mfma_f32_16x16x32_bf16 v[2:5], v[234:237], v[176:179], v[172:175]
	v_mfma_f32_16x16x32_bf16 v[38:41], v[238:241], v[186:189], v[2:5]
	v_mfma_f32_16x16x32_bf16 v[2:5], v[242:245], v[176:179], v[202:205]
	v_mfma_f32_16x16x32_bf16 v[34:37], v[246:249], v[186:189], v[2:5]
	v_mfma_f32_16x16x32_bf16 v[2:5], v[234:237], v[198:201], v[206:209]
	v_mfma_f32_16x16x32_bf16 v[22:25], v[238:241], v[218:221], v[2:5]
	v_mfma_f32_16x16x32_bf16 v[2:5], v[242:245], v[198:201], v[222:225]
	v_mfma_f32_16x16x32_bf16 v[18:21], v[246:249], v[218:221], v[2:5]
	v_mfma_f32_16x16x32_bf16 v[2:5], v[234:237], v[250:253], v[226:229]
	v_mfma_f32_16x16x32_bf16 v[6:9], v[238:241], v[180:183], v[2:5]
	v_mfma_f32_16x16x32_bf16 v[2:5], v[242:245], v[250:253], v[230:233]
	v_mfma_f32_16x16x32_bf16 v[2:5], v[246:249], v[180:183], v[2:5]
	s_barrier
	s_setprio 1
	s_andn2_b64 vcc, exec, s[12:13]
	s_cbranch_vccnz .LBB0_497
	s_barrier

.LBB0_551:
	s_ashr_i32 s19, s18, 31
	s_lshl_b64 s[20:21], s[18:19], 16
	s_add_u32 s48, s55, s20
	s_addc_u32 s49, s56, s21
	s_and_b64 s[4:5], s[4:5], exec
	s_cselect_b32 s5, s49, s53
	s_cselect_b32 s4, s48, s52
	s_add_i32 s19, 0, 0x10000
	s_add_i32 s37, 0, 0x14000
	v_add_u32_e32 v14, s19, v136
	v_add_u32_e32 v30, s37, v136
	ds_read_b128 v[2:5], v14
	ds_read_b128 v[6:9], v14 offset:1024
	ds_read_b128 v[10:13], v14 offset:2048
	ds_read_b128 v[14:17], v14 offset:3072
	ds_read_b128 v[18:21], v30
	ds_read_b128 v[22:25], v30 offset:1024
	ds_read_b128 v[26:29], v30 offset:2048
	ds_read_b128 v[30:33], v30 offset:3072
	s_add_u32 s20, s50, 0x8080
	s_addc_u32 s21, s51, 0
	s_add_i32 m0, s58, 0xc000
	ds_read_b128 v[34:37], v137
	ds_read_b128 v[38:41], v137 offset:1024
	ds_read_b128 v[42:45], v137 offset:2048
	ds_read_b128 v[46:49], v137 offset:3072
	ds_read_b128 v[50:53], v137 offset:4096
	ds_read_b128 v[54:57], v137 offset:5120
	ds_read_b128 v[58:61], v137 offset:6144
	ds_read_b128 v[62:65], v137 offset:7168
	global_load_lds_dwordx4 v130, s[20:21]
	s_add_i32 m0, s58, 0xe000
	s_nop 0
	global_load_lds_dwordx4 v132, s[20:21]
	s_setprio 0
	s_waitcnt vmcnt(8)
	s_waitcnt lgkmcnt(0)
	s_barrier
	s_waitcnt lgkmcnt(0)
	v_mfma_f32_16x16x32_bf16 v[90:93], v[2:5], v[58:61], 0
	v_mfma_f32_16x16x32_bf16 v[66:69], v[2:5], v[34:37], 0
	v_mfma_f32_16x16x32_bf16 v[70:73], v[10:13], v[34:37], 0
	v_mfma_f32_16x16x32_bf16 v[74:77], v[2:5], v[42:45], 0
	v_mfma_f32_16x16x32_bf16 v[78:81], v[10:13], v[42:45], 0
	v_mfma_f32_16x16x32_bf16 v[82:85], v[2:5], v[50:53], 0
	v_mfma_f32_16x16x32_bf16 v[86:89], v[10:13], v[50:53], 0
	v_mfma_f32_16x16x32_bf16 v[94:97], v[6:9], v[62:65], v[90:93]
	v_mfma_f32_16x16x32_bf16 v[90:93], v[10:13], v[58:61], 0
	v_mfma_f32_16x16x32_bf16 v[66:69], v[6:9], v[38:41], v[66:69]
	v_mfma_f32_16x16x32_bf16 v[70:73], v[14:17], v[38:41], v[70:73]
	v_mfma_f32_16x16x32_bf16 v[74:77], v[6:9], v[46:49], v[74:77]
	v_mfma_f32_16x16x32_bf16 v[78:81], v[14:17], v[46:49], v[78:81]
	v_mfma_f32_16x16x32_bf16 v[82:85], v[6:9], v[54:57], v[82:85]
	v_mfma_f32_16x16x32_bf16 v[86:89], v[14:17], v[54:57], v[86:89]
	v_mfma_f32_16x16x32_bf16 v[102:105], v[14:17], v[62:65], v[90:93]
	v_mfma_f32_16x16x32_bf16 v[90:93], v[18:21], v[34:37], 0
	v_mfma_f32_16x16x32_bf16 v[34:37], v[26:29], v[34:37], 0
	v_mfma_f32_16x16x32_bf16 v[110:113], v[22:25], v[38:41], v[90:93]
	v_mfma_f32_16x16x32_bf16 v[34:37], v[30:33], v[38:41], v[34:37]
	v_mfma_f32_16x16x32_bf16 v[38:41], v[18:21], v[42:45], 0
	v_mfma_f32_16x16x32_bf16 v[42:45], v[26:29], v[42:45], 0
	v_mfma_f32_16x16x32_bf16 v[38:41], v[22:25], v[46:49], v[38:41]
	v_mfma_f32_16x16x32_bf16 v[42:45], v[30:33], v[46:49], v[42:45]
	v_mfma_f32_16x16x32_bf16 v[46:49], v[18:21], v[50:53], 0
	v_mfma_f32_16x16x32_bf16 v[50:53], v[26:29], v[50:53], 0
	v_mfma_f32_16x16x32_bf16 v[46:49], v[22:25], v[54:57], v[46:49]
	v_mfma_f32_16x16x32_bf16 v[54:57], v[30:33], v[54:57], v[50:53]
	v_mfma_f32_16x16x32_bf16 v[50:53], v[18:21], v[58:61], 0
	v_mfma_f32_16x16x32_bf16 v[142:145], v[22:25], v[62:65], v[50:53]
	v_mfma_f32_16x16x32_bf16 v[50:53], v[26:29], v[58:61], 0
	v_mfma_f32_16x16x32_bf16 v[146:149], v[30:33], v[62:65], v[50:53]
	s_barrier
	s_setprio 1
	s_add_i32 s19, s19, s57
	v_lshl_add_u64 v[190:191], s[4:5], 0, v[0:1]
	s_mov_b32 m0, s19
	s_nop 1
	ds_read_b128 v[50:53], v137 offset:16384
	ds_read_b128 v[58:61], v137 offset:17408
	ds_read_b128 v[62:65], v137 offset:18432
	ds_read_b128 v[90:93], v137 offset:19456
	ds_read_b128 v[98:101], v137 offset:20480
	ds_read_b128 v[106:109], v137 offset:21504
	ds_read_b128 v[114:117], v137 offset:22528
	ds_read_b128 v[118:121], v137 offset:23552
	global_load_lds_dwordx4 v[190:191], off
	s_add_i32 m0, s19, 0x2000
	s_add_u32 s20, s4, 0x8000
	v_lshl_add_u64 v[192:193], s[4:5], 0, v[134:135]
	s_addc_u32 s21, s5, 0
	s_add_i32 s19, s37, s57
	global_load_lds_dwordx4 v[192:193], off
	s_mov_b32 m0, s19
	v_lshl_add_u64 v[210:211], s[44:45], 0, v[130:131]
	global_load_lds_dwordx4 v0, s[20:21]
	s_add_i32 m0, s19, 0x2000
	v_lshl_add_u64 v[214:215], s[44:45], 0, v[132:133]
	global_load_lds_dwordx4 v134, s[20:21]
	s_mov_b32 m0, s58
	s_nop 0
	global_load_lds_dwordx4 v[210:211], off
	s_mov_b32 m0, s59
	s_nop 0
	global_load_lds_dwordx4 v[214:215], off
	s_setprio 0
	s_waitcnt vmcnt(8)
	s_waitcnt lgkmcnt(0)
	s_barrier
	s_waitcnt lgkmcnt(0)
	v_mfma_f32_16x16x32_bf16 v[122:125], v[2:5], v[50:53], 0
	v_mfma_f32_16x16x32_bf16 v[150:153], v[6:9], v[58:61], v[122:125]
	v_mfma_f32_16x16x32_bf16 v[122:125], v[10:13], v[50:53], 0
	v_mfma_f32_16x16x32_bf16 v[154:157], v[14:17], v[58:61], v[122:125]
	v_mfma_f32_16x16x32_bf16 v[122:125], v[2:5], v[62:65], 0
	v_mfma_f32_16x16x32_bf16 v[158:161], v[6:9], v[90:93], v[122:125]
	v_mfma_f32_16x16x32_bf16 v[122:125], v[10:13], v[62:65], 0
	v_mfma_f32_16x16x32_bf16 v[162:165], v[14:17], v[90:93], v[122:125]
	v_mfma_f32_16x16x32_bf16 v[122:125], v[2:5], v[98:101], 0
	v_mfma_f32_16x16x32_bf16 v[2:5], v[2:5], v[114:117], 0
	v_mfma_f32_16x16x32_bf16 v[166:169], v[6:9], v[106:109], v[122:125]
	v_mfma_f32_16x16x32_bf16 v[2:5], v[6:9], v[118:121], v[2:5]
	v_mfma_f32_16x16x32_bf16 v[6:9], v[10:13], v[114:117], 0
	v_mfma_f32_16x16x32_bf16 v[122:125], v[10:13], v[98:101], 0
	v_mfma_f32_16x16x32_bf16 v[6:9], v[14:17], v[118:121], v[6:9]
	v_mfma_f32_16x16x32_bf16 v[170:173], v[14:17], v[106:109], v[122:125]
	v_mfma_f32_16x16x32_bf16 v[10:13], v[18:21], v[50:53], 0
	v_mfma_f32_16x16x32_bf16 v[14:17], v[22:25], v[58:61], v[10:13]
	v_mfma_f32_16x16x32_bf16 v[10:13], v[26:29], v[50:53], 0
	v_mfma_f32_16x16x32_bf16 v[174:177], v[30:33], v[58:61], v[10:13]
	v_mfma_f32_16x16x32_bf16 v[10:13], v[18:21], v[62:65], 0
	v_mfma_f32_16x16x32_bf16 v[178:181], v[22:25], v[90:93], v[10:13]
	v_mfma_f32_16x16x32_bf16 v[10:13], v[26:29], v[62:65], 0
	v_mfma_f32_16x16x32_bf16 v[186:189], v[30:33], v[90:93], v[10:13]
	v_mfma_f32_16x16x32_bf16 v[10:13], v[18:21], v[98:101], 0
	v_mfma_f32_16x16x32_bf16 v[198:201], v[22:25], v[106:109], v[10:13]
	v_mfma_f32_16x16x32_bf16 v[10:13], v[26:29], v[98:101], 0
	v_mfma_f32_16x16x32_bf16 v[202:205], v[30:33], v[106:109], v[10:13]
	v_mfma_f32_16x16x32_bf16 v[10:13], v[18:21], v[114:117], 0
	v_mfma_f32_16x16x32_bf16 v[206:209], v[22:25], v[118:121], v[10:13]
	v_mfma_f32_16x16x32_bf16 v[10:13], v[26:29], v[114:117], 0
	v_mfma_f32_16x16x32_bf16 v[218:221], v[30:33], v[118:121], v[10:13]
	s_barrier
	s_setprio 1
	s_add_i32 s19, 0, 0x18000
	v_add_u32_e32 v18, s19, v136
	s_add_i32 s37, 0, 0x1c000
	s_nop 1
	ds_read_b128 v[10:13], v18
	ds_read_b128 v[22:25], v18 offset:1024
	ds_read_b128 v[30:33], v18 offset:2048
	ds_read_b128 v[222:225], v18 offset:3072
	v_add_u32_e32 v18, s37, v136
	ds_read_b128 v[226:229], v18
	ds_read_b128 v[230:233], v18 offset:1024
	ds_read_b128 v[234:237], v18 offset:2048
	ds_read_b128 v[238:241], v18 offset:3072
	s_add_u32 s20, s44, 0x8000
	s_addc_u32 s21, s45, 0
	s_mov_b32 m0, s60
	ds_read_b128 v[18:21], v137 offset:32768
	ds_read_b128 v[26:29], v137 offset:33792
	ds_read_b128 v[62:65], v137 offset:34816
	ds_read_b128 v[242:245], v137 offset:35840
	ds_read_b128 v[246:249], v137 offset:36864
	ds_read_b128 v[250:253], v137 offset:37888
	ds_read_b128 v[182:185], v137 offset:38912
	ds_read_b128 v[194:197], v137 offset:39936
	global_load_lds_dwordx4 v130, s[20:21]
	s_mov_b32 m0, s61
	s_nop 0
	global_load_lds_dwordx4 v132, s[20:21]
	s_setprio 0
	s_waitcnt vmcnt(8)
	s_waitcnt lgkmcnt(0)
	s_barrier
	s_waitcnt lgkmcnt(0)
	v_mfma_f32_16x16x32_bf16 v[50:53], v[10:13], v[18:21], v[66:69]
	v_mfma_f32_16x16x32_bf16 v[126:129], v[22:25], v[26:29], v[50:53]
	v_mfma_f32_16x16x32_bf16 v[50:53], v[30:33], v[18:21], v[70:73]
	v_mfma_f32_16x16x32_bf16 v[122:125], v[222:225], v[26:29], v[50:53]
	v_mfma_f32_16x16x32_bf16 v[50:53], v[10:13], v[62:65], v[74:77]
	v_mfma_f32_16x16x32_bf16 v[106:109], v[22:25], v[242:245], v[50:53]
	v_mfma_f32_16x16x32_bf16 v[50:53], v[30:33], v[62:65], v[78:81]
	v_mfma_f32_16x16x32_bf16 v[98:101], v[222:225], v[242:245], v[50:53]
	v_mfma_f32_16x16x32_bf16 v[50:53], v[10:13], v[246:249], v[82:85]
	v_mfma_f32_16x16x32_bf16 v[90:93], v[22:25], v[250:253], v[50:53]
	v_mfma_f32_16x16x32_bf16 v[50:53], v[30:33], v[246:249], v[86:89]
	v_mfma_f32_16x16x32_bf16 v[78:81], v[222:225], v[250:253], v[50:53]
	v_mfma_f32_16x16x32_bf16 v[50:53], v[10:13], v[182:185], v[94:97]
	v_mfma_f32_16x16x32_bf16 v[58:61], v[22:25], v[194:197], v[50:53]
	v_mfma_f32_16x16x32_bf16 v[50:53], v[30:33], v[182:185], v[102:105]
	v_mfma_f32_16x16x32_bf16 v[50:53], v[222:225], v[194:197], v[50:53]
	v_mfma_f32_16x16x32_bf16 v[66:69], v[226:229], v[18:21], v[110:113]
	v_mfma_f32_16x16x32_bf16 v[18:21], v[234:237], v[18:21], v[34:37]
	v_mfma_f32_16x16x32_bf16 v[114:117], v[238:241], v[26:29], v[18:21]
	v_mfma_f32_16x16x32_bf16 v[18:21], v[226:229], v[62:65], v[38:41]
	v_mfma_f32_16x16x32_bf16 v[110:113], v[230:233], v[242:245], v[18:21]
	v_mfma_f32_16x16x32_bf16 v[18:21], v[234:237], v[62:65], v[42:45]
	v_mfma_f32_16x16x32_bf16 v[102:105], v[238:241], v[242:245], v[18:21]
	v_mfma_f32_16x16x32_bf16 v[18:21], v[226:229], v[246:249], v[46:49]
	v_mfma_f32_16x16x32_bf16 v[94:97], v[230:233], v[250:253], v[18:21]
	v_mfma_f32_16x16x32_bf16 v[18:21], v[234:237], v[246:249], v[54:57]
	v_mfma_f32_16x16x32_bf16 v[82:85], v[238:241], v[250:253], v[18:21]
	v_mfma_f32_16x16x32_bf16 v[18:21], v[226:229], v[182:185], v[142:145]
	v_mfma_f32_16x16x32_bf16 v[62:65], v[230:233], v[194:197], v[18:21]
	v_mfma_f32_16x16x32_bf16 v[18:21], v[234:237], v[182:185], v[146:149]
	v_mfma_f32_16x16x32_bf16 v[118:121], v[230:233], v[26:29], v[66:69]
	v_mfma_f32_16x16x32_bf16 v[54:57], v[238:241], v[194:197], v[18:21]
	s_barrier
	s_setprio 1
	s_add_i32 s19, s19, s57
	s_nop 2
	v_lshl_add_u64 v[18:19], v[190:191], 0, s[24:25]
	s_mov_b32 m0, s19
	ds_read_b128 v[38:41], v137 offset:49152
	ds_read_b128 v[46:49], v137 offset:50176
	ds_read_b128 v[142:145], v137 offset:51200
	ds_read_b128 v[146:149], v137 offset:52224
	ds_read_b128 v[182:185], v137 offset:53248
	ds_read_b128 v[194:197], v137 offset:54272
	ds_read_b128 v[242:245], v137 offset:55296
	ds_read_b128 v[246:249], v137 offset:56320
	global_load_lds_dwordx4 v[18:19], off
	s_add_i32 m0, s19, 0x2000
	s_add_u32 s4, s4, 0x8080
	v_lshl_add_u64 v[18:19], v[192:193], 0, s[24:25]
	s_addc_u32 s5, s5, 0
	s_add_i32 s19, s37, s57
	global_load_lds_dwordx4 v[18:19], off
	s_mov_b32 m0, s19
	s_nop 0
	global_load_lds_dwordx4 v0, s[4:5]
	s_add_i32 m0, s19, 0x2000
	s_nop 0
	global_load_lds_dwordx4 v134, s[4:5]
	v_lshl_add_u64 v[18:19], v[210:211], 0, s[24:25]
	s_mov_b32 m0, s66
	s_nop 0
	global_load_lds_dwordx4 v[18:19], off
	v_lshl_add_u64 v[18:19], v[214:215], 0, s[24:25]
	s_mov_b32 m0, s67
	s_nop 0
	global_load_lds_dwordx4 v[18:19], off
	s_setprio 0
	s_waitcnt vmcnt(8)
	s_waitcnt lgkmcnt(0)
	s_barrier
	s_waitcnt lgkmcnt(0)
	v_mfma_f32_16x16x32_bf16 v[18:21], v[10:13], v[38:41], v[150:153]
	v_mfma_f32_16x16x32_bf16 v[86:89], v[22:25], v[46:49], v[18:21]
	v_mfma_f32_16x16x32_bf16 v[18:21], v[30:33], v[38:41], v[154:157]
	v_mfma_f32_16x16x32_bf16 v[74:77], v[222:225], v[46:49], v[18:21]
	v_mfma_f32_16x16x32_bf16 v[18:21], v[10:13], v[142:145], v[158:161]
	v_mfma_f32_16x16x32_bf16 v[42:45], v[22:25], v[146:149], v[18:21]
	v_mfma_f32_16x16x32_bf16 v[18:21], v[30:33], v[142:145], v[162:165]
	v_mfma_f32_16x16x32_bf16 v[34:37], v[222:225], v[146:149], v[18:21]
	v_mfma_f32_16x16x32_bf16 v[18:21], v[10:13], v[182:185], v[166:169]
	v_mfma_f32_16x16x32_bf16 v[2:5], v[10:13], v[242:245], v[2:5]
	v_mfma_f32_16x16x32_bf16 v[26:29], v[22:25], v[194:197], v[18:21]
	v_mfma_f32_16x16x32_bf16 v[18:21], v[30:33], v[182:185], v[170:173]
	v_mfma_f32_16x16x32_bf16 v[10:13], v[22:25], v[246:249], v[2:5]
	v_mfma_f32_16x16x32_bf16 v[2:5], v[30:33], v[242:245], v[6:9]
	v_mfma_f32_16x16x32_bf16 v[18:21], v[222:225], v[194:197], v[18:21]
	v_mfma_f32_16x16x32_bf16 v[2:5], v[222:225], v[246:249], v[2:5]
	v_mfma_f32_16x16x32_bf16 v[6:9], v[226:229], v[38:41], v[14:17]
	v_mfma_f32_16x16x32_bf16 v[70:73], v[230:233], v[46:49], v[6:9]
	v_mfma_f32_16x16x32_bf16 v[6:9], v[234:237], v[38:41], v[174:177]
	v_mfma_f32_16x16x32_bf16 v[66:69], v[238:241], v[46:49], v[6:9]
	v_mfma_f32_16x16x32_bf16 v[6:9], v[226:229], v[142:145], v[178:181]
	v_mfma_f32_16x16x32_bf16 v[46:49], v[230:233], v[146:149], v[6:9]
	v_mfma_f32_16x16x32_bf16 v[6:9], v[234:237], v[142:145], v[186:189]
	v_mfma_f32_16x16x32_bf16 v[38:41], v[238:241], v[146:149], v[6:9]
	v_mfma_f32_16x16x32_bf16 v[6:9], v[226:229], v[182:185], v[198:201]
	v_mfma_f32_16x16x32_bf16 v[30:33], v[230:233], v[194:197], v[6:9]
	v_mfma_f32_16x16x32_bf16 v[6:9], v[234:237], v[182:185], v[202:205]
	v_mfma_f32_16x16x32_bf16 v[22:25], v[238:241], v[194:197], v[6:9]
	v_mfma_f32_16x16x32_bf16 v[6:9], v[226:229], v[242:245], v[206:209]
	v_mfma_f32_16x16x32_bf16 v[14:17], v[230:233], v[246:249], v[6:9]
	v_mfma_f32_16x16x32_bf16 v[6:9], v[234:237], v[242:245], v[218:221]
	v_mfma_f32_16x16x32_bf16 v[6:9], v[238:241], v[246:249], v[6:9]
	s_barrier
	s_setprio 1
	s_andn2_b64 vcc, exec, s[8:9]
	s_cbranch_vccnz .LBB0_553
	s_barrier

.LBB0_571:
	s_ashr_i32 s55, s54, 31
	s_lshl_b64 s[20:21], s[54:55], 16
	s_add_u32 s58, s69, s20
	s_addc_u32 s59, s70, s21
	s_and_b64 s[6:7], s[6:7], exec
	s_cselect_b32 s7, s59, s61
	s_cselect_b32 s6, s58, s60
	s_add_i32 s9, 0, 0x10000
	s_add_i32 s37, 0, 0x14000
	v_add_u32_e32 v14, s9, v160
	v_add_u32_e32 v30, s37, v160
	ds_read_b128 v[2:5], v14
	ds_read_b128 v[6:9], v14 offset:1024
	ds_read_b128 v[10:13], v14 offset:2048
	ds_read_b128 v[14:17], v14 offset:3072
	ds_read_b128 v[18:21], v30
	ds_read_b128 v[22:25], v30 offset:1024
	ds_read_b128 v[26:29], v30 offset:2048
	ds_read_b128 v[30:33], v30 offset:3072
	s_add_u32 s20, s62, 0x10080
	s_addc_u32 s21, s63, 0
	s_add_i32 m0, s71, 0xc000
	ds_read_b128 v[34:37], v161
	ds_read_b128 v[38:41], v161 offset:1024
	ds_read_b128 v[42:45], v161 offset:2048
	ds_read_b128 v[46:49], v161 offset:3072
	ds_read_b128 v[50:53], v161 offset:4096
	ds_read_b128 v[54:57], v161 offset:5120
	ds_read_b128 v[58:61], v161 offset:6144
	ds_read_b128 v[62:65], v161 offset:7168
	global_load_lds_dwordx4 v138, s[20:21]
	s_add_i32 m0, s71, 0xe000
	s_nop 0
	global_load_lds_dwordx4 v140, s[20:21]
	s_setprio 0
	s_waitcnt vmcnt(8)
	s_waitcnt lgkmcnt(0)
	s_barrier
	s_waitcnt lgkmcnt(0)
	v_mfma_f32_16x16x32_bf16 v[66:69], v[2:5], v[34:37], 0
	v_mfma_f32_16x16x32_bf16 v[70:73], v[10:13], v[34:37], 0
	v_mfma_f32_16x16x32_bf16 v[74:77], v[2:5], v[42:45], 0
	v_mfma_f32_16x16x32_bf16 v[78:81], v[10:13], v[42:45], 0
	v_mfma_f32_16x16x32_bf16 v[82:85], v[2:5], v[50:53], 0
	v_mfma_f32_16x16x32_bf16 v[86:89], v[10:13], v[50:53], 0
	v_mfma_f32_16x16x32_bf16 v[90:93], v[2:5], v[58:61], 0
	v_mfma_f32_16x16x32_bf16 v[94:97], v[10:13], v[58:61], 0
	v_mfma_f32_16x16x32_bf16 v[66:69], v[6:9], v[38:41], v[66:69]
	v_mfma_f32_16x16x32_bf16 v[70:73], v[14:17], v[38:41], v[70:73]
	v_mfma_f32_16x16x32_bf16 v[74:77], v[6:9], v[46:49], v[74:77]
	v_mfma_f32_16x16x32_bf16 v[78:81], v[14:17], v[46:49], v[78:81]
	v_mfma_f32_16x16x32_bf16 v[82:85], v[6:9], v[54:57], v[82:85]
	v_mfma_f32_16x16x32_bf16 v[86:89], v[14:17], v[54:57], v[86:89]
	v_mfma_f32_16x16x32_bf16 v[90:93], v[6:9], v[62:65], v[90:93]
	v_mfma_f32_16x16x32_bf16 v[94:97], v[14:17], v[62:65], v[94:97]
	v_mfma_f32_16x16x32_bf16 v[98:101], v[18:21], v[34:37], 0
	v_mfma_f32_16x16x32_bf16 v[34:37], v[26:29], v[34:37], 0
	v_mfma_f32_16x16x32_bf16 v[98:101], v[22:25], v[38:41], v[98:101]
	v_mfma_f32_16x16x32_bf16 v[34:37], v[30:33], v[38:41], v[34:37]
	v_mfma_f32_16x16x32_bf16 v[38:41], v[18:21], v[42:45], 0
	v_mfma_f32_16x16x32_bf16 v[42:45], v[26:29], v[42:45], 0
	v_mfma_f32_16x16x32_bf16 v[38:41], v[22:25], v[46:49], v[38:41]
	v_mfma_f32_16x16x32_bf16 v[42:45], v[30:33], v[46:49], v[42:45]
	v_mfma_f32_16x16x32_bf16 v[46:49], v[18:21], v[50:53], 0
	v_mfma_f32_16x16x32_bf16 v[50:53], v[26:29], v[50:53], 0
	v_mfma_f32_16x16x32_bf16 v[46:49], v[22:25], v[54:57], v[46:49]
	v_mfma_f32_16x16x32_bf16 v[50:53], v[30:33], v[54:57], v[50:53]
	v_mfma_f32_16x16x32_bf16 v[54:57], v[18:21], v[58:61], 0
	v_mfma_f32_16x16x32_bf16 v[58:61], v[26:29], v[58:61], 0
	v_mfma_f32_16x16x32_bf16 v[54:57], v[22:25], v[62:65], v[54:57]
	v_mfma_f32_16x16x32_bf16 v[102:105], v[30:33], v[62:65], v[58:61]
	s_barrier
	s_setprio 1
	s_add_i32 s9, s9, s66
	v_lshl_add_u64 v[156:157], s[6:7], 0, v[0:1]
	s_mov_b32 m0, s9
	s_nop 0
	ds_read_b128 v[58:61], v161 offset:16384
	ds_read_b128 v[62:65], v161 offset:17408
	ds_read_b128 v[106:109], v161 offset:18432
	ds_read_b128 v[110:113], v161 offset:19456
	ds_read_b128 v[114:117], v161 offset:20480
	ds_read_b128 v[118:121], v161 offset:21504
	ds_read_b128 v[122:125], v161 offset:22528
	ds_read_b128 v[126:129], v161 offset:23552
	global_load_lds_dwordx4 v[156:157], off
	s_add_i32 m0, s9, 0x2000
	s_add_u32 s20, s6, 0x8000
	v_lshl_add_u64 v[210:211], s[6:7], 0, v[142:143]
	s_addc_u32 s21, s7, 0
	s_add_i32 s9, s37, s66
	global_load_lds_dwordx4 v[210:211], off
	s_mov_b32 m0, s9
	v_lshl_add_u64 v[214:215], s[56:57], 0, v[138:139]
	global_load_lds_dwordx4 v0, s[20:21]
	s_add_i32 m0, s9, 0x2000
	v_lshl_add_u64 v[216:217], s[56:57], 0, v[140:141]
	global_load_lds_dwordx4 v142, s[20:21]
	s_mov_b32 m0, s71
	s_nop 0
	global_load_lds_dwordx4 v[214:215], off
	s_mov_b32 m0, s72
	s_nop 0
	global_load_lds_dwordx4 v[216:217], off
	s_setprio 0
	s_waitcnt vmcnt(8)
	s_waitcnt lgkmcnt(0)
	s_barrier
	s_waitcnt lgkmcnt(0)
	v_mfma_f32_16x16x32_bf16 v[130:133], v[2:5], v[58:61], 0
	v_mfma_f32_16x16x32_bf16 v[144:147], v[6:9], v[62:65], v[130:133]
	v_mfma_f32_16x16x32_bf16 v[130:133], v[10:13], v[58:61], 0
	v_mfma_f32_16x16x32_bf16 v[148:151], v[14:17], v[62:65], v[130:133]
	v_mfma_f32_16x16x32_bf16 v[130:133], v[2:5], v[106:109], 0
	v_mfma_f32_16x16x32_bf16 v[152:155], v[6:9], v[110:113], v[130:133]
	v_mfma_f32_16x16x32_bf16 v[130:133], v[10:13], v[106:109], 0
	v_mfma_f32_16x16x32_bf16 v[162:165], v[14:17], v[110:113], v[130:133]
	v_mfma_f32_16x16x32_bf16 v[130:133], v[2:5], v[114:117], 0
	v_mfma_f32_16x16x32_bf16 v[2:5], v[2:5], v[122:125], 0
	v_mfma_f32_16x16x32_bf16 v[166:169], v[6:9], v[118:121], v[130:133]
	v_mfma_f32_16x16x32_bf16 v[130:133], v[10:13], v[114:117], 0
	v_mfma_f32_16x16x32_bf16 v[174:177], v[6:9], v[126:129], v[2:5]
	v_mfma_f32_16x16x32_bf16 v[2:5], v[10:13], v[122:125], 0
	v_mfma_f32_16x16x32_bf16 v[170:173], v[14:17], v[118:121], v[130:133]
	v_mfma_f32_16x16x32_bf16 v[10:13], v[14:17], v[126:129], v[2:5]
	v_mfma_f32_16x16x32_bf16 v[2:5], v[18:21], v[58:61], 0
	v_mfma_f32_16x16x32_bf16 v[14:17], v[22:25], v[62:65], v[2:5]
	v_mfma_f32_16x16x32_bf16 v[2:5], v[26:29], v[58:61], 0
	v_mfma_f32_16x16x32_bf16 v[178:181], v[30:33], v[62:65], v[2:5]
	v_mfma_f32_16x16x32_bf16 v[2:5], v[18:21], v[106:109], 0
	v_mfma_f32_16x16x32_bf16 v[182:185], v[22:25], v[110:113], v[2:5]
	v_mfma_f32_16x16x32_bf16 v[2:5], v[26:29], v[106:109], 0
	v_mfma_f32_16x16x32_bf16 v[186:189], v[30:33], v[110:113], v[2:5]
	v_mfma_f32_16x16x32_bf16 v[2:5], v[18:21], v[114:117], 0
	v_mfma_f32_16x16x32_bf16 v[194:197], v[22:25], v[118:121], v[2:5]
	v_mfma_f32_16x16x32_bf16 v[2:5], v[26:29], v[114:117], 0
	v_mfma_f32_16x16x32_bf16 v[198:201], v[30:33], v[118:121], v[2:5]
	v_mfma_f32_16x16x32_bf16 v[2:5], v[18:21], v[122:125], 0
	v_mfma_f32_16x16x32_bf16 v[18:21], v[22:25], v[126:129], v[2:5]
	v_mfma_f32_16x16x32_bf16 v[2:5], v[26:29], v[122:125], 0
	v_mfma_f32_16x16x32_bf16 v[202:205], v[30:33], v[126:129], v[2:5]
	s_barrier
	s_setprio 1
	s_add_i32 s9, 0, 0x18000
	s_nop 3
	v_add_u32_e32 v2, s9, v160
	s_add_i32 s37, 0, 0x1c000
	ds_read_b128 v[22:25], v2
	ds_read_b128 v[26:29], v2 offset:1024
	ds_read_b128 v[30:33], v2 offset:2048
	ds_read_b128 v[206:209], v2 offset:3072
	v_add_u32_e32 v2, s37, v160
	ds_read_b128 v[218:221], v2
	ds_read_b128 v[222:225], v2 offset:1024
	ds_read_b128 v[226:229], v2 offset:2048
	ds_read_b128 v[230:233], v2 offset:3072
	s_add_u32 s20, s56, 0x10000
	s_addc_u32 s21, s57, 0
	s_mov_b32 m0, s73
	ds_read_b128 v[58:61], v161 offset:32768
	ds_read_b128 v[62:65], v161 offset:33792
	ds_read_b128 v[106:109], v161 offset:34816
	ds_read_b128 v[110:113], v161 offset:35840
	ds_read_b128 v[234:237], v161 offset:36864
	ds_read_b128 v[238:241], v161 offset:37888
	ds_read_b128 v[242:245], v161 offset:38912
	ds_read_b128 v[246:249], v161 offset:39936
	global_load_lds_dwordx4 v138, s[20:21]
	s_mov_b32 m0, s92
	s_nop 0
	global_load_lds_dwordx4 v140, s[20:21]
	s_setprio 0
	s_waitcnt vmcnt(8)
	s_waitcnt lgkmcnt(0)
	s_barrier
	s_waitcnt lgkmcnt(0)
	v_mfma_f32_16x16x32_bf16 v[2:5], v[22:25], v[58:61], v[66:69]
	v_mfma_f32_16x16x32_bf16 v[66:69], v[22:25], v[106:109], v[74:77]
	v_mfma_f32_16x16x32_bf16 v[134:137], v[26:29], v[110:113], v[66:69]
	v_mfma_f32_16x16x32_bf16 v[66:69], v[30:33], v[106:109], v[78:81]
	v_mfma_f32_16x16x32_bf16 v[130:133], v[206:209], v[110:113], v[66:69]
	v_mfma_f32_16x16x32_bf16 v[66:69], v[22:25], v[234:237], v[82:85]
	v_mfma_f32_16x16x32_bf16 v[126:129], v[26:29], v[238:241], v[66:69]
	v_mfma_f32_16x16x32_bf16 v[66:69], v[30:33], v[234:237], v[86:89]
	v_mfma_f32_16x16x32_bf16 v[122:125], v[206:209], v[238:241], v[66:69]
	v_mfma_f32_16x16x32_bf16 v[66:69], v[22:25], v[242:245], v[90:93]
	v_mfma_f32_16x16x32_bf16 v[6:9], v[26:29], v[62:65], v[2:5]
	v_mfma_f32_16x16x32_bf16 v[2:5], v[30:33], v[58:61], v[70:73]
	v_mfma_f32_16x16x32_bf16 v[118:121], v[26:29], v[246:249], v[66:69]
	v_mfma_f32_16x16x32_bf16 v[66:69], v[30:33], v[242:245], v[94:97]
	v_mfma_f32_16x16x32_bf16 v[2:5], v[206:209], v[62:65], v[2:5]
	v_mfma_f32_16x16x32_bf16 v[114:117], v[206:209], v[246:249], v[66:69]
	v_mfma_f32_16x16x32_bf16 v[34:37], v[226:229], v[58:61], v[34:37]
	v_mfma_f32_16x16x32_bf16 v[74:77], v[230:233], v[62:65], v[34:37]
	v_mfma_f32_16x16x32_bf16 v[34:37], v[218:221], v[106:109], v[38:41]
	v_mfma_f32_16x16x32_bf16 v[66:69], v[218:221], v[58:61], v[98:101]
	v_mfma_f32_16x16x32_bf16 v[70:73], v[222:225], v[110:113], v[34:37]
	v_mfma_f32_16x16x32_bf16 v[34:37], v[226:229], v[106:109], v[42:45]
	v_mfma_f32_16x16x32_bf16 v[78:81], v[222:225], v[62:65], v[66:69]
	v_mfma_f32_16x16x32_bf16 v[66:69], v[230:233], v[110:113], v[34:37]
	v_mfma_f32_16x16x32_bf16 v[34:37], v[218:221], v[234:237], v[46:49]
	v_mfma_f32_16x16x32_bf16 v[62:65], v[222:225], v[238:241], v[34:37]
	v_mfma_f32_16x16x32_bf16 v[34:37], v[226:229], v[234:237], v[50:53]
	v_mfma_f32_16x16x32_bf16 v[58:61], v[230:233], v[238:241], v[34:37]
	v_mfma_f32_16x16x32_bf16 v[34:37], v[218:221], v[242:245], v[54:57]
	v_mfma_f32_16x16x32_bf16 v[54:57], v[222:225], v[246:249], v[34:37]
	v_mfma_f32_16x16x32_bf16 v[34:37], v[226:229], v[242:245], v[102:105]
	v_mfma_f32_16x16x32_bf16 v[50:53], v[230:233], v[246:249], v[34:37]
	s_barrier
	s_setprio 1
	s_add_i32 s9, s9, s66
	v_lshl_add_u64 v[42:43], v[156:157], 0, s[24:25]
	s_mov_b32 m0, s9
	s_nop 1
	ds_read_b128 v[34:37], v161 offset:49152
	ds_read_b128 v[38:41], v161 offset:50176
	ds_read_b128 v[234:237], v161 offset:51200
	ds_read_b128 v[238:241], v161 offset:52224
	ds_read_b128 v[242:245], v161 offset:53248
	ds_read_b128 v[246:249], v161 offset:54272
	ds_read_b128 v[250:253], v161 offset:55296
	ds_read_b128 v[190:193], v161 offset:56320
	global_load_lds_dwordx4 v[42:43], off
	s_add_i32 m0, s9, 0x2000
	s_add_u32 s6, s6, 0x8080
	v_lshl_add_u64 v[42:43], v[210:211], 0, s[24:25]
	s_addc_u32 s7, s7, 0
	s_add_i32 s9, s37, s66
	global_load_lds_dwordx4 v[42:43], off
	s_mov_b32 m0, s9
	s_nop 0
	global_load_lds_dwordx4 v0, s[6:7]
	s_add_i32 m0, s9, 0x2000
	s_nop 0
	global_load_lds_dwordx4 v142, s[6:7]
	v_lshl_add_u64 v[42:43], v[214:215], 0, s[24:25]
	s_mov_b32 m0, s95
	s_nop 0
	global_load_lds_dwordx4 v[42:43], off
	v_lshl_add_u64 v[42:43], v[216:217], 0, s[24:25]
	s_mov_b32 m0, s96
	s_nop 0
	global_load_lds_dwordx4 v[42:43], off
	s_setprio 0
	s_waitcnt vmcnt(8)
	s_waitcnt lgkmcnt(0)
	s_barrier
	s_waitcnt lgkmcnt(0)
	v_mfma_f32_16x16x32_bf16 v[42:45], v[22:25], v[34:37], v[144:147]
	v_mfma_f32_16x16x32_bf16 v[110:113], v[26:29], v[38:41], v[42:45]
	v_mfma_f32_16x16x32_bf16 v[42:45], v[30:33], v[34:37], v[148:151]
	v_mfma_f32_16x16x32_bf16 v[106:109], v[206:209], v[38:41], v[42:45]
	v_mfma_f32_16x16x32_bf16 v[42:45], v[22:25], v[234:237], v[152:155]
	v_mfma_f32_16x16x32_bf16 v[102:105], v[26:29], v[238:241], v[42:45]
	v_mfma_f32_16x16x32_bf16 v[42:45], v[30:33], v[234:237], v[162:165]
	v_mfma_f32_16x16x32_bf16 v[98:101], v[206:209], v[238:241], v[42:45]
	v_mfma_f32_16x16x32_bf16 v[42:45], v[22:25], v[242:245], v[166:169]
	v_mfma_f32_16x16x32_bf16 v[94:97], v[26:29], v[246:249], v[42:45]
	v_mfma_f32_16x16x32_bf16 v[42:45], v[30:33], v[242:245], v[170:173]
	v_mfma_f32_16x16x32_bf16 v[22:25], v[22:25], v[250:253], v[174:177]
	v_mfma_f32_16x16x32_bf16 v[10:13], v[30:33], v[250:253], v[10:13]
	v_mfma_f32_16x16x32_bf16 v[90:93], v[206:209], v[246:249], v[42:45]
	v_mfma_f32_16x16x32_bf16 v[86:89], v[26:29], v[190:193], v[22:25]
	v_mfma_f32_16x16x32_bf16 v[82:85], v[206:209], v[190:193], v[10:13]
	v_mfma_f32_16x16x32_bf16 v[10:13], v[218:221], v[34:37], v[14:17]
	v_mfma_f32_16x16x32_bf16 v[46:49], v[222:225], v[38:41], v[10:13]
	v_mfma_f32_16x16x32_bf16 v[10:13], v[226:229], v[34:37], v[178:181]
	v_mfma_f32_16x16x32_bf16 v[42:45], v[230:233], v[38:41], v[10:13]
	v_mfma_f32_16x16x32_bf16 v[10:13], v[218:221], v[234:237], v[182:185]
	v_mfma_f32_16x16x32_bf16 v[38:41], v[222:225], v[238:241], v[10:13]
	v_mfma_f32_16x16x32_bf16 v[10:13], v[226:229], v[234:237], v[186:189]
	v_mfma_f32_16x16x32_bf16 v[34:37], v[230:233], v[238:241], v[10:13]
	v_mfma_f32_16x16x32_bf16 v[10:13], v[218:221], v[242:245], v[194:197]
	v_mfma_f32_16x16x32_bf16 v[30:33], v[222:225], v[246:249], v[10:13]
	v_mfma_f32_16x16x32_bf16 v[10:13], v[226:229], v[242:245], v[198:201]
	v_mfma_f32_16x16x32_bf16 v[26:29], v[230:233], v[246:249], v[10:13]
	v_mfma_f32_16x16x32_bf16 v[10:13], v[218:221], v[250:253], v[18:21]
	v_mfma_f32_16x16x32_bf16 v[22:25], v[222:225], v[190:193], v[10:13]
	v_mfma_f32_16x16x32_bf16 v[10:13], v[226:229], v[250:253], v[202:205]
	v_mfma_f32_16x16x32_bf16 v[18:21], v[230:233], v[190:193], v[10:13]
	s_barrier
	s_setprio 1
	s_andn2_b64 vcc, exec, s[50:51]
	s_cbranch_vccnz .LBB0_573
	s_barrier

.LBB0_1525:
	s_add_u32 s20, s6, 0xfffc0080
	s_addc_u32 s21, s7, -1
	s_add_i32 s37, 0, 0x10000
	s_cmp_eq_u32 s71, 12
	s_cselect_b32 s51, s19, s21
	s_cselect_b32 s50, s18, s20
	s_cselect_b32 s49, s17, s70
	s_cselect_b32 s48, s47, s69
	s_add_i32 s72, 0, 0x14000
	v_add_u32_e32 v156, s37, v145
	v_add_u32_e32 v172, s72, v145
	ds_read_b128 v[140:143], v156
	ds_read_b128 v[148:151], v156 offset:1024
	ds_read_b128 v[152:155], v156 offset:2048
	ds_read_b128 v[156:159], v156 offset:3072
	ds_read_b128 v[160:163], v172
	ds_read_b128 v[164:167], v172 offset:1024
	ds_read_b128 v[168:171], v172 offset:2048
	ds_read_b128 v[172:175], v172 offset:3072
	s_add_i32 m0, s58, 0xc000
	ds_read_b128 v[176:179], v147
	ds_read_b128 v[180:183], v147 offset:1024
	ds_read_b128 v[184:187], v147 offset:2048
	ds_read_b128 v[188:191], v147 offset:3072
	ds_read_b128 v[192:195], v147 offset:4096
	ds_read_b128 v[196:199], v147 offset:5120
	ds_read_b128 v[200:203], v147 offset:6144
	ds_read_b128 v[204:207], v147 offset:7168
	global_load_lds_dwordx4 v136, s[6:7]
	s_add_i32 m0, s58, 0xe000
	s_nop 0
	global_load_lds_dwordx4 v138, s[6:7]
	s_setprio 0
	s_waitcnt vmcnt(8)
	s_waitcnt lgkmcnt(0)
	s_barrier
	s_waitcnt lgkmcnt(0)
	v_mfma_f32_16x16x32_bf16 v[126:129], v[140:143], v[176:179], v[126:129]
	v_mfma_f32_16x16x32_bf16 v[122:125], v[152:155], v[176:179], v[122:125]
	v_mfma_f32_16x16x32_bf16 v[114:117], v[140:143], v[184:187], v[114:117]
	v_mfma_f32_16x16x32_bf16 v[106:109], v[152:155], v[184:187], v[106:109]
	v_mfma_f32_16x16x32_bf16 v[98:101], v[140:143], v[192:195], v[98:101]
	v_mfma_f32_16x16x32_bf16 v[90:93], v[152:155], v[192:195], v[90:93]
	v_mfma_f32_16x16x32_bf16 v[82:85], v[140:143], v[200:203], v[82:85]
	v_mfma_f32_16x16x32_bf16 v[74:77], v[152:155], v[200:203], v[74:77]
	v_mfma_f32_16x16x32_bf16 v[126:129], v[148:151], v[180:183], v[126:129]
	v_mfma_f32_16x16x32_bf16 v[122:125], v[156:159], v[180:183], v[122:125]
	v_mfma_f32_16x16x32_bf16 v[114:117], v[148:151], v[188:191], v[114:117]
	v_mfma_f32_16x16x32_bf16 v[106:109], v[156:159], v[188:191], v[106:109]
	v_mfma_f32_16x16x32_bf16 v[98:101], v[148:151], v[196:199], v[98:101]
	v_mfma_f32_16x16x32_bf16 v[90:93], v[156:159], v[196:199], v[90:93]
	v_mfma_f32_16x16x32_bf16 v[82:85], v[148:151], v[204:207], v[82:85]
	v_mfma_f32_16x16x32_bf16 v[74:77], v[156:159], v[204:207], v[74:77]
	v_mfma_f32_16x16x32_bf16 v[118:121], v[160:163], v[176:179], v[118:121]
	v_mfma_f32_16x16x32_bf16 v[110:113], v[168:171], v[176:179], v[110:113]
	v_mfma_f32_16x16x32_bf16 v[102:105], v[160:163], v[184:187], v[102:105]
	v_mfma_f32_16x16x32_bf16 v[94:97], v[168:171], v[184:187], v[94:97]
	v_mfma_f32_16x16x32_bf16 v[86:89], v[160:163], v[192:195], v[86:89]
	v_mfma_f32_16x16x32_bf16 v[78:81], v[168:171], v[192:195], v[78:81]
	v_mfma_f32_16x16x32_bf16 v[70:73], v[160:163], v[200:203], v[70:73]
	v_mfma_f32_16x16x32_bf16 v[66:69], v[168:171], v[200:203], v[66:69]
	v_mfma_f32_16x16x32_bf16 v[118:121], v[164:167], v[180:183], v[118:121]
	v_mfma_f32_16x16x32_bf16 v[110:113], v[172:175], v[180:183], v[110:113]
	v_mfma_f32_16x16x32_bf16 v[102:105], v[164:167], v[188:191], v[102:105]
	v_mfma_f32_16x16x32_bf16 v[94:97], v[172:175], v[188:191], v[94:97]
	v_mfma_f32_16x16x32_bf16 v[86:89], v[164:167], v[196:199], v[86:89]
	v_mfma_f32_16x16x32_bf16 v[78:81], v[172:175], v[196:199], v[78:81]
	v_mfma_f32_16x16x32_bf16 v[70:73], v[164:167], v[204:207], v[70:73]
	v_mfma_f32_16x16x32_bf16 v[66:69], v[172:175], v[204:207], v[66:69]
	s_barrier
	s_setprio 1
	s_add_i32 s20, s37, s57
	v_lshl_add_u64 v[208:209], s[48:49], 0, v[0:1]
	s_mov_b32 m0, s20
	ds_read_b128 v[176:179], v147 offset:16384
	ds_read_b128 v[180:183], v147 offset:17408
	ds_read_b128 v[184:187], v147 offset:18432
	ds_read_b128 v[188:191], v147 offset:19456
	ds_read_b128 v[192:195], v147 offset:20480
	ds_read_b128 v[196:199], v147 offset:21504
	ds_read_b128 v[200:203], v147 offset:22528
	ds_read_b128 v[204:207], v147 offset:23552
	global_load_lds_dwordx4 v[208:209], off
	s_add_i32 m0, s20, 0x2000
	s_add_u32 s20, s48, 0x40000
	v_lshl_add_u64 v[210:211], s[48:49], 0, v[134:135]
	s_addc_u32 s21, s49, 0
	s_add_i32 s37, s72, s57
	global_load_lds_dwordx4 v[210:211], off
	s_mov_b32 m0, s37
	v_lshl_add_u64 v[216:217], s[50:51], 0, v[132:133]
	global_load_lds_dwordx4 v0, s[20:21]
	s_add_i32 m0, s37, 0x2000
	s_nop 0
	global_load_lds_dwordx4 v134, s[20:21]
	v_lshl_add_u64 v[214:215], s[50:51], 0, v[130:131]
	s_mov_b32 m0, s58
	s_nop 0
	global_load_lds_dwordx4 v[214:215], off
	s_mov_b32 m0, s59
	s_nop 0
	global_load_lds_dwordx4 v[216:217], off
	s_setprio 0
	s_waitcnt vmcnt(8)
	s_waitcnt lgkmcnt(0)
	s_barrier
	s_waitcnt lgkmcnt(0)
	v_mfma_f32_16x16x32_bf16 v[62:65], v[140:143], v[176:179], v[62:65]
	v_mfma_f32_16x16x32_bf16 v[58:61], v[152:155], v[176:179], v[58:61]
	v_mfma_f32_16x16x32_bf16 v[50:53], v[140:143], v[184:187], v[50:53]
	v_mfma_f32_16x16x32_bf16 v[42:45], v[152:155], v[184:187], v[42:45]
	v_mfma_f32_16x16x32_bf16 v[34:37], v[140:143], v[192:195], v[34:37]
	v_mfma_f32_16x16x32_bf16 v[26:29], v[152:155], v[192:195], v[26:29]
	v_mfma_f32_16x16x32_bf16 v[18:21], v[140:143], v[200:203], v[18:21]
	v_mfma_f32_16x16x32_bf16 v[10:13], v[152:155], v[200:203], v[10:13]
	v_mfma_f32_16x16x32_bf16 v[62:65], v[148:151], v[180:183], v[62:65]
	v_mfma_f32_16x16x32_bf16 v[58:61], v[156:159], v[180:183], v[58:61]
	v_mfma_f32_16x16x32_bf16 v[50:53], v[148:151], v[188:191], v[50:53]
	v_mfma_f32_16x16x32_bf16 v[42:45], v[156:159], v[188:191], v[42:45]
	v_mfma_f32_16x16x32_bf16 v[34:37], v[148:151], v[196:199], v[34:37]
	v_mfma_f32_16x16x32_bf16 v[26:29], v[156:159], v[196:199], v[26:29]
	v_mfma_f32_16x16x32_bf16 v[18:21], v[148:151], v[204:207], v[18:21]
	v_mfma_f32_16x16x32_bf16 v[10:13], v[156:159], v[204:207], v[10:13]
	v_mfma_f32_16x16x32_bf16 v[54:57], v[160:163], v[176:179], v[54:57]
	v_mfma_f32_16x16x32_bf16 v[46:49], v[168:171], v[176:179], v[46:49]
	v_mfma_f32_16x16x32_bf16 v[38:41], v[160:163], v[184:187], v[38:41]
	v_mfma_f32_16x16x32_bf16 v[30:33], v[168:171], v[184:187], v[30:33]
	v_mfma_f32_16x16x32_bf16 v[22:25], v[160:163], v[192:195], v[22:25]
	v_mfma_f32_16x16x32_bf16 v[14:17], v[168:171], v[192:195], v[14:17]
	v_mfma_f32_16x16x32_bf16 v[6:9], v[160:163], v[200:203], v[6:9]
	v_mfma_f32_16x16x32_bf16 v[2:5], v[168:171], v[200:203], v[2:5]
	v_mfma_f32_16x16x32_bf16 v[54:57], v[164:167], v[180:183], v[54:57]
	v_mfma_f32_16x16x32_bf16 v[46:49], v[172:175], v[180:183], v[46:49]
	v_mfma_f32_16x16x32_bf16 v[38:41], v[164:167], v[188:191], v[38:41]
	v_mfma_f32_16x16x32_bf16 v[30:33], v[172:175], v[188:191], v[30:33]
	v_mfma_f32_16x16x32_bf16 v[22:25], v[164:167], v[196:199], v[22:25]
	v_mfma_f32_16x16x32_bf16 v[14:17], v[172:175], v[196:199], v[14:17]
	v_mfma_f32_16x16x32_bf16 v[6:9], v[164:167], v[204:207], v[6:9]
	v_mfma_f32_16x16x32_bf16 v[2:5], v[172:175], v[204:207], v[2:5]
	s_barrier
	s_setprio 1
	s_add_i32 s37, 0, 0x18000
	s_add_i32 s72, 0, 0x1c000
	v_add_u32_e32 v156, s37, v145
	v_add_u32_e32 v172, s72, v145
	ds_read_b128 v[140:143], v156
	ds_read_b128 v[148:151], v156 offset:1024
	ds_read_b128 v[152:155], v156 offset:2048
	ds_read_b128 v[156:159], v156 offset:3072
	ds_read_b128 v[160:163], v172
	ds_read_b128 v[164:167], v172 offset:1024
	ds_read_b128 v[168:171], v172 offset:2048
	ds_read_b128 v[172:175], v172 offset:3072
	s_add_u32 s20, s50, 0x40000
	s_addc_u32 s21, s51, 0
	s_mov_b32 m0, s60
	ds_read_b128 v[176:179], v147 offset:32768
	ds_read_b128 v[180:183], v147 offset:33792
	ds_read_b128 v[184:187], v147 offset:34816
	ds_read_b128 v[188:191], v147 offset:35840
	ds_read_b128 v[192:195], v147 offset:36864
	ds_read_b128 v[196:199], v147 offset:37888
	ds_read_b128 v[200:203], v147 offset:38912
	ds_read_b128 v[204:207], v147 offset:39936
	global_load_lds_dwordx4 v130, s[20:21]
	v_lshl_add_u64 v[218:219], s[20:21], 0, v[132:133]
	s_mov_b32 m0, s61
	s_nop 0
	global_load_lds_dwordx4 v[218:219], off
	s_setprio 0
	s_waitcnt vmcnt(8)
	s_waitcnt lgkmcnt(0)
	s_barrier
	s_waitcnt lgkmcnt(0)
	v_mfma_f32_16x16x32_bf16 v[126:129], v[140:143], v[176:179], v[126:129]
	v_mfma_f32_16x16x32_bf16 v[122:125], v[152:155], v[176:179], v[122:125]
	v_mfma_f32_16x16x32_bf16 v[114:117], v[140:143], v[184:187], v[114:117]
	v_mfma_f32_16x16x32_bf16 v[106:109], v[152:155], v[184:187], v[106:109]
	v_mfma_f32_16x16x32_bf16 v[98:101], v[140:143], v[192:195], v[98:101]
	v_mfma_f32_16x16x32_bf16 v[90:93], v[152:155], v[192:195], v[90:93]
	v_mfma_f32_16x16x32_bf16 v[82:85], v[140:143], v[200:203], v[82:85]
	v_mfma_f32_16x16x32_bf16 v[74:77], v[152:155], v[200:203], v[74:77]
	v_mfma_f32_16x16x32_bf16 v[126:129], v[148:151], v[180:183], v[126:129]
	v_mfma_f32_16x16x32_bf16 v[122:125], v[156:159], v[180:183], v[122:125]
	v_mfma_f32_16x16x32_bf16 v[114:117], v[148:151], v[188:191], v[114:117]
	v_mfma_f32_16x16x32_bf16 v[106:109], v[156:159], v[188:191], v[106:109]
	v_mfma_f32_16x16x32_bf16 v[98:101], v[148:151], v[196:199], v[98:101]
	v_mfma_f32_16x16x32_bf16 v[90:93], v[156:159], v[196:199], v[90:93]
	v_mfma_f32_16x16x32_bf16 v[82:85], v[148:151], v[204:207], v[82:85]
	v_mfma_f32_16x16x32_bf16 v[74:77], v[156:159], v[204:207], v[74:77]
	v_mfma_f32_16x16x32_bf16 v[118:121], v[160:163], v[176:179], v[118:121]
	v_mfma_f32_16x16x32_bf16 v[110:113], v[168:171], v[176:179], v[110:113]
	v_mfma_f32_16x16x32_bf16 v[102:105], v[160:163], v[184:187], v[102:105]
	v_mfma_f32_16x16x32_bf16 v[94:97], v[168:171], v[184:187], v[94:97]
	v_mfma_f32_16x16x32_bf16 v[86:89], v[160:163], v[192:195], v[86:89]
	v_mfma_f32_16x16x32_bf16 v[78:81], v[168:171], v[192:195], v[78:81]
	v_mfma_f32_16x16x32_bf16 v[70:73], v[160:163], v[200:203], v[70:73]
	v_mfma_f32_16x16x32_bf16 v[66:69], v[168:171], v[200:203], v[66:69]
	v_mfma_f32_16x16x32_bf16 v[118:121], v[164:167], v[180:183], v[118:121]
	v_mfma_f32_16x16x32_bf16 v[110:113], v[172:175], v[180:183], v[110:113]
	v_mfma_f32_16x16x32_bf16 v[102:105], v[164:167], v[188:191], v[102:105]
	v_mfma_f32_16x16x32_bf16 v[94:97], v[172:175], v[188:191], v[94:97]
	v_mfma_f32_16x16x32_bf16 v[86:89], v[164:167], v[196:199], v[86:89]
	v_mfma_f32_16x16x32_bf16 v[78:81], v[172:175], v[196:199], v[78:81]
	v_mfma_f32_16x16x32_bf16 v[70:73], v[164:167], v[204:207], v[70:73]
	v_mfma_f32_16x16x32_bf16 v[66:69], v[172:175], v[204:207], v[66:69]
	s_barrier
	s_setprio 1
	s_add_i32 s20, s37, s57
	v_lshl_add_u64 v[208:209], v[208:209], 0, s[24:25]
	s_mov_b32 m0, s20
	ds_read_b128 v[176:179], v147 offset:49152
	ds_read_b128 v[180:183], v147 offset:50176
	ds_read_b128 v[184:187], v147 offset:51200
	ds_read_b128 v[188:191], v147 offset:52224
	ds_read_b128 v[192:195], v147 offset:53248
	ds_read_b128 v[196:199], v147 offset:54272
	ds_read_b128 v[200:203], v147 offset:55296
	ds_read_b128 v[204:207], v147 offset:56320
	global_load_lds_dwordx4 v[208:209], off
	s_add_i32 m0, s20, 0x2000
	s_add_u32 s20, s48, 0x40080
	v_lshl_add_u64 v[208:209], v[210:211], 0, s[24:25]
	s_addc_u32 s21, s49, 0
	s_add_i32 s37, s72, s57
	global_load_lds_dwordx4 v[208:209], off
	s_mov_b32 m0, s37
	s_nop 0
	global_load_lds_dwordx4 v0, s[20:21]
	s_add_i32 m0, s37, 0x2000
	s_nop 0
	global_load_lds_dwordx4 v134, s[20:21]
	v_lshl_add_u64 v[208:209], v[214:215], 0, s[24:25]
	s_mov_b32 m0, s62
	s_nop 0
	global_load_lds_dwordx4 v[208:209], off
	v_lshl_add_u64 v[208:209], v[216:217], 0, s[24:25]
	s_mov_b32 m0, s63
	s_nop 0
	global_load_lds_dwordx4 v[208:209], off
	s_setprio 0
	s_waitcnt vmcnt(8)
	s_waitcnt lgkmcnt(0)
	s_barrier
	s_waitcnt lgkmcnt(0)
	v_mfma_f32_16x16x32_bf16 v[62:65], v[140:143], v[176:179], v[62:65]
	v_mfma_f32_16x16x32_bf16 v[58:61], v[152:155], v[176:179], v[58:61]
	v_mfma_f32_16x16x32_bf16 v[50:53], v[140:143], v[184:187], v[50:53]
	v_mfma_f32_16x16x32_bf16 v[42:45], v[152:155], v[184:187], v[42:45]
	v_mfma_f32_16x16x32_bf16 v[34:37], v[140:143], v[192:195], v[34:37]
	v_mfma_f32_16x16x32_bf16 v[26:29], v[152:155], v[192:195], v[26:29]
	v_mfma_f32_16x16x32_bf16 v[18:21], v[140:143], v[200:203], v[18:21]
	v_mfma_f32_16x16x32_bf16 v[10:13], v[152:155], v[200:203], v[10:13]
	v_mfma_f32_16x16x32_bf16 v[62:65], v[148:151], v[180:183], v[62:65]
	v_mfma_f32_16x16x32_bf16 v[58:61], v[156:159], v[180:183], v[58:61]
	v_mfma_f32_16x16x32_bf16 v[50:53], v[148:151], v[188:191], v[50:53]
	v_mfma_f32_16x16x32_bf16 v[42:45], v[156:159], v[188:191], v[42:45]
	v_mfma_f32_16x16x32_bf16 v[34:37], v[148:151], v[196:199], v[34:37]
	v_mfma_f32_16x16x32_bf16 v[26:29], v[156:159], v[196:199], v[26:29]
	v_mfma_f32_16x16x32_bf16 v[18:21], v[148:151], v[204:207], v[18:21]
	v_mfma_f32_16x16x32_bf16 v[10:13], v[156:159], v[204:207], v[10:13]
	v_mfma_f32_16x16x32_bf16 v[54:57], v[160:163], v[176:179], v[54:57]
	v_mfma_f32_16x16x32_bf16 v[46:49], v[168:171], v[176:179], v[46:49]
	v_mfma_f32_16x16x32_bf16 v[38:41], v[160:163], v[184:187], v[38:41]
	v_mfma_f32_16x16x32_bf16 v[30:33], v[168:171], v[184:187], v[30:33]
	v_mfma_f32_16x16x32_bf16 v[22:25], v[160:163], v[192:195], v[22:25]
	v_mfma_f32_16x16x32_bf16 v[14:17], v[168:171], v[192:195], v[14:17]
	v_mfma_f32_16x16x32_bf16 v[6:9], v[160:163], v[200:203], v[6:9]
	v_mfma_f32_16x16x32_bf16 v[2:5], v[168:171], v[200:203], v[2:5]
	v_mfma_f32_16x16x32_bf16 v[54:57], v[164:167], v[180:183], v[54:57]
	v_mfma_f32_16x16x32_bf16 v[46:49], v[172:175], v[180:183], v[46:49]
	v_mfma_f32_16x16x32_bf16 v[38:41], v[164:167], v[188:191], v[38:41]
	v_mfma_f32_16x16x32_bf16 v[30:33], v[172:175], v[188:191], v[30:33]
	v_mfma_f32_16x16x32_bf16 v[22:25], v[164:167], v[196:199], v[22:25]
	v_mfma_f32_16x16x32_bf16 v[14:17], v[172:175], v[196:199], v[14:17]
	v_mfma_f32_16x16x32_bf16 v[6:9], v[164:167], v[204:207], v[6:9]
	v_mfma_f32_16x16x32_bf16 v[2:5], v[172:175], v[204:207], v[2:5]
	s_barrier
	s_setprio 1
	s_add_i32 s71, s71, 2
	s_add_u32 s6, s6, 0x100
	s_addc_u32 s7, s7, 0
	s_add_u32 s69, s69, 0x100
	s_addc_u32 s70, s70, 0
	s_cmp_gt_u32 s71, 13
	s_cbranch_scc0 .LBB0_1525
	s_and_b64 vcc, exec, s[12:13]
	s_cbranch_vccz .LBB0_1528
	s_barrier

.LBB0_1880:
	s_add_u32 s20, s4, 0xfffc0080
	s_addc_u32 s21, s5, -1
	s_add_i32 s37, 0, 0x10000
	s_cmp_eq_u32 s85, 12
	s_cselect_b32 s53, s45, s21
	s_cselect_b32 s52, s44, s20
	s_cselect_b32 s51, s43, s81
	s_cselect_b32 s50, s49, s73
	s_add_i32 s77, 0, 0x14000
	v_add_u32_e32 v152, s37, v142
	v_add_u32_e32 v168, s77, v142
	ds_read_b128 v[136:139], v152
	ds_read_b128 v[144:147], v152 offset:1024
	ds_read_b128 v[148:151], v152 offset:2048
	ds_read_b128 v[152:155], v152 offset:3072
	ds_read_b128 v[156:159], v168
	ds_read_b128 v[160:163], v168 offset:1024
	ds_read_b128 v[164:167], v168 offset:2048
	ds_read_b128 v[168:171], v168 offset:3072
	s_add_i32 m0, s60, 0xc000
	ds_read_b128 v[172:175], v143
	ds_read_b128 v[176:179], v143 offset:1024
	ds_read_b128 v[180:183], v143 offset:2048
	ds_read_b128 v[184:187], v143 offset:3072
	ds_read_b128 v[188:191], v143 offset:4096
	ds_read_b128 v[192:195], v143 offset:5120
	ds_read_b128 v[196:199], v143 offset:6144
	ds_read_b128 v[200:203], v143 offset:7168
	global_load_lds_dwordx4 v132, s[4:5]
	s_add_i32 m0, s60, 0xe000
	s_nop 0
	global_load_lds_dwordx4 v134, s[4:5]
	s_setprio 0
	s_waitcnt vmcnt(8)
	s_waitcnt lgkmcnt(0)
	s_barrier
	s_waitcnt lgkmcnt(0)
	v_mfma_f32_16x16x32_bf16 v[126:129], v[136:139], v[172:175], v[126:129]
	v_mfma_f32_16x16x32_bf16 v[122:125], v[148:151], v[172:175], v[122:125]
	v_mfma_f32_16x16x32_bf16 v[110:113], v[136:139], v[180:183], v[110:113]
	v_mfma_f32_16x16x32_bf16 v[106:109], v[148:151], v[180:183], v[106:109]
	v_mfma_f32_16x16x32_bf16 v[94:97], v[136:139], v[188:191], v[94:97]
	v_mfma_f32_16x16x32_bf16 v[90:93], v[148:151], v[188:191], v[90:93]
	v_mfma_f32_16x16x32_bf16 v[78:81], v[136:139], v[196:199], v[78:81]
	v_mfma_f32_16x16x32_bf16 v[74:77], v[148:151], v[196:199], v[74:77]
	v_mfma_f32_16x16x32_bf16 v[126:129], v[144:147], v[176:179], v[126:129]
	v_mfma_f32_16x16x32_bf16 v[122:125], v[152:155], v[176:179], v[122:125]
	v_mfma_f32_16x16x32_bf16 v[110:113], v[144:147], v[184:187], v[110:113]
	v_mfma_f32_16x16x32_bf16 v[106:109], v[152:155], v[184:187], v[106:109]
	v_mfma_f32_16x16x32_bf16 v[94:97], v[144:147], v[192:195], v[94:97]
	v_mfma_f32_16x16x32_bf16 v[90:93], v[152:155], v[192:195], v[90:93]
	v_mfma_f32_16x16x32_bf16 v[78:81], v[144:147], v[200:203], v[78:81]
	v_mfma_f32_16x16x32_bf16 v[74:77], v[152:155], v[200:203], v[74:77]
	v_mfma_f32_16x16x32_bf16 v[118:121], v[156:159], v[172:175], v[118:121]
	v_mfma_f32_16x16x32_bf16 v[114:117], v[164:167], v[172:175], v[114:117]
	v_mfma_f32_16x16x32_bf16 v[102:105], v[156:159], v[180:183], v[102:105]
	v_mfma_f32_16x16x32_bf16 v[98:101], v[164:167], v[180:183], v[98:101]
	v_mfma_f32_16x16x32_bf16 v[86:89], v[156:159], v[188:191], v[86:89]
	v_mfma_f32_16x16x32_bf16 v[82:85], v[164:167], v[188:191], v[82:85]
	v_mfma_f32_16x16x32_bf16 v[70:73], v[156:159], v[196:199], v[70:73]
	v_mfma_f32_16x16x32_bf16 v[66:69], v[164:167], v[196:199], v[66:69]
	v_mfma_f32_16x16x32_bf16 v[118:121], v[160:163], v[176:179], v[118:121]
	v_mfma_f32_16x16x32_bf16 v[114:117], v[168:171], v[176:179], v[114:117]
	v_mfma_f32_16x16x32_bf16 v[102:105], v[160:163], v[184:187], v[102:105]
	v_mfma_f32_16x16x32_bf16 v[98:101], v[168:171], v[184:187], v[98:101]
	v_mfma_f32_16x16x32_bf16 v[86:89], v[160:163], v[192:195], v[86:89]
	v_mfma_f32_16x16x32_bf16 v[82:85], v[168:171], v[192:195], v[82:85]
	v_mfma_f32_16x16x32_bf16 v[70:73], v[160:163], v[200:203], v[70:73]
	v_mfma_f32_16x16x32_bf16 v[66:69], v[168:171], v[200:203], v[66:69]
	s_barrier
	s_setprio 1
	s_add_i32 s20, s37, s59
	v_lshl_add_u64 v[204:205], s[50:51], 0, v[0:1]
	s_mov_b32 m0, s20
	ds_read_b128 v[172:175], v143 offset:16384
	ds_read_b128 v[176:179], v143 offset:17408
	ds_read_b128 v[180:183], v143 offset:18432
	ds_read_b128 v[184:187], v143 offset:19456
	ds_read_b128 v[188:191], v143 offset:20480
	ds_read_b128 v[192:195], v143 offset:21504
	ds_read_b128 v[196:199], v143 offset:22528
	ds_read_b128 v[200:203], v143 offset:23552
	global_load_lds_dwordx4 v[204:205], off
	s_add_i32 m0, s20, 0x2000
	s_add_u32 s20, s50, 0x40000
	v_lshl_add_u64 v[206:207], s[50:51], 0, v[130:131]
	s_addc_u32 s21, s51, 0
	s_add_i32 s37, s77, s59
	global_load_lds_dwordx4 v[206:207], off
	s_mov_b32 m0, s37
	v_lshl_add_u64 v[210:211], s[52:53], 0, v[130:131]
	global_load_lds_dwordx4 v0, s[20:21]
	s_add_i32 m0, s37, 0x2000
	s_nop 0
	global_load_lds_dwordx4 v130, s[20:21]
	v_lshl_add_u64 v[208:209], s[52:53], 0, v[0:1]
	s_mov_b32 m0, s60
	s_nop 0
	global_load_lds_dwordx4 v[208:209], off
	s_mov_b32 m0, s61
	s_nop 0
	global_load_lds_dwordx4 v[210:211], off
	s_setprio 0
	s_waitcnt vmcnt(8)
	s_waitcnt lgkmcnt(0)
	s_barrier
	s_waitcnt lgkmcnt(0)
	v_mfma_f32_16x16x32_bf16 v[62:65], v[136:139], v[172:175], v[62:65]
	v_mfma_f32_16x16x32_bf16 v[58:61], v[148:151], v[172:175], v[58:61]
	v_mfma_f32_16x16x32_bf16 v[46:49], v[136:139], v[180:183], v[46:49]
	v_mfma_f32_16x16x32_bf16 v[42:45], v[148:151], v[180:183], v[42:45]
	v_mfma_f32_16x16x32_bf16 v[30:33], v[136:139], v[188:191], v[30:33]
	v_mfma_f32_16x16x32_bf16 v[26:29], v[148:151], v[188:191], v[26:29]
	v_mfma_f32_16x16x32_bf16 v[14:17], v[136:139], v[196:199], v[14:17]
	v_mfma_f32_16x16x32_bf16 v[10:13], v[148:151], v[196:199], v[10:13]
	v_mfma_f32_16x16x32_bf16 v[62:65], v[144:147], v[176:179], v[62:65]
	v_mfma_f32_16x16x32_bf16 v[58:61], v[152:155], v[176:179], v[58:61]
	v_mfma_f32_16x16x32_bf16 v[46:49], v[144:147], v[184:187], v[46:49]
	v_mfma_f32_16x16x32_bf16 v[42:45], v[152:155], v[184:187], v[42:45]
	v_mfma_f32_16x16x32_bf16 v[30:33], v[144:147], v[192:195], v[30:33]
	v_mfma_f32_16x16x32_bf16 v[26:29], v[152:155], v[192:195], v[26:29]
	v_mfma_f32_16x16x32_bf16 v[14:17], v[144:147], v[200:203], v[14:17]
	v_mfma_f32_16x16x32_bf16 v[10:13], v[152:155], v[200:203], v[10:13]
	v_mfma_f32_16x16x32_bf16 v[54:57], v[156:159], v[172:175], v[54:57]
	v_mfma_f32_16x16x32_bf16 v[50:53], v[164:167], v[172:175], v[50:53]
	v_mfma_f32_16x16x32_bf16 v[38:41], v[156:159], v[180:183], v[38:41]
	v_mfma_f32_16x16x32_bf16 v[34:37], v[164:167], v[180:183], v[34:37]
	v_mfma_f32_16x16x32_bf16 v[22:25], v[156:159], v[188:191], v[22:25]
	v_mfma_f32_16x16x32_bf16 v[18:21], v[164:167], v[188:191], v[18:21]
	v_mfma_f32_16x16x32_bf16 v[6:9], v[156:159], v[196:199], v[6:9]
	v_mfma_f32_16x16x32_bf16 v[2:5], v[164:167], v[196:199], v[2:5]
	v_mfma_f32_16x16x32_bf16 v[54:57], v[160:163], v[176:179], v[54:57]
	v_mfma_f32_16x16x32_bf16 v[50:53], v[168:171], v[176:179], v[50:53]
	v_mfma_f32_16x16x32_bf16 v[38:41], v[160:163], v[184:187], v[38:41]
	v_mfma_f32_16x16x32_bf16 v[34:37], v[168:171], v[184:187], v[34:37]
	v_mfma_f32_16x16x32_bf16 v[22:25], v[160:163], v[192:195], v[22:25]
	v_mfma_f32_16x16x32_bf16 v[18:21], v[168:171], v[192:195], v[18:21]
	v_mfma_f32_16x16x32_bf16 v[6:9], v[160:163], v[200:203], v[6:9]
	v_mfma_f32_16x16x32_bf16 v[2:5], v[168:171], v[200:203], v[2:5]
	s_barrier
	s_setprio 1
	s_add_i32 s37, 0, 0x18000
	s_add_i32 s77, 0, 0x1c000
	v_add_u32_e32 v152, s37, v142
	v_add_u32_e32 v168, s77, v142
	ds_read_b128 v[136:139], v152
	ds_read_b128 v[144:147], v152 offset:1024
	ds_read_b128 v[148:151], v152 offset:2048
	ds_read_b128 v[152:155], v152 offset:3072
	ds_read_b128 v[156:159], v168
	ds_read_b128 v[160:163], v168 offset:1024
	ds_read_b128 v[164:167], v168 offset:2048
	ds_read_b128 v[168:171], v168 offset:3072
	s_add_u32 s20, s52, 0x40000
	s_addc_u32 s21, s53, 0
	s_mov_b32 m0, s62
	ds_read_b128 v[172:175], v143 offset:32768
	ds_read_b128 v[176:179], v143 offset:33792
	ds_read_b128 v[180:183], v143 offset:34816
	ds_read_b128 v[184:187], v143 offset:35840
	ds_read_b128 v[188:191], v143 offset:36864
	ds_read_b128 v[192:195], v143 offset:37888
	ds_read_b128 v[196:199], v143 offset:38912
	ds_read_b128 v[200:203], v143 offset:39936
	global_load_lds_dwordx4 v0, s[20:21]
	v_lshl_add_u64 v[214:215], s[20:21], 0, v[130:131]
	s_mov_b32 m0, s63
	s_nop 0
	global_load_lds_dwordx4 v[214:215], off
	s_setprio 0
	s_waitcnt vmcnt(8)
	s_waitcnt lgkmcnt(0)
	s_barrier
	s_waitcnt lgkmcnt(0)
	v_mfma_f32_16x16x32_bf16 v[126:129], v[136:139], v[172:175], v[126:129]
	v_mfma_f32_16x16x32_bf16 v[122:125], v[148:151], v[172:175], v[122:125]
	v_mfma_f32_16x16x32_bf16 v[110:113], v[136:139], v[180:183], v[110:113]
	v_mfma_f32_16x16x32_bf16 v[106:109], v[148:151], v[180:183], v[106:109]
	v_mfma_f32_16x16x32_bf16 v[94:97], v[136:139], v[188:191], v[94:97]
	v_mfma_f32_16x16x32_bf16 v[90:93], v[148:151], v[188:191], v[90:93]
	v_mfma_f32_16x16x32_bf16 v[78:81], v[136:139], v[196:199], v[78:81]
	v_mfma_f32_16x16x32_bf16 v[74:77], v[148:151], v[196:199], v[74:77]
	v_mfma_f32_16x16x32_bf16 v[126:129], v[144:147], v[176:179], v[126:129]
	v_mfma_f32_16x16x32_bf16 v[122:125], v[152:155], v[176:179], v[122:125]
	v_mfma_f32_16x16x32_bf16 v[110:113], v[144:147], v[184:187], v[110:113]
	v_mfma_f32_16x16x32_bf16 v[106:109], v[152:155], v[184:187], v[106:109]
	v_mfma_f32_16x16x32_bf16 v[94:97], v[144:147], v[192:195], v[94:97]
	v_mfma_f32_16x16x32_bf16 v[90:93], v[152:155], v[192:195], v[90:93]
	v_mfma_f32_16x16x32_bf16 v[78:81], v[144:147], v[200:203], v[78:81]
	v_mfma_f32_16x16x32_bf16 v[74:77], v[152:155], v[200:203], v[74:77]
	v_mfma_f32_16x16x32_bf16 v[118:121], v[156:159], v[172:175], v[118:121]
	v_mfma_f32_16x16x32_bf16 v[114:117], v[164:167], v[172:175], v[114:117]
	v_mfma_f32_16x16x32_bf16 v[102:105], v[156:159], v[180:183], v[102:105]
	v_mfma_f32_16x16x32_bf16 v[98:101], v[164:167], v[180:183], v[98:101]
	v_mfma_f32_16x16x32_bf16 v[86:89], v[156:159], v[188:191], v[86:89]
	v_mfma_f32_16x16x32_bf16 v[82:85], v[164:167], v[188:191], v[82:85]
	v_mfma_f32_16x16x32_bf16 v[70:73], v[156:159], v[196:199], v[70:73]
	v_mfma_f32_16x16x32_bf16 v[66:69], v[164:167], v[196:199], v[66:69]
	v_mfma_f32_16x16x32_bf16 v[118:121], v[160:163], v[176:179], v[118:121]
	v_mfma_f32_16x16x32_bf16 v[114:117], v[168:171], v[176:179], v[114:117]
	v_mfma_f32_16x16x32_bf16 v[102:105], v[160:163], v[184:187], v[102:105]
	v_mfma_f32_16x16x32_bf16 v[98:101], v[168:171], v[184:187], v[98:101]
	v_mfma_f32_16x16x32_bf16 v[86:89], v[160:163], v[192:195], v[86:89]
	v_mfma_f32_16x16x32_bf16 v[82:85], v[168:171], v[192:195], v[82:85]
	v_mfma_f32_16x16x32_bf16 v[70:73], v[160:163], v[200:203], v[70:73]
	v_mfma_f32_16x16x32_bf16 v[66:69], v[168:171], v[200:203], v[66:69]
	s_barrier
	s_setprio 1
	s_add_i32 s20, s37, s59
	v_lshl_add_u64 v[204:205], v[204:205], 0, s[24:25]
	s_mov_b32 m0, s20
	ds_read_b128 v[172:175], v143 offset:49152
	ds_read_b128 v[176:179], v143 offset:50176
	ds_read_b128 v[180:183], v143 offset:51200
	ds_read_b128 v[184:187], v143 offset:52224
	ds_read_b128 v[188:191], v143 offset:53248
	ds_read_b128 v[192:195], v143 offset:54272
	ds_read_b128 v[196:199], v143 offset:55296
	ds_read_b128 v[200:203], v143 offset:56320
	global_load_lds_dwordx4 v[204:205], off
	s_add_i32 m0, s20, 0x2000
	s_add_u32 s20, s50, 0x40080
	v_lshl_add_u64 v[204:205], v[206:207], 0, s[24:25]
	s_addc_u32 s21, s51, 0
	s_add_i32 s37, s77, s59
	global_load_lds_dwordx4 v[204:205], off
	s_mov_b32 m0, s37
	s_nop 0
	global_load_lds_dwordx4 v0, s[20:21]
	s_add_i32 m0, s37, 0x2000
	s_nop 0
	global_load_lds_dwordx4 v130, s[20:21]
	v_lshl_add_u64 v[204:205], v[208:209], 0, s[24:25]
	s_mov_b32 m0, s67
	s_nop 0
	global_load_lds_dwordx4 v[204:205], off
	v_lshl_add_u64 v[204:205], v[210:211], 0, s[24:25]
	s_mov_b32 m0, s68
	s_nop 0
	global_load_lds_dwordx4 v[204:205], off
	s_setprio 0
	s_waitcnt vmcnt(8)
	s_waitcnt lgkmcnt(0)
	s_barrier
	s_waitcnt lgkmcnt(0)
	v_mfma_f32_16x16x32_bf16 v[62:65], v[136:139], v[172:175], v[62:65]
	v_mfma_f32_16x16x32_bf16 v[58:61], v[148:151], v[172:175], v[58:61]
	v_mfma_f32_16x16x32_bf16 v[46:49], v[136:139], v[180:183], v[46:49]
	v_mfma_f32_16x16x32_bf16 v[42:45], v[148:151], v[180:183], v[42:45]
	v_mfma_f32_16x16x32_bf16 v[30:33], v[136:139], v[188:191], v[30:33]
	v_mfma_f32_16x16x32_bf16 v[26:29], v[148:151], v[188:191], v[26:29]
	v_mfma_f32_16x16x32_bf16 v[14:17], v[136:139], v[196:199], v[14:17]
	v_mfma_f32_16x16x32_bf16 v[10:13], v[148:151], v[196:199], v[10:13]
	v_mfma_f32_16x16x32_bf16 v[62:65], v[144:147], v[176:179], v[62:65]
	v_mfma_f32_16x16x32_bf16 v[58:61], v[152:155], v[176:179], v[58:61]
	v_mfma_f32_16x16x32_bf16 v[46:49], v[144:147], v[184:187], v[46:49]
	v_mfma_f32_16x16x32_bf16 v[42:45], v[152:155], v[184:187], v[42:45]
	v_mfma_f32_16x16x32_bf16 v[30:33], v[144:147], v[192:195], v[30:33]
	v_mfma_f32_16x16x32_bf16 v[26:29], v[152:155], v[192:195], v[26:29]
	v_mfma_f32_16x16x32_bf16 v[14:17], v[144:147], v[200:203], v[14:17]
	v_mfma_f32_16x16x32_bf16 v[10:13], v[152:155], v[200:203], v[10:13]
	v_mfma_f32_16x16x32_bf16 v[54:57], v[156:159], v[172:175], v[54:57]
	v_mfma_f32_16x16x32_bf16 v[50:53], v[164:167], v[172:175], v[50:53]
	v_mfma_f32_16x16x32_bf16 v[38:41], v[156:159], v[180:183], v[38:41]
	v_mfma_f32_16x16x32_bf16 v[34:37], v[164:167], v[180:183], v[34:37]
	v_mfma_f32_16x16x32_bf16 v[22:25], v[156:159], v[188:191], v[22:25]
	v_mfma_f32_16x16x32_bf16 v[18:21], v[164:167], v[188:191], v[18:21]
	v_mfma_f32_16x16x32_bf16 v[6:9], v[156:159], v[196:199], v[6:9]
	v_mfma_f32_16x16x32_bf16 v[2:5], v[164:167], v[196:199], v[2:5]
	v_mfma_f32_16x16x32_bf16 v[54:57], v[160:163], v[176:179], v[54:57]
	v_mfma_f32_16x16x32_bf16 v[50:53], v[168:171], v[176:179], v[50:53]
	v_mfma_f32_16x16x32_bf16 v[38:41], v[160:163], v[184:187], v[38:41]
	v_mfma_f32_16x16x32_bf16 v[34:37], v[168:171], v[184:187], v[34:37]
	v_mfma_f32_16x16x32_bf16 v[22:25], v[160:163], v[192:195], v[22:25]
	v_mfma_f32_16x16x32_bf16 v[18:21], v[168:171], v[192:195], v[18:21]
	v_mfma_f32_16x16x32_bf16 v[6:9], v[160:163], v[200:203], v[6:9]
	v_mfma_f32_16x16x32_bf16 v[2:5], v[168:171], v[200:203], v[2:5]
	s_barrier
	s_setprio 1
	s_add_i32 s85, s85, 2
	s_add_u32 s4, s4, 0x100
	s_addc_u32 s5, s5, 0
	s_add_u32 s73, s73, 0x100
	s_addc_u32 s81, s81, 0
	s_cmp_gt_u32 s85, 13
	s_cbranch_scc0 .LBB0_1880
	s_and_b64 vcc, exec, s[18:19]
	s_cbranch_vccz .LBB0_1883
	s_barrier

.LBB0_1972:
	s_add_u32 s37, s48, s17
	s_addc_u32 s45, s49, 0
	s_add_u32 s52, s37, 0x100
	s_addc_u32 s53, s45, 0
	s_and_b64 s[20:21], s[50:51], exec
	s_cselect_b32 s55, s19, s53
	s_cselect_b32 s54, s18, s52
	s_add_u32 s17, s46, s17
	s_addc_u32 s20, s47, 0
	s_add_u32 s17, s17, 0x100
	s_addc_u32 s52, s20, 0
	s_add_i32 s78, 0, 0x10000
	s_and_b64 s[20:21], s[50:51], exec
	s_cselect_b32 s57, s43, s52
	s_cselect_b32 s56, s42, s17
	s_add_i32 s20, 0, 0x14000
	s_add_u32 s60, s37, 0x80080
	s_addc_u32 s61, s45, 0
	s_add_i32 s77, s78, s66
	s_add_i32 m0, s67, 0xc000
	s_add_i32 s21, s67, 0xe000
	s_add_i32 s37, s77, 0x2000
	s_add_u32 s58, s56, 0x40000
	v_add_u32_e32 v152, s78, v141
	v_add_u32_e32 v168, s20, v141
	s_addc_u32 s59, s57, 0
	s_add_i32 s83, s20, s66
	ds_read_b128 v[136:139], v152
	ds_read_b128 v[144:147], v152 offset:1024
	ds_read_b128 v[148:151], v152 offset:2048
	ds_read_b128 v[152:155], v152 offset:3072
	ds_read_b128 v[156:159], v168
	ds_read_b128 v[160:163], v168 offset:1024
	ds_read_b128 v[164:167], v168 offset:2048
	ds_read_b128 v[168:171], v168 offset:3072
	s_add_i32 s82, s83, 0x2000
	s_add_i32 s92, 0, 0x18000
	s_add_i32 s88, 0, 0x1c000
	s_add_u32 s52, s54, 0x80000
	s_addc_u32 s53, s55, 0
	s_add_i32 s45, s92, s66
	s_add_i32 s17, s45, 0x2000
	s_add_u32 s50, s56, 0x40080
	s_addc_u32 s51, s57, 0
	s_add_i32 s20, s88, s66
	s_add_i32 s78, s20, 0x2000
	ds_read_b128 v[172:175], v143
	ds_read_b128 v[176:179], v143 offset:1024
	ds_read_b128 v[180:183], v143 offset:2048
	ds_read_b128 v[184:187], v143 offset:3072
	ds_read_b128 v[188:191], v143 offset:4096
	ds_read_b128 v[192:195], v143 offset:5120
	ds_read_b128 v[196:199], v143 offset:6144
	ds_read_b128 v[200:203], v143 offset:7168
	global_load_lds_dwordx4 v130, s[60:61]
	s_mov_b32 m0, s21
	s_nop 0
	global_load_lds_dwordx4 v132, s[60:61]
	s_setprio 0
	s_waitcnt vmcnt(8)
	s_waitcnt lgkmcnt(0)
	s_barrier
	s_waitcnt lgkmcnt(0)
	v_mfma_f32_16x16x32_bf16 v[126:129], v[136:139], v[172:175], v[126:129]
	v_mfma_f32_16x16x32_bf16 v[122:125], v[148:151], v[172:175], v[122:125]
	v_mfma_f32_16x16x32_bf16 v[114:117], v[136:139], v[180:183], v[114:117]
	v_mfma_f32_16x16x32_bf16 v[106:109], v[148:151], v[180:183], v[106:109]
	v_mfma_f32_16x16x32_bf16 v[98:101], v[136:139], v[188:191], v[98:101]
	v_mfma_f32_16x16x32_bf16 v[90:93], v[148:151], v[188:191], v[90:93]
	v_mfma_f32_16x16x32_bf16 v[82:85], v[136:139], v[196:199], v[82:85]
	v_mfma_f32_16x16x32_bf16 v[74:77], v[148:151], v[196:199], v[74:77]
	v_mfma_f32_16x16x32_bf16 v[126:129], v[144:147], v[176:179], v[126:129]
	v_mfma_f32_16x16x32_bf16 v[122:125], v[152:155], v[176:179], v[122:125]
	v_mfma_f32_16x16x32_bf16 v[114:117], v[144:147], v[184:187], v[114:117]
	v_mfma_f32_16x16x32_bf16 v[106:109], v[152:155], v[184:187], v[106:109]
	v_mfma_f32_16x16x32_bf16 v[98:101], v[144:147], v[192:195], v[98:101]
	v_mfma_f32_16x16x32_bf16 v[90:93], v[152:155], v[192:195], v[90:93]
	v_mfma_f32_16x16x32_bf16 v[82:85], v[144:147], v[200:203], v[82:85]
	v_mfma_f32_16x16x32_bf16 v[74:77], v[152:155], v[200:203], v[74:77]
	v_mfma_f32_16x16x32_bf16 v[118:121], v[156:159], v[172:175], v[118:121]
	v_mfma_f32_16x16x32_bf16 v[110:113], v[164:167], v[172:175], v[110:113]
	v_mfma_f32_16x16x32_bf16 v[102:105], v[156:159], v[180:183], v[102:105]
	v_mfma_f32_16x16x32_bf16 v[94:97], v[164:167], v[180:183], v[94:97]
	v_mfma_f32_16x16x32_bf16 v[86:89], v[156:159], v[188:191], v[86:89]
	v_mfma_f32_16x16x32_bf16 v[78:81], v[164:167], v[188:191], v[78:81]
	v_mfma_f32_16x16x32_bf16 v[70:73], v[156:159], v[196:199], v[70:73]
	v_mfma_f32_16x16x32_bf16 v[66:69], v[164:167], v[196:199], v[66:69]
	v_mfma_f32_16x16x32_bf16 v[118:121], v[160:163], v[176:179], v[118:121]
	v_mfma_f32_16x16x32_bf16 v[110:113], v[168:171], v[176:179], v[110:113]
	v_mfma_f32_16x16x32_bf16 v[102:105], v[160:163], v[184:187], v[102:105]
	v_mfma_f32_16x16x32_bf16 v[94:97], v[168:171], v[184:187], v[94:97]
	v_mfma_f32_16x16x32_bf16 v[86:89], v[160:163], v[192:195], v[86:89]
	v_mfma_f32_16x16x32_bf16 v[78:81], v[168:171], v[192:195], v[78:81]
	v_mfma_f32_16x16x32_bf16 v[70:73], v[160:163], v[200:203], v[70:73]
	v_mfma_f32_16x16x32_bf16 v[66:69], v[168:171], v[200:203], v[66:69]
	s_barrier
	s_setprio 1
	s_mov_b32 m0, s77
	v_lshl_add_u64 v[204:205], s[56:57], 0, v[0:1]
	ds_read_b128 v[172:175], v143 offset:16384
	ds_read_b128 v[176:179], v143 offset:17408
	ds_read_b128 v[180:183], v143 offset:18432
	ds_read_b128 v[184:187], v143 offset:19456
	ds_read_b128 v[188:191], v143 offset:20480
	ds_read_b128 v[192:195], v143 offset:21504
	ds_read_b128 v[196:199], v143 offset:22528
	ds_read_b128 v[200:203], v143 offset:23552
	global_load_lds_dwordx4 v[204:205], off
	v_lshl_add_u64 v[206:207], s[56:57], 0, v[134:135]
	s_mov_b32 m0, s37
	global_load_lds_dwordx4 v[206:207], off
	s_mov_b32 m0, s83
	v_lshl_add_u64 v[210:211], s[54:55], 0, v[132:133]
	global_load_lds_dwordx4 v0, s[58:59]
	s_mov_b32 m0, s82
	s_nop 0
	global_load_lds_dwordx4 v134, s[58:59]
	v_lshl_add_u64 v[208:209], s[54:55], 0, v[130:131]
	s_mov_b32 m0, s67
	s_nop 0
	global_load_lds_dwordx4 v[208:209], off
	s_mov_b32 m0, s68
	s_nop 0
	global_load_lds_dwordx4 v[210:211], off
	s_setprio 0
	s_waitcnt vmcnt(8)
	s_waitcnt lgkmcnt(0)
	s_barrier
	s_waitcnt lgkmcnt(0)
	v_mfma_f32_16x16x32_bf16 v[62:65], v[136:139], v[172:175], v[62:65]
	v_mfma_f32_16x16x32_bf16 v[58:61], v[148:151], v[172:175], v[58:61]
	v_mfma_f32_16x16x32_bf16 v[50:53], v[136:139], v[180:183], v[50:53]
	v_mfma_f32_16x16x32_bf16 v[42:45], v[148:151], v[180:183], v[42:45]
	v_mfma_f32_16x16x32_bf16 v[34:37], v[136:139], v[188:191], v[34:37]
	v_mfma_f32_16x16x32_bf16 v[26:29], v[148:151], v[188:191], v[26:29]
	v_mfma_f32_16x16x32_bf16 v[18:21], v[136:139], v[196:199], v[18:21]
	v_mfma_f32_16x16x32_bf16 v[10:13], v[148:151], v[196:199], v[10:13]
	v_mfma_f32_16x16x32_bf16 v[62:65], v[144:147], v[176:179], v[62:65]
	v_mfma_f32_16x16x32_bf16 v[58:61], v[152:155], v[176:179], v[58:61]
	v_mfma_f32_16x16x32_bf16 v[50:53], v[144:147], v[184:187], v[50:53]
	v_mfma_f32_16x16x32_bf16 v[42:45], v[152:155], v[184:187], v[42:45]
	v_mfma_f32_16x16x32_bf16 v[34:37], v[144:147], v[192:195], v[34:37]
	v_mfma_f32_16x16x32_bf16 v[26:29], v[152:155], v[192:195], v[26:29]
	v_mfma_f32_16x16x32_bf16 v[18:21], v[144:147], v[200:203], v[18:21]
	v_mfma_f32_16x16x32_bf16 v[10:13], v[152:155], v[200:203], v[10:13]
	v_mfma_f32_16x16x32_bf16 v[54:57], v[156:159], v[172:175], v[54:57]
	v_mfma_f32_16x16x32_bf16 v[46:49], v[164:167], v[172:175], v[46:49]
	v_mfma_f32_16x16x32_bf16 v[38:41], v[156:159], v[180:183], v[38:41]
	v_mfma_f32_16x16x32_bf16 v[30:33], v[164:167], v[180:183], v[30:33]
	v_mfma_f32_16x16x32_bf16 v[22:25], v[156:159], v[188:191], v[22:25]
	v_mfma_f32_16x16x32_bf16 v[14:17], v[164:167], v[188:191], v[14:17]
	v_mfma_f32_16x16x32_bf16 v[6:9], v[156:159], v[196:199], v[6:9]
	v_mfma_f32_16x16x32_bf16 v[2:5], v[164:167], v[196:199], v[2:5]
	v_mfma_f32_16x16x32_bf16 v[54:57], v[160:163], v[176:179], v[54:57]
	v_mfma_f32_16x16x32_bf16 v[46:49], v[168:171], v[176:179], v[46:49]
	v_mfma_f32_16x16x32_bf16 v[38:41], v[160:163], v[184:187], v[38:41]
	v_mfma_f32_16x16x32_bf16 v[30:33], v[168:171], v[184:187], v[30:33]
	v_mfma_f32_16x16x32_bf16 v[22:25], v[160:163], v[192:195], v[22:25]
	v_mfma_f32_16x16x32_bf16 v[14:17], v[168:171], v[192:195], v[14:17]
	v_mfma_f32_16x16x32_bf16 v[6:9], v[160:163], v[200:203], v[6:9]
	v_mfma_f32_16x16x32_bf16 v[2:5], v[168:171], v[200:203], v[2:5]
	s_barrier
	s_setprio 1
	v_add_u32_e32 v152, s92, v141
	v_add_u32_e32 v168, s88, v141
	ds_read_b128 v[136:139], v152
	ds_read_b128 v[144:147], v152 offset:1024
	ds_read_b128 v[148:151], v152 offset:2048
	ds_read_b128 v[152:155], v152 offset:3072
	ds_read_b128 v[156:159], v168
	ds_read_b128 v[160:163], v168 offset:1024
	ds_read_b128 v[164:167], v168 offset:2048
	ds_read_b128 v[168:171], v168 offset:3072
	s_mov_b32 m0, s69
	ds_read_b128 v[172:175], v143 offset:32768
	ds_read_b128 v[176:179], v143 offset:33792
	ds_read_b128 v[180:183], v143 offset:34816
	ds_read_b128 v[184:187], v143 offset:35840
	ds_read_b128 v[188:191], v143 offset:36864
	ds_read_b128 v[192:195], v143 offset:37888
	ds_read_b128 v[196:199], v143 offset:38912
	ds_read_b128 v[200:203], v143 offset:39936
	global_load_lds_dwordx4 v130, s[52:53]
	v_lshl_add_u64 v[214:215], s[52:53], 0, v[132:133]
	s_mov_b32 m0, s70
	s_nop 0
	global_load_lds_dwordx4 v[214:215], off
	s_setprio 0
	s_waitcnt vmcnt(8)
	s_waitcnt lgkmcnt(0)
	s_barrier
	s_waitcnt lgkmcnt(0)
	v_mfma_f32_16x16x32_bf16 v[126:129], v[136:139], v[172:175], v[126:129]
	v_mfma_f32_16x16x32_bf16 v[122:125], v[148:151], v[172:175], v[122:125]
	v_mfma_f32_16x16x32_bf16 v[114:117], v[136:139], v[180:183], v[114:117]
	v_mfma_f32_16x16x32_bf16 v[106:109], v[148:151], v[180:183], v[106:109]
	v_mfma_f32_16x16x32_bf16 v[98:101], v[136:139], v[188:191], v[98:101]
	v_mfma_f32_16x16x32_bf16 v[90:93], v[148:151], v[188:191], v[90:93]
	v_mfma_f32_16x16x32_bf16 v[82:85], v[136:139], v[196:199], v[82:85]
	v_mfma_f32_16x16x32_bf16 v[74:77], v[148:151], v[196:199], v[74:77]
	v_mfma_f32_16x16x32_bf16 v[126:129], v[144:147], v[176:179], v[126:129]
	v_mfma_f32_16x16x32_bf16 v[122:125], v[152:155], v[176:179], v[122:125]
	v_mfma_f32_16x16x32_bf16 v[114:117], v[144:147], v[184:187], v[114:117]
	v_mfma_f32_16x16x32_bf16 v[106:109], v[152:155], v[184:187], v[106:109]
	v_mfma_f32_16x16x32_bf16 v[98:101], v[144:147], v[192:195], v[98:101]
	v_mfma_f32_16x16x32_bf16 v[90:93], v[152:155], v[192:195], v[90:93]
	v_mfma_f32_16x16x32_bf16 v[82:85], v[144:147], v[200:203], v[82:85]
	v_mfma_f32_16x16x32_bf16 v[74:77], v[152:155], v[200:203], v[74:77]
	v_mfma_f32_16x16x32_bf16 v[118:121], v[156:159], v[172:175], v[118:121]
	v_mfma_f32_16x16x32_bf16 v[110:113], v[164:167], v[172:175], v[110:113]
	v_mfma_f32_16x16x32_bf16 v[102:105], v[156:159], v[180:183], v[102:105]
	v_mfma_f32_16x16x32_bf16 v[94:97], v[164:167], v[180:183], v[94:97]
	v_mfma_f32_16x16x32_bf16 v[86:89], v[156:159], v[188:191], v[86:89]
	v_mfma_f32_16x16x32_bf16 v[78:81], v[164:167], v[188:191], v[78:81]
	v_mfma_f32_16x16x32_bf16 v[70:73], v[156:159], v[196:199], v[70:73]
	v_mfma_f32_16x16x32_bf16 v[66:69], v[164:167], v[196:199], v[66:69]
	v_mfma_f32_16x16x32_bf16 v[118:121], v[160:163], v[176:179], v[118:121]
	v_mfma_f32_16x16x32_bf16 v[110:113], v[168:171], v[176:179], v[110:113]
	v_mfma_f32_16x16x32_bf16 v[102:105], v[160:163], v[184:187], v[102:105]
	v_mfma_f32_16x16x32_bf16 v[94:97], v[168:171], v[184:187], v[94:97]
	v_mfma_f32_16x16x32_bf16 v[86:89], v[160:163], v[192:195], v[86:89]
	v_mfma_f32_16x16x32_bf16 v[78:81], v[168:171], v[192:195], v[78:81]
	v_mfma_f32_16x16x32_bf16 v[70:73], v[160:163], v[200:203], v[70:73]
	v_mfma_f32_16x16x32_bf16 v[66:69], v[168:171], v[200:203], v[66:69]
	s_barrier
	s_setprio 1
	s_mov_b32 m0, s45
	v_lshl_add_u64 v[204:205], v[204:205], 0, s[24:25]
	ds_read_b128 v[172:175], v143 offset:49152
	ds_read_b128 v[176:179], v143 offset:50176
	ds_read_b128 v[180:183], v143 offset:51200
	ds_read_b128 v[184:187], v143 offset:52224
	ds_read_b128 v[188:191], v143 offset:53248
	ds_read_b128 v[192:195], v143 offset:54272
	ds_read_b128 v[196:199], v143 offset:55296
	ds_read_b128 v[200:203], v143 offset:56320
	global_load_lds_dwordx4 v[204:205], off
	v_lshl_add_u64 v[204:205], v[206:207], 0, s[24:25]
	s_mov_b32 m0, s17
	s_nop 0
	global_load_lds_dwordx4 v[204:205], off
	s_mov_b32 m0, s20
	s_nop 0
	global_load_lds_dwordx4 v0, s[50:51]
	s_mov_b32 m0, s78
	s_nop 0
	global_load_lds_dwordx4 v134, s[50:51]
	v_lshl_add_u64 v[204:205], v[208:209], 0, s[24:25]
	s_mov_b32 m0, s71
	s_nop 0
	global_load_lds_dwordx4 v[204:205], off
	v_lshl_add_u64 v[204:205], v[210:211], 0, s[24:25]
	s_mov_b32 m0, s72
	s_nop 0
	global_load_lds_dwordx4 v[204:205], off
	s_setprio 0
	s_waitcnt vmcnt(8)
	s_waitcnt lgkmcnt(0)
	s_barrier
	s_waitcnt lgkmcnt(0)
	v_mfma_f32_16x16x32_bf16 v[62:65], v[136:139], v[172:175], v[62:65]
	v_mfma_f32_16x16x32_bf16 v[58:61], v[148:151], v[172:175], v[58:61]
	v_mfma_f32_16x16x32_bf16 v[50:53], v[136:139], v[180:183], v[50:53]
	v_mfma_f32_16x16x32_bf16 v[42:45], v[148:151], v[180:183], v[42:45]
	v_mfma_f32_16x16x32_bf16 v[34:37], v[136:139], v[188:191], v[34:37]
	v_mfma_f32_16x16x32_bf16 v[26:29], v[148:151], v[188:191], v[26:29]
	v_mfma_f32_16x16x32_bf16 v[18:21], v[136:139], v[196:199], v[18:21]
	v_mfma_f32_16x16x32_bf16 v[10:13], v[148:151], v[196:199], v[10:13]
	v_mfma_f32_16x16x32_bf16 v[62:65], v[144:147], v[176:179], v[62:65]
	v_mfma_f32_16x16x32_bf16 v[58:61], v[152:155], v[176:179], v[58:61]
	v_mfma_f32_16x16x32_bf16 v[50:53], v[144:147], v[184:187], v[50:53]
	v_mfma_f32_16x16x32_bf16 v[42:45], v[152:155], v[184:187], v[42:45]
	v_mfma_f32_16x16x32_bf16 v[34:37], v[144:147], v[192:195], v[34:37]
	v_mfma_f32_16x16x32_bf16 v[26:29], v[152:155], v[192:195], v[26:29]
	v_mfma_f32_16x16x32_bf16 v[18:21], v[144:147], v[200:203], v[18:21]
	v_mfma_f32_16x16x32_bf16 v[10:13], v[152:155], v[200:203], v[10:13]
	v_mfma_f32_16x16x32_bf16 v[54:57], v[156:159], v[172:175], v[54:57]
	v_mfma_f32_16x16x32_bf16 v[46:49], v[164:167], v[172:175], v[46:49]
	v_mfma_f32_16x16x32_bf16 v[38:41], v[156:159], v[180:183], v[38:41]
	v_mfma_f32_16x16x32_bf16 v[30:33], v[164:167], v[180:183], v[30:33]
	v_mfma_f32_16x16x32_bf16 v[22:25], v[156:159], v[188:191], v[22:25]
	v_mfma_f32_16x16x32_bf16 v[14:17], v[164:167], v[188:191], v[14:17]
	v_mfma_f32_16x16x32_bf16 v[6:9], v[156:159], v[196:199], v[6:9]
	v_mfma_f32_16x16x32_bf16 v[2:5], v[164:167], v[196:199], v[2:5]
	v_mfma_f32_16x16x32_bf16 v[54:57], v[160:163], v[176:179], v[54:57]
	v_mfma_f32_16x16x32_bf16 v[46:49], v[168:171], v[176:179], v[46:49]
	v_mfma_f32_16x16x32_bf16 v[38:41], v[160:163], v[184:187], v[38:41]
	v_mfma_f32_16x16x32_bf16 v[30:33], v[168:171], v[184:187], v[30:33]
	v_mfma_f32_16x16x32_bf16 v[22:25], v[160:163], v[192:195], v[22:25]
	v_mfma_f32_16x16x32_bf16 v[14:17], v[168:171], v[192:195], v[14:17]
	v_mfma_f32_16x16x32_bf16 v[6:9], v[160:163], v[200:203], v[6:9]
	v_mfma_f32_16x16x32_bf16 v[2:5], v[168:171], v[200:203], v[2:5]
	s_barrier
	s_setprio 1
	s_movk_i32 s17, 0x100
	s_andn2_b64 vcc, exec, s[4:5]
	s_mov_b64 s[50:51], -1
	s_mov_b64 s[4:5], 0
	s_cbranch_vccz .LBB0_1972
	s_and_b64 vcc, exec, s[12:13]
	s_cbranch_vccz .LBB0_1975
	s_barrier

.LBB0_2034:
	s_add_u32 s37, s46, s13
	s_addc_u32 s43, s47, 0
	s_add_u32 s50, s37, 0x100
	s_addc_u32 s51, s43, 0
	s_and_b64 s[20:21], s[48:49], exec
	s_cselect_b32 s53, s17, s51
	s_cselect_b32 s52, s16, s50
	s_add_u32 s13, s44, s13
	s_addc_u32 s20, s45, 0
	s_add_u32 s13, s13, 0x100
	s_addc_u32 s50, s20, 0
	s_add_i32 s78, 0, 0x10000
	s_and_b64 s[20:21], s[48:49], exec
	s_cselect_b32 s55, s19, s50
	s_cselect_b32 s54, s18, s13
	s_add_i32 s20, 0, 0x14000
	s_add_u32 s58, s37, 0x40080
	s_addc_u32 s59, s43, 0
	s_add_i32 s77, s78, s64
	s_add_i32 m0, s65, 0xc000
	s_add_i32 s21, s65, 0xe000
	s_add_i32 s37, s77, 0x2000
	s_add_u32 s56, s54, 0x80000
	v_add_u32_e32 v152, s78, v141
	v_add_u32_e32 v168, s20, v141
	s_addc_u32 s57, s55, 0
	s_add_i32 s83, s20, s64
	ds_read_b128 v[136:139], v152
	ds_read_b128 v[144:147], v152 offset:1024
	ds_read_b128 v[148:151], v152 offset:2048
	ds_read_b128 v[152:155], v152 offset:3072
	ds_read_b128 v[156:159], v168
	ds_read_b128 v[160:163], v168 offset:1024
	ds_read_b128 v[164:167], v168 offset:2048
	ds_read_b128 v[168:171], v168 offset:3072
	s_add_i32 s82, s83, 0x2000
	s_add_i32 s87, 0, 0x18000
	s_add_i32 s86, 0, 0x1c000
	s_add_u32 s50, s52, 0x40000
	s_addc_u32 s51, s53, 0
	s_add_i32 s43, s87, s64
	s_add_i32 s13, s43, 0x2000
	s_add_u32 s48, s54, 0x80080
	s_addc_u32 s49, s55, 0
	s_add_i32 s20, s86, s64
	s_add_i32 s78, s20, 0x2000
	ds_read_b128 v[172:175], v143
	ds_read_b128 v[176:179], v143 offset:1024
	ds_read_b128 v[180:183], v143 offset:2048
	ds_read_b128 v[184:187], v143 offset:3072
	ds_read_b128 v[188:191], v143 offset:4096
	ds_read_b128 v[192:195], v143 offset:5120
	ds_read_b128 v[196:199], v143 offset:6144
	ds_read_b128 v[200:203], v143 offset:7168
	global_load_lds_dwordx4 v130, s[58:59]
	s_mov_b32 m0, s21
	s_nop 0
	global_load_lds_dwordx4 v132, s[58:59]
	s_setprio 0
	s_waitcnt vmcnt(8)
	s_waitcnt lgkmcnt(0)
	s_barrier
	s_waitcnt lgkmcnt(0)
	v_mfma_f32_16x16x32_bf16 v[126:129], v[136:139], v[172:175], v[126:129]
	v_mfma_f32_16x16x32_bf16 v[122:125], v[148:151], v[172:175], v[122:125]
	v_mfma_f32_16x16x32_bf16 v[114:117], v[136:139], v[180:183], v[114:117]
	v_mfma_f32_16x16x32_bf16 v[106:109], v[148:151], v[180:183], v[106:109]
	v_mfma_f32_16x16x32_bf16 v[98:101], v[136:139], v[188:191], v[98:101]
	v_mfma_f32_16x16x32_bf16 v[90:93], v[148:151], v[188:191], v[90:93]
	v_mfma_f32_16x16x32_bf16 v[82:85], v[136:139], v[196:199], v[82:85]
	v_mfma_f32_16x16x32_bf16 v[74:77], v[148:151], v[196:199], v[74:77]
	v_mfma_f32_16x16x32_bf16 v[126:129], v[144:147], v[176:179], v[126:129]
	v_mfma_f32_16x16x32_bf16 v[122:125], v[152:155], v[176:179], v[122:125]
	v_mfma_f32_16x16x32_bf16 v[114:117], v[144:147], v[184:187], v[114:117]
	v_mfma_f32_16x16x32_bf16 v[106:109], v[152:155], v[184:187], v[106:109]
	v_mfma_f32_16x16x32_bf16 v[98:101], v[144:147], v[192:195], v[98:101]
	v_mfma_f32_16x16x32_bf16 v[90:93], v[152:155], v[192:195], v[90:93]
	v_mfma_f32_16x16x32_bf16 v[82:85], v[144:147], v[200:203], v[82:85]
	v_mfma_f32_16x16x32_bf16 v[74:77], v[152:155], v[200:203], v[74:77]
	v_mfma_f32_16x16x32_bf16 v[118:121], v[156:159], v[172:175], v[118:121]
	v_mfma_f32_16x16x32_bf16 v[110:113], v[164:167], v[172:175], v[110:113]
	v_mfma_f32_16x16x32_bf16 v[102:105], v[156:159], v[180:183], v[102:105]
	v_mfma_f32_16x16x32_bf16 v[94:97], v[164:167], v[180:183], v[94:97]
	v_mfma_f32_16x16x32_bf16 v[86:89], v[156:159], v[188:191], v[86:89]
	v_mfma_f32_16x16x32_bf16 v[78:81], v[164:167], v[188:191], v[78:81]
	v_mfma_f32_16x16x32_bf16 v[70:73], v[156:159], v[196:199], v[70:73]
	v_mfma_f32_16x16x32_bf16 v[66:69], v[164:167], v[196:199], v[66:69]
	v_mfma_f32_16x16x32_bf16 v[118:121], v[160:163], v[176:179], v[118:121]
	v_mfma_f32_16x16x32_bf16 v[110:113], v[168:171], v[176:179], v[110:113]
	v_mfma_f32_16x16x32_bf16 v[102:105], v[160:163], v[184:187], v[102:105]
	v_mfma_f32_16x16x32_bf16 v[94:97], v[168:171], v[184:187], v[94:97]
	v_mfma_f32_16x16x32_bf16 v[86:89], v[160:163], v[192:195], v[86:89]
	v_mfma_f32_16x16x32_bf16 v[78:81], v[168:171], v[192:195], v[78:81]
	v_mfma_f32_16x16x32_bf16 v[70:73], v[160:163], v[200:203], v[70:73]
	v_mfma_f32_16x16x32_bf16 v[66:69], v[168:171], v[200:203], v[66:69]
	s_barrier
	s_setprio 1
	s_mov_b32 m0, s77
	v_lshl_add_u64 v[204:205], s[54:55], 0, v[0:1]
	ds_read_b128 v[172:175], v143 offset:16384
	ds_read_b128 v[176:179], v143 offset:17408
	ds_read_b128 v[180:183], v143 offset:18432
	ds_read_b128 v[184:187], v143 offset:19456
	ds_read_b128 v[188:191], v143 offset:20480
	ds_read_b128 v[192:195], v143 offset:21504
	ds_read_b128 v[196:199], v143 offset:22528
	ds_read_b128 v[200:203], v143 offset:23552
	global_load_lds_dwordx4 v[204:205], off
	v_lshl_add_u64 v[206:207], s[54:55], 0, v[134:135]
	s_mov_b32 m0, s37
	global_load_lds_dwordx4 v[206:207], off
	s_mov_b32 m0, s83
	v_lshl_add_u64 v[210:211], s[52:53], 0, v[132:133]
	global_load_lds_dwordx4 v0, s[56:57]
	s_mov_b32 m0, s82
	s_nop 0
	global_load_lds_dwordx4 v134, s[56:57]
	v_lshl_add_u64 v[208:209], s[52:53], 0, v[130:131]
	s_mov_b32 m0, s65
	s_nop 0
	global_load_lds_dwordx4 v[208:209], off
	s_mov_b32 m0, s66
	s_nop 0
	global_load_lds_dwordx4 v[210:211], off
	s_setprio 0
	s_waitcnt vmcnt(8)
	s_waitcnt lgkmcnt(0)
	s_barrier
	s_waitcnt lgkmcnt(0)
	v_mfma_f32_16x16x32_bf16 v[62:65], v[136:139], v[172:175], v[62:65]
	v_mfma_f32_16x16x32_bf16 v[58:61], v[148:151], v[172:175], v[58:61]
	v_mfma_f32_16x16x32_bf16 v[50:53], v[136:139], v[180:183], v[50:53]
	v_mfma_f32_16x16x32_bf16 v[42:45], v[148:151], v[180:183], v[42:45]
	v_mfma_f32_16x16x32_bf16 v[34:37], v[136:139], v[188:191], v[34:37]
	v_mfma_f32_16x16x32_bf16 v[26:29], v[148:151], v[188:191], v[26:29]
	v_mfma_f32_16x16x32_bf16 v[18:21], v[136:139], v[196:199], v[18:21]
	v_mfma_f32_16x16x32_bf16 v[10:13], v[148:151], v[196:199], v[10:13]
	v_mfma_f32_16x16x32_bf16 v[62:65], v[144:147], v[176:179], v[62:65]
	v_mfma_f32_16x16x32_bf16 v[58:61], v[152:155], v[176:179], v[58:61]
	v_mfma_f32_16x16x32_bf16 v[50:53], v[144:147], v[184:187], v[50:53]
	v_mfma_f32_16x16x32_bf16 v[42:45], v[152:155], v[184:187], v[42:45]
	v_mfma_f32_16x16x32_bf16 v[34:37], v[144:147], v[192:195], v[34:37]
	v_mfma_f32_16x16x32_bf16 v[26:29], v[152:155], v[192:195], v[26:29]
	v_mfma_f32_16x16x32_bf16 v[18:21], v[144:147], v[200:203], v[18:21]
	v_mfma_f32_16x16x32_bf16 v[10:13], v[152:155], v[200:203], v[10:13]
	v_mfma_f32_16x16x32_bf16 v[54:57], v[156:159], v[172:175], v[54:57]
	v_mfma_f32_16x16x32_bf16 v[46:49], v[164:167], v[172:175], v[46:49]
	v_mfma_f32_16x16x32_bf16 v[38:41], v[156:159], v[180:183], v[38:41]
	v_mfma_f32_16x16x32_bf16 v[30:33], v[164:167], v[180:183], v[30:33]
	v_mfma_f32_16x16x32_bf16 v[22:25], v[156:159], v[188:191], v[22:25]
	v_mfma_f32_16x16x32_bf16 v[14:17], v[164:167], v[188:191], v[14:17]
	v_mfma_f32_16x16x32_bf16 v[6:9], v[156:159], v[196:199], v[6:9]
	v_mfma_f32_16x16x32_bf16 v[2:5], v[164:167], v[196:199], v[2:5]
	v_mfma_f32_16x16x32_bf16 v[54:57], v[160:163], v[176:179], v[54:57]
	v_mfma_f32_16x16x32_bf16 v[46:49], v[168:171], v[176:179], v[46:49]
	v_mfma_f32_16x16x32_bf16 v[38:41], v[160:163], v[184:187], v[38:41]
	v_mfma_f32_16x16x32_bf16 v[30:33], v[168:171], v[184:187], v[30:33]
	v_mfma_f32_16x16x32_bf16 v[22:25], v[160:163], v[192:195], v[22:25]
	v_mfma_f32_16x16x32_bf16 v[14:17], v[168:171], v[192:195], v[14:17]
	v_mfma_f32_16x16x32_bf16 v[6:9], v[160:163], v[200:203], v[6:9]
	v_mfma_f32_16x16x32_bf16 v[2:5], v[168:171], v[200:203], v[2:5]
	s_barrier
	s_setprio 1
	v_add_u32_e32 v152, s87, v141
	v_add_u32_e32 v168, s86, v141
	ds_read_b128 v[136:139], v152
	ds_read_b128 v[144:147], v152 offset:1024
	ds_read_b128 v[148:151], v152 offset:2048
	ds_read_b128 v[152:155], v152 offset:3072
	ds_read_b128 v[156:159], v168
	ds_read_b128 v[160:163], v168 offset:1024
	ds_read_b128 v[164:167], v168 offset:2048
	ds_read_b128 v[168:171], v168 offset:3072
	s_mov_b32 m0, s67
	ds_read_b128 v[172:175], v143 offset:32768
	ds_read_b128 v[176:179], v143 offset:33792
	ds_read_b128 v[180:183], v143 offset:34816
	ds_read_b128 v[184:187], v143 offset:35840
	ds_read_b128 v[188:191], v143 offset:36864
	ds_read_b128 v[192:195], v143 offset:37888
	ds_read_b128 v[196:199], v143 offset:38912
	ds_read_b128 v[200:203], v143 offset:39936
	global_load_lds_dwordx4 v130, s[50:51]
	v_lshl_add_u64 v[214:215], s[50:51], 0, v[132:133]
	s_mov_b32 m0, s68
	s_nop 0
	global_load_lds_dwordx4 v[214:215], off
	s_setprio 0
	s_waitcnt vmcnt(8)
	s_waitcnt lgkmcnt(0)
	s_barrier
	s_waitcnt lgkmcnt(0)
	v_mfma_f32_16x16x32_bf16 v[126:129], v[136:139], v[172:175], v[126:129]
	v_mfma_f32_16x16x32_bf16 v[122:125], v[148:151], v[172:175], v[122:125]
	v_mfma_f32_16x16x32_bf16 v[114:117], v[136:139], v[180:183], v[114:117]
	v_mfma_f32_16x16x32_bf16 v[106:109], v[148:151], v[180:183], v[106:109]
	v_mfma_f32_16x16x32_bf16 v[98:101], v[136:139], v[188:191], v[98:101]
	v_mfma_f32_16x16x32_bf16 v[90:93], v[148:151], v[188:191], v[90:93]
	v_mfma_f32_16x16x32_bf16 v[82:85], v[136:139], v[196:199], v[82:85]
	v_mfma_f32_16x16x32_bf16 v[74:77], v[148:151], v[196:199], v[74:77]
	v_mfma_f32_16x16x32_bf16 v[126:129], v[144:147], v[176:179], v[126:129]
	v_mfma_f32_16x16x32_bf16 v[122:125], v[152:155], v[176:179], v[122:125]
	v_mfma_f32_16x16x32_bf16 v[114:117], v[144:147], v[184:187], v[114:117]
	v_mfma_f32_16x16x32_bf16 v[106:109], v[152:155], v[184:187], v[106:109]
	v_mfma_f32_16x16x32_bf16 v[98:101], v[144:147], v[192:195], v[98:101]
	v_mfma_f32_16x16x32_bf16 v[90:93], v[152:155], v[192:195], v[90:93]
	v_mfma_f32_16x16x32_bf16 v[82:85], v[144:147], v[200:203], v[82:85]
	v_mfma_f32_16x16x32_bf16 v[74:77], v[152:155], v[200:203], v[74:77]
	v_mfma_f32_16x16x32_bf16 v[118:121], v[156:159], v[172:175], v[118:121]
	v_mfma_f32_16x16x32_bf16 v[110:113], v[164:167], v[172:175], v[110:113]
	v_mfma_f32_16x16x32_bf16 v[102:105], v[156:159], v[180:183], v[102:105]
	v_mfma_f32_16x16x32_bf16 v[94:97], v[164:167], v[180:183], v[94:97]
	v_mfma_f32_16x16x32_bf16 v[86:89], v[156:159], v[188:191], v[86:89]
	v_mfma_f32_16x16x32_bf16 v[78:81], v[164:167], v[188:191], v[78:81]
	v_mfma_f32_16x16x32_bf16 v[70:73], v[156:159], v[196:199], v[70:73]
	v_mfma_f32_16x16x32_bf16 v[66:69], v[164:167], v[196:199], v[66:69]
	v_mfma_f32_16x16x32_bf16 v[118:121], v[160:163], v[176:179], v[118:121]
	v_mfma_f32_16x16x32_bf16 v[110:113], v[168:171], v[176:179], v[110:113]
	v_mfma_f32_16x16x32_bf16 v[102:105], v[160:163], v[184:187], v[102:105]
	v_mfma_f32_16x16x32_bf16 v[94:97], v[168:171], v[184:187], v[94:97]
	v_mfma_f32_16x16x32_bf16 v[86:89], v[160:163], v[192:195], v[86:89]
	v_mfma_f32_16x16x32_bf16 v[78:81], v[168:171], v[192:195], v[78:81]
	v_mfma_f32_16x16x32_bf16 v[70:73], v[160:163], v[200:203], v[70:73]
	v_mfma_f32_16x16x32_bf16 v[66:69], v[168:171], v[200:203], v[66:69]
	s_barrier
	s_setprio 1
	s_mov_b32 m0, s43
	v_lshl_add_u64 v[204:205], v[204:205], 0, s[24:25]
	ds_read_b128 v[172:175], v143 offset:49152
	ds_read_b128 v[176:179], v143 offset:50176
	ds_read_b128 v[180:183], v143 offset:51200
	ds_read_b128 v[184:187], v143 offset:52224
	ds_read_b128 v[188:191], v143 offset:53248
	ds_read_b128 v[192:195], v143 offset:54272
	ds_read_b128 v[196:199], v143 offset:55296
	ds_read_b128 v[200:203], v143 offset:56320
	global_load_lds_dwordx4 v[204:205], off
	v_lshl_add_u64 v[204:205], v[206:207], 0, s[24:25]
	s_mov_b32 m0, s13
	s_nop 0
	global_load_lds_dwordx4 v[204:205], off
	s_mov_b32 m0, s20
	s_nop 0
	global_load_lds_dwordx4 v0, s[48:49]
	s_mov_b32 m0, s78
	s_nop 0
	global_load_lds_dwordx4 v134, s[48:49]
	v_lshl_add_u64 v[204:205], v[208:209], 0, s[24:25]
	s_mov_b32 m0, s69
	s_nop 0
	global_load_lds_dwordx4 v[204:205], off
	v_lshl_add_u64 v[204:205], v[210:211], 0, s[24:25]
	s_mov_b32 m0, s70
	s_nop 0
	global_load_lds_dwordx4 v[204:205], off
	s_setprio 0
	s_waitcnt vmcnt(8)
	s_waitcnt lgkmcnt(0)
	s_barrier
	s_waitcnt lgkmcnt(0)
	v_mfma_f32_16x16x32_bf16 v[62:65], v[136:139], v[172:175], v[62:65]
	v_mfma_f32_16x16x32_bf16 v[58:61], v[148:151], v[172:175], v[58:61]
	v_mfma_f32_16x16x32_bf16 v[50:53], v[136:139], v[180:183], v[50:53]
	v_mfma_f32_16x16x32_bf16 v[42:45], v[148:151], v[180:183], v[42:45]
	v_mfma_f32_16x16x32_bf16 v[34:37], v[136:139], v[188:191], v[34:37]
	v_mfma_f32_16x16x32_bf16 v[26:29], v[148:151], v[188:191], v[26:29]
	v_mfma_f32_16x16x32_bf16 v[18:21], v[136:139], v[196:199], v[18:21]
	v_mfma_f32_16x16x32_bf16 v[10:13], v[148:151], v[196:199], v[10:13]
	v_mfma_f32_16x16x32_bf16 v[62:65], v[144:147], v[176:179], v[62:65]
	v_mfma_f32_16x16x32_bf16 v[58:61], v[152:155], v[176:179], v[58:61]
	v_mfma_f32_16x16x32_bf16 v[50:53], v[144:147], v[184:187], v[50:53]
	v_mfma_f32_16x16x32_bf16 v[42:45], v[152:155], v[184:187], v[42:45]
	v_mfma_f32_16x16x32_bf16 v[34:37], v[144:147], v[192:195], v[34:37]
	v_mfma_f32_16x16x32_bf16 v[26:29], v[152:155], v[192:195], v[26:29]
	v_mfma_f32_16x16x32_bf16 v[18:21], v[144:147], v[200:203], v[18:21]
	v_mfma_f32_16x16x32_bf16 v[10:13], v[152:155], v[200:203], v[10:13]
	v_mfma_f32_16x16x32_bf16 v[54:57], v[156:159], v[172:175], v[54:57]
	v_mfma_f32_16x16x32_bf16 v[46:49], v[164:167], v[172:175], v[46:49]
	v_mfma_f32_16x16x32_bf16 v[38:41], v[156:159], v[180:183], v[38:41]
	v_mfma_f32_16x16x32_bf16 v[30:33], v[164:167], v[180:183], v[30:33]
	v_mfma_f32_16x16x32_bf16 v[22:25], v[156:159], v[188:191], v[22:25]
	v_mfma_f32_16x16x32_bf16 v[14:17], v[164:167], v[188:191], v[14:17]
	v_mfma_f32_16x16x32_bf16 v[6:9], v[156:159], v[196:199], v[6:9]
	v_mfma_f32_16x16x32_bf16 v[2:5], v[164:167], v[196:199], v[2:5]
	v_mfma_f32_16x16x32_bf16 v[54:57], v[160:163], v[176:179], v[54:57]
	v_mfma_f32_16x16x32_bf16 v[46:49], v[168:171], v[176:179], v[46:49]
	v_mfma_f32_16x16x32_bf16 v[38:41], v[160:163], v[184:187], v[38:41]
	v_mfma_f32_16x16x32_bf16 v[30:33], v[168:171], v[184:187], v[30:33]
	v_mfma_f32_16x16x32_bf16 v[22:25], v[160:163], v[192:195], v[22:25]
	v_mfma_f32_16x16x32_bf16 v[14:17], v[168:171], v[192:195], v[14:17]
	v_mfma_f32_16x16x32_bf16 v[6:9], v[160:163], v[200:203], v[6:9]
	v_mfma_f32_16x16x32_bf16 v[2:5], v[168:171], v[200:203], v[2:5]
	s_barrier
	s_setprio 1
	s_movk_i32 s13, 0x100
	s_andn2_b64 vcc, exec, s[4:5]
	s_mov_b64 s[48:49], -1
	s_mov_b64 s[4:5], 0
	s_cbranch_vccz .LBB0_2034
	s_and_b64 vcc, exec, s[10:11]
	s_cbranch_vccz .LBB0_2037
	s_barrier

.LBB0_2148:
	s_add_u32 s6, s4, 0xfffc0080
	s_addc_u32 s7, s5, -1
	s_add_i32 s20, 0, 0x10000
	s_cmp_eq_u32 s72, 12
	s_cselect_b32 s51, s43, s7
	s_cselect_b32 s50, s42, s6
	s_cselect_b32 s7, s45, s47
	s_cselect_b32 s6, s44, s19
	s_add_i32 s37, 0, 0x14000
	v_add_u32_e32 v152, s20, v174
	v_add_u32_e32 v168, s37, v174
	ds_read_b128 v[140:143], v152
	ds_read_b128 v[144:147], v152 offset:1024
	ds_read_b128 v[148:151], v152 offset:2048
	ds_read_b128 v[152:155], v152 offset:3072
	ds_read_b128 v[156:159], v168
	ds_read_b128 v[160:163], v168 offset:1024
	ds_read_b128 v[164:167], v168 offset:2048
	ds_read_b128 v[168:171], v168 offset:3072
	s_add_i32 m0, s49, 0xc000
	ds_read_b128 v[176:179], v175
	ds_read_b128 v[180:183], v175 offset:1024
	ds_read_b128 v[184:187], v175 offset:2048
	ds_read_b128 v[188:191], v175 offset:3072
	ds_read_b128 v[192:195], v175 offset:4096
	ds_read_b128 v[196:199], v175 offset:5120
	ds_read_b128 v[200:203], v175 offset:6144
	ds_read_b128 v[204:207], v175 offset:7168
	global_load_lds_dwordx4 v136, s[4:5]
	s_add_i32 m0, s49, 0xe000
	s_nop 0
	global_load_lds_dwordx4 v138, s[4:5]
	s_setprio 0
	s_waitcnt vmcnt(8)
	s_waitcnt lgkmcnt(0)
	s_barrier
	s_waitcnt lgkmcnt(0)
	v_mfma_f32_16x16x32_bf16 v[126:129], v[140:143], v[176:179], v[126:129]
	v_mfma_f32_16x16x32_bf16 v[122:125], v[148:151], v[176:179], v[122:125]
	v_mfma_f32_16x16x32_bf16 v[110:113], v[140:143], v[184:187], v[110:113]
	v_mfma_f32_16x16x32_bf16 v[106:109], v[148:151], v[184:187], v[106:109]
	v_mfma_f32_16x16x32_bf16 v[94:97], v[140:143], v[192:195], v[94:97]
	v_mfma_f32_16x16x32_bf16 v[90:93], v[148:151], v[192:195], v[90:93]
	v_mfma_f32_16x16x32_bf16 v[78:81], v[140:143], v[200:203], v[78:81]
	v_mfma_f32_16x16x32_bf16 v[74:77], v[148:151], v[200:203], v[74:77]
	v_mfma_f32_16x16x32_bf16 v[126:129], v[144:147], v[180:183], v[126:129]
	v_mfma_f32_16x16x32_bf16 v[122:125], v[152:155], v[180:183], v[122:125]
	v_mfma_f32_16x16x32_bf16 v[110:113], v[144:147], v[188:191], v[110:113]
	v_mfma_f32_16x16x32_bf16 v[106:109], v[152:155], v[188:191], v[106:109]
	v_mfma_f32_16x16x32_bf16 v[94:97], v[144:147], v[196:199], v[94:97]
	v_mfma_f32_16x16x32_bf16 v[90:93], v[152:155], v[196:199], v[90:93]
	v_mfma_f32_16x16x32_bf16 v[78:81], v[144:147], v[204:207], v[78:81]
	v_mfma_f32_16x16x32_bf16 v[74:77], v[152:155], v[204:207], v[74:77]
	v_mfma_f32_16x16x32_bf16 v[118:121], v[156:159], v[176:179], v[118:121]
	v_mfma_f32_16x16x32_bf16 v[114:117], v[164:167], v[176:179], v[114:117]
	v_mfma_f32_16x16x32_bf16 v[102:105], v[156:159], v[184:187], v[102:105]
	v_mfma_f32_16x16x32_bf16 v[98:101], v[164:167], v[184:187], v[98:101]
	v_mfma_f32_16x16x32_bf16 v[86:89], v[156:159], v[192:195], v[86:89]
	v_mfma_f32_16x16x32_bf16 v[82:85], v[164:167], v[192:195], v[82:85]
	v_mfma_f32_16x16x32_bf16 v[70:73], v[156:159], v[200:203], v[70:73]
	v_mfma_f32_16x16x32_bf16 v[66:69], v[164:167], v[200:203], v[66:69]
	v_mfma_f32_16x16x32_bf16 v[118:121], v[160:163], v[180:183], v[118:121]
	v_mfma_f32_16x16x32_bf16 v[114:117], v[168:171], v[180:183], v[114:117]
	v_mfma_f32_16x16x32_bf16 v[102:105], v[160:163], v[188:191], v[102:105]
	v_mfma_f32_16x16x32_bf16 v[98:101], v[168:171], v[188:191], v[98:101]
	v_mfma_f32_16x16x32_bf16 v[86:89], v[160:163], v[196:199], v[86:89]
	v_mfma_f32_16x16x32_bf16 v[82:85], v[168:171], v[196:199], v[82:85]
	v_mfma_f32_16x16x32_bf16 v[70:73], v[160:163], v[204:207], v[70:73]
	v_mfma_f32_16x16x32_bf16 v[66:69], v[168:171], v[204:207], v[66:69]
	s_barrier
	s_setprio 1
	s_add_i32 s20, s20, s54
	v_lshl_add_u64 v[208:209], s[6:7], 0, v[0:1]
	s_mov_b32 m0, s20
	ds_read_b128 v[176:179], v175 offset:16384
	ds_read_b128 v[180:183], v175 offset:17408
	ds_read_b128 v[184:187], v175 offset:18432
	ds_read_b128 v[188:191], v175 offset:19456
	ds_read_b128 v[192:195], v175 offset:20480
	ds_read_b128 v[196:199], v175 offset:21504
	ds_read_b128 v[200:203], v175 offset:22528
	ds_read_b128 v[204:207], v175 offset:23552
	global_load_lds_dwordx4 v[208:209], off
	s_add_i32 m0, s20, 0x2000
	s_add_u32 s20, s6, 0x40000
	v_lshl_add_u64 v[210:211], s[6:7], 0, v[134:135]
	s_addc_u32 s21, s7, 0
	s_add_i32 s37, s37, s54
	global_load_lds_dwordx4 v[210:211], off
	s_mov_b32 m0, s37
	v_lshl_add_u64 v[216:217], s[50:51], 0, v[132:133]
	global_load_lds_dwordx4 v0, s[20:21]
	s_add_i32 m0, s37, 0x2000
	s_nop 0
	global_load_lds_dwordx4 v134, s[20:21]
	v_lshl_add_u64 v[214:215], s[50:51], 0, v[130:131]
	s_mov_b32 m0, s49
	s_nop 0
	global_load_lds_dwordx4 v[214:215], off
	s_mov_b32 m0, s55
	s_nop 0
	global_load_lds_dwordx4 v[216:217], off
	s_setprio 0
	s_waitcnt vmcnt(8)
	s_waitcnt lgkmcnt(0)
	s_barrier
	s_waitcnt lgkmcnt(0)
	v_mfma_f32_16x16x32_bf16 v[62:65], v[140:143], v[176:179], v[62:65]
	v_mfma_f32_16x16x32_bf16 v[58:61], v[148:151], v[176:179], v[58:61]
	v_mfma_f32_16x16x32_bf16 v[46:49], v[140:143], v[184:187], v[46:49]
	v_mfma_f32_16x16x32_bf16 v[42:45], v[148:151], v[184:187], v[42:45]
	v_mfma_f32_16x16x32_bf16 v[30:33], v[140:143], v[192:195], v[30:33]
	v_mfma_f32_16x16x32_bf16 v[26:29], v[148:151], v[192:195], v[26:29]
	v_mfma_f32_16x16x32_bf16 v[14:17], v[140:143], v[200:203], v[14:17]
	v_mfma_f32_16x16x32_bf16 v[10:13], v[148:151], v[200:203], v[10:13]
	v_mfma_f32_16x16x32_bf16 v[62:65], v[144:147], v[180:183], v[62:65]
	v_mfma_f32_16x16x32_bf16 v[58:61], v[152:155], v[180:183], v[58:61]
	v_mfma_f32_16x16x32_bf16 v[46:49], v[144:147], v[188:191], v[46:49]
	v_mfma_f32_16x16x32_bf16 v[42:45], v[152:155], v[188:191], v[42:45]
	v_mfma_f32_16x16x32_bf16 v[30:33], v[144:147], v[196:199], v[30:33]
	v_mfma_f32_16x16x32_bf16 v[26:29], v[152:155], v[196:199], v[26:29]
	v_mfma_f32_16x16x32_bf16 v[14:17], v[144:147], v[204:207], v[14:17]
	v_mfma_f32_16x16x32_bf16 v[10:13], v[152:155], v[204:207], v[10:13]
	v_mfma_f32_16x16x32_bf16 v[54:57], v[156:159], v[176:179], v[54:57]
	v_mfma_f32_16x16x32_bf16 v[50:53], v[164:167], v[176:179], v[50:53]
	v_mfma_f32_16x16x32_bf16 v[38:41], v[156:159], v[184:187], v[38:41]
	v_mfma_f32_16x16x32_bf16 v[34:37], v[164:167], v[184:187], v[34:37]
	v_mfma_f32_16x16x32_bf16 v[22:25], v[156:159], v[192:195], v[22:25]
	v_mfma_f32_16x16x32_bf16 v[18:21], v[164:167], v[192:195], v[18:21]
	v_mfma_f32_16x16x32_bf16 v[6:9], v[156:159], v[200:203], v[6:9]
	v_mfma_f32_16x16x32_bf16 v[2:5], v[164:167], v[200:203], v[2:5]
	v_mfma_f32_16x16x32_bf16 v[54:57], v[160:163], v[180:183], v[54:57]
	v_mfma_f32_16x16x32_bf16 v[50:53], v[168:171], v[180:183], v[50:53]
	v_mfma_f32_16x16x32_bf16 v[38:41], v[160:163], v[188:191], v[38:41]
	v_mfma_f32_16x16x32_bf16 v[34:37], v[168:171], v[188:191], v[34:37]
	v_mfma_f32_16x16x32_bf16 v[22:25], v[160:163], v[196:199], v[22:25]
	v_mfma_f32_16x16x32_bf16 v[18:21], v[168:171], v[196:199], v[18:21]
	v_mfma_f32_16x16x32_bf16 v[6:9], v[160:163], v[204:207], v[6:9]
	v_mfma_f32_16x16x32_bf16 v[2:5], v[168:171], v[204:207], v[2:5]
	s_barrier
	s_setprio 1
	s_add_i32 s37, 0, 0x18000
	s_add_i32 s73, 0, 0x1c000
	v_add_u32_e32 v152, s37, v174
	v_add_u32_e32 v168, s73, v174
	ds_read_b128 v[140:143], v152
	ds_read_b128 v[144:147], v152 offset:1024
	ds_read_b128 v[148:151], v152 offset:2048
	ds_read_b128 v[152:155], v152 offset:3072
	ds_read_b128 v[156:159], v168
	ds_read_b128 v[160:163], v168 offset:1024
	ds_read_b128 v[164:167], v168 offset:2048
	ds_read_b128 v[168:171], v168 offset:3072
	s_add_u32 s20, s50, 0x40000
	s_addc_u32 s21, s51, 0
	s_mov_b32 m0, s56
	ds_read_b128 v[176:179], v175 offset:32768
	ds_read_b128 v[180:183], v175 offset:33792
	ds_read_b128 v[184:187], v175 offset:34816
	ds_read_b128 v[188:191], v175 offset:35840
	ds_read_b128 v[192:195], v175 offset:36864
	ds_read_b128 v[196:199], v175 offset:37888
	ds_read_b128 v[200:203], v175 offset:38912
	ds_read_b128 v[204:207], v175 offset:39936
	global_load_lds_dwordx4 v130, s[20:21]
	v_lshl_add_u64 v[218:219], s[20:21], 0, v[132:133]
	s_mov_b32 m0, s57
	s_nop 0
	global_load_lds_dwordx4 v[218:219], off
	s_setprio 0
	s_waitcnt vmcnt(8)
	s_waitcnt lgkmcnt(0)
	s_barrier
	s_waitcnt lgkmcnt(0)
	v_mfma_f32_16x16x32_bf16 v[126:129], v[140:143], v[176:179], v[126:129]
	v_mfma_f32_16x16x32_bf16 v[122:125], v[148:151], v[176:179], v[122:125]
	v_mfma_f32_16x16x32_bf16 v[110:113], v[140:143], v[184:187], v[110:113]
	v_mfma_f32_16x16x32_bf16 v[106:109], v[148:151], v[184:187], v[106:109]
	v_mfma_f32_16x16x32_bf16 v[94:97], v[140:143], v[192:195], v[94:97]
	v_mfma_f32_16x16x32_bf16 v[90:93], v[148:151], v[192:195], v[90:93]
	v_mfma_f32_16x16x32_bf16 v[78:81], v[140:143], v[200:203], v[78:81]
	v_mfma_f32_16x16x32_bf16 v[74:77], v[148:151], v[200:203], v[74:77]
	v_mfma_f32_16x16x32_bf16 v[126:129], v[144:147], v[180:183], v[126:129]
	v_mfma_f32_16x16x32_bf16 v[122:125], v[152:155], v[180:183], v[122:125]
	v_mfma_f32_16x16x32_bf16 v[110:113], v[144:147], v[188:191], v[110:113]
	v_mfma_f32_16x16x32_bf16 v[106:109], v[152:155], v[188:191], v[106:109]
	v_mfma_f32_16x16x32_bf16 v[94:97], v[144:147], v[196:199], v[94:97]
	v_mfma_f32_16x16x32_bf16 v[90:93], v[152:155], v[196:199], v[90:93]
	v_mfma_f32_16x16x32_bf16 v[78:81], v[144:147], v[204:207], v[78:81]
	v_mfma_f32_16x16x32_bf16 v[74:77], v[152:155], v[204:207], v[74:77]
	v_mfma_f32_16x16x32_bf16 v[118:121], v[156:159], v[176:179], v[118:121]
	v_mfma_f32_16x16x32_bf16 v[114:117], v[164:167], v[176:179], v[114:117]
	v_mfma_f32_16x16x32_bf16 v[102:105], v[156:159], v[184:187], v[102:105]
	v_mfma_f32_16x16x32_bf16 v[98:101], v[164:167], v[184:187], v[98:101]
	v_mfma_f32_16x16x32_bf16 v[86:89], v[156:159], v[192:195], v[86:89]
	v_mfma_f32_16x16x32_bf16 v[82:85], v[164:167], v[192:195], v[82:85]
	v_mfma_f32_16x16x32_bf16 v[70:73], v[156:159], v[200:203], v[70:73]
	v_mfma_f32_16x16x32_bf16 v[66:69], v[164:167], v[200:203], v[66:69]
	v_mfma_f32_16x16x32_bf16 v[118:121], v[160:163], v[180:183], v[118:121]
	v_mfma_f32_16x16x32_bf16 v[114:117], v[168:171], v[180:183], v[114:117]
	v_mfma_f32_16x16x32_bf16 v[102:105], v[160:163], v[188:191], v[102:105]
	v_mfma_f32_16x16x32_bf16 v[98:101], v[168:171], v[188:191], v[98:101]
	v_mfma_f32_16x16x32_bf16 v[86:89], v[160:163], v[196:199], v[86:89]
	v_mfma_f32_16x16x32_bf16 v[82:85], v[168:171], v[196:199], v[82:85]
	v_mfma_f32_16x16x32_bf16 v[70:73], v[160:163], v[204:207], v[70:73]
	v_mfma_f32_16x16x32_bf16 v[66:69], v[168:171], v[204:207], v[66:69]
	s_barrier
	s_setprio 1
	s_add_i32 s20, s37, s54
	v_lshl_add_u64 v[208:209], v[208:209], 0, s[24:25]
	s_mov_b32 m0, s20
	ds_read_b128 v[176:179], v175 offset:49152
	ds_read_b128 v[180:183], v175 offset:50176
	ds_read_b128 v[184:187], v175 offset:51200
	ds_read_b128 v[188:191], v175 offset:52224
	ds_read_b128 v[192:195], v175 offset:53248
	ds_read_b128 v[196:199], v175 offset:54272
	ds_read_b128 v[200:203], v175 offset:55296
	ds_read_b128 v[204:207], v175 offset:56320
	global_load_lds_dwordx4 v[208:209], off
	s_add_i32 m0, s20, 0x2000
	s_add_u32 s6, s6, 0x40080
	v_lshl_add_u64 v[208:209], v[210:211], 0, s[24:25]
	s_addc_u32 s7, s7, 0
	s_add_i32 s20, s73, s54
	global_load_lds_dwordx4 v[208:209], off
	s_mov_b32 m0, s20
	s_nop 0
	global_load_lds_dwordx4 v0, s[6:7]
	s_add_i32 m0, s20, 0x2000
	s_nop 0
	global_load_lds_dwordx4 v134, s[6:7]
	v_lshl_add_u64 v[208:209], v[214:215], 0, s[24:25]
	s_mov_b32 m0, s62
	s_nop 0
	global_load_lds_dwordx4 v[208:209], off
	v_lshl_add_u64 v[208:209], v[216:217], 0, s[24:25]
	s_mov_b32 m0, s63
	s_nop 0
	global_load_lds_dwordx4 v[208:209], off
	s_setprio 0
	s_waitcnt vmcnt(8)
	s_waitcnt lgkmcnt(0)
	s_barrier
	s_waitcnt lgkmcnt(0)
	v_mfma_f32_16x16x32_bf16 v[62:65], v[140:143], v[176:179], v[62:65]
	v_mfma_f32_16x16x32_bf16 v[58:61], v[148:151], v[176:179], v[58:61]
	v_mfma_f32_16x16x32_bf16 v[46:49], v[140:143], v[184:187], v[46:49]
	v_mfma_f32_16x16x32_bf16 v[42:45], v[148:151], v[184:187], v[42:45]
	v_mfma_f32_16x16x32_bf16 v[30:33], v[140:143], v[192:195], v[30:33]
	v_mfma_f32_16x16x32_bf16 v[26:29], v[148:151], v[192:195], v[26:29]
	v_mfma_f32_16x16x32_bf16 v[14:17], v[140:143], v[200:203], v[14:17]
	v_mfma_f32_16x16x32_bf16 v[10:13], v[148:151], v[200:203], v[10:13]
	v_mfma_f32_16x16x32_bf16 v[62:65], v[144:147], v[180:183], v[62:65]
	v_mfma_f32_16x16x32_bf16 v[58:61], v[152:155], v[180:183], v[58:61]
	v_mfma_f32_16x16x32_bf16 v[46:49], v[144:147], v[188:191], v[46:49]
	v_mfma_f32_16x16x32_bf16 v[42:45], v[152:155], v[188:191], v[42:45]
	v_mfma_f32_16x16x32_bf16 v[30:33], v[144:147], v[196:199], v[30:33]
	v_mfma_f32_16x16x32_bf16 v[26:29], v[152:155], v[196:199], v[26:29]
	v_mfma_f32_16x16x32_bf16 v[14:17], v[144:147], v[204:207], v[14:17]
	v_mfma_f32_16x16x32_bf16 v[10:13], v[152:155], v[204:207], v[10:13]
	v_mfma_f32_16x16x32_bf16 v[54:57], v[156:159], v[176:179], v[54:57]
	v_mfma_f32_16x16x32_bf16 v[50:53], v[164:167], v[176:179], v[50:53]
	v_mfma_f32_16x16x32_bf16 v[38:41], v[156:159], v[184:187], v[38:41]
	v_mfma_f32_16x16x32_bf16 v[34:37], v[164:167], v[184:187], v[34:37]
	v_mfma_f32_16x16x32_bf16 v[22:25], v[156:159], v[192:195], v[22:25]
	v_mfma_f32_16x16x32_bf16 v[18:21], v[164:167], v[192:195], v[18:21]
	v_mfma_f32_16x16x32_bf16 v[6:9], v[156:159], v[200:203], v[6:9]
	v_mfma_f32_16x16x32_bf16 v[2:5], v[164:167], v[200:203], v[2:5]
	v_mfma_f32_16x16x32_bf16 v[54:57], v[160:163], v[180:183], v[54:57]
	v_mfma_f32_16x16x32_bf16 v[50:53], v[168:171], v[180:183], v[50:53]
	v_mfma_f32_16x16x32_bf16 v[38:41], v[160:163], v[188:191], v[38:41]
	v_mfma_f32_16x16x32_bf16 v[34:37], v[168:171], v[188:191], v[34:37]
	v_mfma_f32_16x16x32_bf16 v[22:25], v[160:163], v[196:199], v[22:25]
	v_mfma_f32_16x16x32_bf16 v[18:21], v[168:171], v[196:199], v[18:21]
	v_mfma_f32_16x16x32_bf16 v[6:9], v[160:163], v[204:207], v[6:9]
	v_mfma_f32_16x16x32_bf16 v[2:5], v[168:171], v[204:207], v[2:5]
	s_barrier
	s_setprio 1
	s_add_i32 s72, s72, 2
	s_add_u32 s4, s4, 0x100
	s_addc_u32 s5, s5, 0
	s_add_u32 s19, s19, 0x100
	s_addc_u32 s47, s47, 0
	s_cmp_gt_u32 s72, 13
	s_cbranch_scc0 .LBB0_2148
	s_and_b64 vcc, exec, s[16:17]
	s_cbranch_vccz .LBB0_2151
	s_barrier

.LBB0_2262:
	s_add_u32 s20, s44, 0xfffc0080
	s_addc_u32 s21, s45, -1
	s_add_i32 s37, 0, 0x10000
	s_cmp_eq_u32 s69, 12
	s_cselect_b32 s49, s5, s21
	s_cselect_b32 s48, s4, s20
	s_cselect_b32 s47, s19, s43
	s_cselect_b32 s46, s18, s17
	s_add_i32 s70, 0, 0x14000
	v_add_u32_e32 v152, s37, v142
	v_add_u32_e32 v168, s70, v142
	ds_read_b128 v[136:139], v152
	ds_read_b128 v[144:147], v152 offset:1024
	ds_read_b128 v[148:151], v152 offset:2048
	ds_read_b128 v[152:155], v152 offset:3072
	ds_read_b128 v[156:159], v168
	ds_read_b128 v[160:163], v168 offset:1024
	ds_read_b128 v[164:167], v168 offset:2048
	ds_read_b128 v[168:171], v168 offset:3072
	s_add_i32 m0, s56, 0xc000
	ds_read_b128 v[172:175], v143
	ds_read_b128 v[176:179], v143 offset:1024
	ds_read_b128 v[180:183], v143 offset:2048
	ds_read_b128 v[184:187], v143 offset:3072
	ds_read_b128 v[188:191], v143 offset:4096
	ds_read_b128 v[192:195], v143 offset:5120
	ds_read_b128 v[196:199], v143 offset:6144
	ds_read_b128 v[200:203], v143 offset:7168
	global_load_lds_dwordx4 v132, s[44:45]
	s_add_i32 m0, s56, 0xe000
	s_nop 0
	global_load_lds_dwordx4 v134, s[44:45]
	s_setprio 0
	s_waitcnt vmcnt(8)
	s_waitcnt lgkmcnt(0)
	s_barrier
	s_waitcnt lgkmcnt(0)
	v_mfma_f32_16x16x32_bf16 v[126:129], v[136:139], v[172:175], v[126:129]
	v_mfma_f32_16x16x32_bf16 v[122:125], v[148:151], v[172:175], v[122:125]
	v_mfma_f32_16x16x32_bf16 v[110:113], v[136:139], v[180:183], v[110:113]
	v_mfma_f32_16x16x32_bf16 v[106:109], v[148:151], v[180:183], v[106:109]
	v_mfma_f32_16x16x32_bf16 v[94:97], v[136:139], v[188:191], v[94:97]
	v_mfma_f32_16x16x32_bf16 v[90:93], v[148:151], v[188:191], v[90:93]
	v_mfma_f32_16x16x32_bf16 v[78:81], v[136:139], v[196:199], v[78:81]
	v_mfma_f32_16x16x32_bf16 v[74:77], v[148:151], v[196:199], v[74:77]
	v_mfma_f32_16x16x32_bf16 v[126:129], v[144:147], v[176:179], v[126:129]
	v_mfma_f32_16x16x32_bf16 v[122:125], v[152:155], v[176:179], v[122:125]
	v_mfma_f32_16x16x32_bf16 v[110:113], v[144:147], v[184:187], v[110:113]
	v_mfma_f32_16x16x32_bf16 v[106:109], v[152:155], v[184:187], v[106:109]
	v_mfma_f32_16x16x32_bf16 v[94:97], v[144:147], v[192:195], v[94:97]
	v_mfma_f32_16x16x32_bf16 v[90:93], v[152:155], v[192:195], v[90:93]
	v_mfma_f32_16x16x32_bf16 v[78:81], v[144:147], v[200:203], v[78:81]
	v_mfma_f32_16x16x32_bf16 v[74:77], v[152:155], v[200:203], v[74:77]
	v_mfma_f32_16x16x32_bf16 v[118:121], v[156:159], v[172:175], v[118:121]
	v_mfma_f32_16x16x32_bf16 v[114:117], v[164:167], v[172:175], v[114:117]
	v_mfma_f32_16x16x32_bf16 v[102:105], v[156:159], v[180:183], v[102:105]
	v_mfma_f32_16x16x32_bf16 v[98:101], v[164:167], v[180:183], v[98:101]
	v_mfma_f32_16x16x32_bf16 v[86:89], v[156:159], v[188:191], v[86:89]
	v_mfma_f32_16x16x32_bf16 v[82:85], v[164:167], v[188:191], v[82:85]
	v_mfma_f32_16x16x32_bf16 v[70:73], v[156:159], v[196:199], v[70:73]
	v_mfma_f32_16x16x32_bf16 v[66:69], v[164:167], v[196:199], v[66:69]
	v_mfma_f32_16x16x32_bf16 v[118:121], v[160:163], v[176:179], v[118:121]
	v_mfma_f32_16x16x32_bf16 v[114:117], v[168:171], v[176:179], v[114:117]
	v_mfma_f32_16x16x32_bf16 v[102:105], v[160:163], v[184:187], v[102:105]
	v_mfma_f32_16x16x32_bf16 v[98:101], v[168:171], v[184:187], v[98:101]
	v_mfma_f32_16x16x32_bf16 v[86:89], v[160:163], v[192:195], v[86:89]
	v_mfma_f32_16x16x32_bf16 v[82:85], v[168:171], v[192:195], v[82:85]
	v_mfma_f32_16x16x32_bf16 v[70:73], v[160:163], v[200:203], v[70:73]
	v_mfma_f32_16x16x32_bf16 v[66:69], v[168:171], v[200:203], v[66:69]
	s_barrier
	s_setprio 1
	s_add_i32 s20, s37, s55
	v_lshl_add_u64 v[204:205], s[46:47], 0, v[0:1]
	s_mov_b32 m0, s20
	ds_read_b128 v[172:175], v143 offset:16384
	ds_read_b128 v[176:179], v143 offset:17408
	ds_read_b128 v[180:183], v143 offset:18432
	ds_read_b128 v[184:187], v143 offset:19456
	ds_read_b128 v[188:191], v143 offset:20480
	ds_read_b128 v[192:195], v143 offset:21504
	ds_read_b128 v[196:199], v143 offset:22528
	ds_read_b128 v[200:203], v143 offset:23552
	global_load_lds_dwordx4 v[204:205], off
	s_add_i32 m0, s20, 0x2000
	s_add_u32 s20, s46, 0x40000
	v_lshl_add_u64 v[206:207], s[46:47], 0, v[130:131]
	s_addc_u32 s21, s47, 0
	s_add_i32 s37, s70, s55
	global_load_lds_dwordx4 v[206:207], off
	s_mov_b32 m0, s37
	v_lshl_add_u64 v[210:211], s[48:49], 0, v[130:131]
	global_load_lds_dwordx4 v0, s[20:21]
	s_add_i32 m0, s37, 0x2000
	s_nop 0
	global_load_lds_dwordx4 v130, s[20:21]
	v_lshl_add_u64 v[208:209], s[48:49], 0, v[0:1]
	s_mov_b32 m0, s56
	s_nop 0
	global_load_lds_dwordx4 v[208:209], off
	s_mov_b32 m0, s57
	s_nop 0
	global_load_lds_dwordx4 v[210:211], off
	s_setprio 0
	s_waitcnt vmcnt(8)
	s_waitcnt lgkmcnt(0)
	s_barrier
	s_waitcnt lgkmcnt(0)
	v_mfma_f32_16x16x32_bf16 v[62:65], v[136:139], v[172:175], v[62:65]
	v_mfma_f32_16x16x32_bf16 v[58:61], v[148:151], v[172:175], v[58:61]
	v_mfma_f32_16x16x32_bf16 v[46:49], v[136:139], v[180:183], v[46:49]
	v_mfma_f32_16x16x32_bf16 v[42:45], v[148:151], v[180:183], v[42:45]
	v_mfma_f32_16x16x32_bf16 v[30:33], v[136:139], v[188:191], v[30:33]
	v_mfma_f32_16x16x32_bf16 v[26:29], v[148:151], v[188:191], v[26:29]
	v_mfma_f32_16x16x32_bf16 v[14:17], v[136:139], v[196:199], v[14:17]
	v_mfma_f32_16x16x32_bf16 v[10:13], v[148:151], v[196:199], v[10:13]
	v_mfma_f32_16x16x32_bf16 v[62:65], v[144:147], v[176:179], v[62:65]
	v_mfma_f32_16x16x32_bf16 v[58:61], v[152:155], v[176:179], v[58:61]
	v_mfma_f32_16x16x32_bf16 v[46:49], v[144:147], v[184:187], v[46:49]
	v_mfma_f32_16x16x32_bf16 v[42:45], v[152:155], v[184:187], v[42:45]
	v_mfma_f32_16x16x32_bf16 v[30:33], v[144:147], v[192:195], v[30:33]
	v_mfma_f32_16x16x32_bf16 v[26:29], v[152:155], v[192:195], v[26:29]
	v_mfma_f32_16x16x32_bf16 v[14:17], v[144:147], v[200:203], v[14:17]
	v_mfma_f32_16x16x32_bf16 v[10:13], v[152:155], v[200:203], v[10:13]
	v_mfma_f32_16x16x32_bf16 v[54:57], v[156:159], v[172:175], v[54:57]
	v_mfma_f32_16x16x32_bf16 v[50:53], v[164:167], v[172:175], v[50:53]
	v_mfma_f32_16x16x32_bf16 v[38:41], v[156:159], v[180:183], v[38:41]
	v_mfma_f32_16x16x32_bf16 v[34:37], v[164:167], v[180:183], v[34:37]
	v_mfma_f32_16x16x32_bf16 v[22:25], v[156:159], v[188:191], v[22:25]
	v_mfma_f32_16x16x32_bf16 v[18:21], v[164:167], v[188:191], v[18:21]
	v_mfma_f32_16x16x32_bf16 v[6:9], v[156:159], v[196:199], v[6:9]
	v_mfma_f32_16x16x32_bf16 v[2:5], v[164:167], v[196:199], v[2:5]
	v_mfma_f32_16x16x32_bf16 v[54:57], v[160:163], v[176:179], v[54:57]
	v_mfma_f32_16x16x32_bf16 v[50:53], v[168:171], v[176:179], v[50:53]
	v_mfma_f32_16x16x32_bf16 v[38:41], v[160:163], v[184:187], v[38:41]
	v_mfma_f32_16x16x32_bf16 v[34:37], v[168:171], v[184:187], v[34:37]
	v_mfma_f32_16x16x32_bf16 v[22:25], v[160:163], v[192:195], v[22:25]
	v_mfma_f32_16x16x32_bf16 v[18:21], v[168:171], v[192:195], v[18:21]
	v_mfma_f32_16x16x32_bf16 v[6:9], v[160:163], v[200:203], v[6:9]
	v_mfma_f32_16x16x32_bf16 v[2:5], v[168:171], v[200:203], v[2:5]
	s_barrier
	s_setprio 1
	s_add_i32 s37, 0, 0x18000
	s_add_i32 s70, 0, 0x1c000
	v_add_u32_e32 v152, s37, v142
	v_add_u32_e32 v168, s70, v142
	ds_read_b128 v[136:139], v152
	ds_read_b128 v[144:147], v152 offset:1024
	ds_read_b128 v[148:151], v152 offset:2048
	ds_read_b128 v[152:155], v152 offset:3072
	ds_read_b128 v[156:159], v168
	ds_read_b128 v[160:163], v168 offset:1024
	ds_read_b128 v[164:167], v168 offset:2048
	ds_read_b128 v[168:171], v168 offset:3072
	s_add_u32 s20, s48, 0x40000
	s_addc_u32 s21, s49, 0
	s_mov_b32 m0, s58
	ds_read_b128 v[172:175], v143 offset:32768
	ds_read_b128 v[176:179], v143 offset:33792
	ds_read_b128 v[180:183], v143 offset:34816
	ds_read_b128 v[184:187], v143 offset:35840
	ds_read_b128 v[188:191], v143 offset:36864
	ds_read_b128 v[192:195], v143 offset:37888
	ds_read_b128 v[196:199], v143 offset:38912
	ds_read_b128 v[200:203], v143 offset:39936
	global_load_lds_dwordx4 v0, s[20:21]
	v_lshl_add_u64 v[214:215], s[20:21], 0, v[130:131]
	s_mov_b32 m0, s59
	s_nop 0
	global_load_lds_dwordx4 v[214:215], off
	s_setprio 0
	s_waitcnt vmcnt(8)
	s_waitcnt lgkmcnt(0)
	s_barrier
	s_waitcnt lgkmcnt(0)
	v_mfma_f32_16x16x32_bf16 v[126:129], v[136:139], v[172:175], v[126:129]
	v_mfma_f32_16x16x32_bf16 v[122:125], v[148:151], v[172:175], v[122:125]
	v_mfma_f32_16x16x32_bf16 v[110:113], v[136:139], v[180:183], v[110:113]
	v_mfma_f32_16x16x32_bf16 v[106:109], v[148:151], v[180:183], v[106:109]
	v_mfma_f32_16x16x32_bf16 v[94:97], v[136:139], v[188:191], v[94:97]
	v_mfma_f32_16x16x32_bf16 v[90:93], v[148:151], v[188:191], v[90:93]
	v_mfma_f32_16x16x32_bf16 v[78:81], v[136:139], v[196:199], v[78:81]
	v_mfma_f32_16x16x32_bf16 v[74:77], v[148:151], v[196:199], v[74:77]
	v_mfma_f32_16x16x32_bf16 v[126:129], v[144:147], v[176:179], v[126:129]
	v_mfma_f32_16x16x32_bf16 v[122:125], v[152:155], v[176:179], v[122:125]
	v_mfma_f32_16x16x32_bf16 v[110:113], v[144:147], v[184:187], v[110:113]
	v_mfma_f32_16x16x32_bf16 v[106:109], v[152:155], v[184:187], v[106:109]
	v_mfma_f32_16x16x32_bf16 v[94:97], v[144:147], v[192:195], v[94:97]
	v_mfma_f32_16x16x32_bf16 v[90:93], v[152:155], v[192:195], v[90:93]
	v_mfma_f32_16x16x32_bf16 v[78:81], v[144:147], v[200:203], v[78:81]
	v_mfma_f32_16x16x32_bf16 v[74:77], v[152:155], v[200:203], v[74:77]
	v_mfma_f32_16x16x32_bf16 v[118:121], v[156:159], v[172:175], v[118:121]
	v_mfma_f32_16x16x32_bf16 v[114:117], v[164:167], v[172:175], v[114:117]
	v_mfma_f32_16x16x32_bf16 v[102:105], v[156:159], v[180:183], v[102:105]
	v_mfma_f32_16x16x32_bf16 v[98:101], v[164:167], v[180:183], v[98:101]
	v_mfma_f32_16x16x32_bf16 v[86:89], v[156:159], v[188:191], v[86:89]
	v_mfma_f32_16x16x32_bf16 v[82:85], v[164:167], v[188:191], v[82:85]
	v_mfma_f32_16x16x32_bf16 v[70:73], v[156:159], v[196:199], v[70:73]
	v_mfma_f32_16x16x32_bf16 v[66:69], v[164:167], v[196:199], v[66:69]
	v_mfma_f32_16x16x32_bf16 v[118:121], v[160:163], v[176:179], v[118:121]
	v_mfma_f32_16x16x32_bf16 v[114:117], v[168:171], v[176:179], v[114:117]
	v_mfma_f32_16x16x32_bf16 v[102:105], v[160:163], v[184:187], v[102:105]
	v_mfma_f32_16x16x32_bf16 v[98:101], v[168:171], v[184:187], v[98:101]
	v_mfma_f32_16x16x32_bf16 v[86:89], v[160:163], v[192:195], v[86:89]
	v_mfma_f32_16x16x32_bf16 v[82:85], v[168:171], v[192:195], v[82:85]
	v_mfma_f32_16x16x32_bf16 v[70:73], v[160:163], v[200:203], v[70:73]
	v_mfma_f32_16x16x32_bf16 v[66:69], v[168:171], v[200:203], v[66:69]
	s_barrier
	s_setprio 1
	s_add_i32 s20, s37, s55
	v_lshl_add_u64 v[204:205], v[204:205], 0, s[24:25]
	s_mov_b32 m0, s20
	ds_read_b128 v[172:175], v143 offset:49152
	ds_read_b128 v[176:179], v143 offset:50176
	ds_read_b128 v[180:183], v143 offset:51200
	ds_read_b128 v[184:187], v143 offset:52224
	ds_read_b128 v[188:191], v143 offset:53248
	ds_read_b128 v[192:195], v143 offset:54272
	ds_read_b128 v[196:199], v143 offset:55296
	ds_read_b128 v[200:203], v143 offset:56320
	global_load_lds_dwordx4 v[204:205], off
	s_add_i32 m0, s20, 0x2000
	s_add_u32 s20, s46, 0x40080
	v_lshl_add_u64 v[204:205], v[206:207], 0, s[24:25]
	s_addc_u32 s21, s47, 0
	s_add_i32 s37, s70, s55
	global_load_lds_dwordx4 v[204:205], off
	s_mov_b32 m0, s37
	s_nop 0
	global_load_lds_dwordx4 v0, s[20:21]
	s_add_i32 m0, s37, 0x2000
	s_nop 0
	global_load_lds_dwordx4 v130, s[20:21]
	v_lshl_add_u64 v[204:205], v[208:209], 0, s[24:25]
	s_mov_b32 m0, s63
	s_nop 0
	global_load_lds_dwordx4 v[204:205], off
	v_lshl_add_u64 v[204:205], v[210:211], 0, s[24:25]
	s_mov_b32 m0, s64
	s_nop 0
	global_load_lds_dwordx4 v[204:205], off
	s_setprio 0
	s_waitcnt vmcnt(8)
	s_waitcnt lgkmcnt(0)
	s_barrier
	s_waitcnt lgkmcnt(0)
	v_mfma_f32_16x16x32_bf16 v[62:65], v[136:139], v[172:175], v[62:65]
	v_mfma_f32_16x16x32_bf16 v[58:61], v[148:151], v[172:175], v[58:61]
	v_mfma_f32_16x16x32_bf16 v[46:49], v[136:139], v[180:183], v[46:49]
	v_mfma_f32_16x16x32_bf16 v[42:45], v[148:151], v[180:183], v[42:45]
	v_mfma_f32_16x16x32_bf16 v[30:33], v[136:139], v[188:191], v[30:33]
	v_mfma_f32_16x16x32_bf16 v[26:29], v[148:151], v[188:191], v[26:29]
	v_mfma_f32_16x16x32_bf16 v[14:17], v[136:139], v[196:199], v[14:17]
	v_mfma_f32_16x16x32_bf16 v[10:13], v[148:151], v[196:199], v[10:13]
	v_mfma_f32_16x16x32_bf16 v[62:65], v[144:147], v[176:179], v[62:65]
	v_mfma_f32_16x16x32_bf16 v[58:61], v[152:155], v[176:179], v[58:61]
	v_mfma_f32_16x16x32_bf16 v[46:49], v[144:147], v[184:187], v[46:49]
	v_mfma_f32_16x16x32_bf16 v[42:45], v[152:155], v[184:187], v[42:45]
	v_mfma_f32_16x16x32_bf16 v[30:33], v[144:147], v[192:195], v[30:33]
	v_mfma_f32_16x16x32_bf16 v[26:29], v[152:155], v[192:195], v[26:29]
	v_mfma_f32_16x16x32_bf16 v[14:17], v[144:147], v[200:203], v[14:17]
	v_mfma_f32_16x16x32_bf16 v[10:13], v[152:155], v[200:203], v[10:13]
	v_mfma_f32_16x16x32_bf16 v[54:57], v[156:159], v[172:175], v[54:57]
	v_mfma_f32_16x16x32_bf16 v[50:53], v[164:167], v[172:175], v[50:53]
	v_mfma_f32_16x16x32_bf16 v[38:41], v[156:159], v[180:183], v[38:41]
	v_mfma_f32_16x16x32_bf16 v[34:37], v[164:167], v[180:183], v[34:37]
	v_mfma_f32_16x16x32_bf16 v[22:25], v[156:159], v[188:191], v[22:25]
	v_mfma_f32_16x16x32_bf16 v[18:21], v[164:167], v[188:191], v[18:21]
	v_mfma_f32_16x16x32_bf16 v[6:9], v[156:159], v[196:199], v[6:9]
	v_mfma_f32_16x16x32_bf16 v[2:5], v[164:167], v[196:199], v[2:5]
	v_mfma_f32_16x16x32_bf16 v[54:57], v[160:163], v[176:179], v[54:57]
	v_mfma_f32_16x16x32_bf16 v[50:53], v[168:171], v[176:179], v[50:53]
	v_mfma_f32_16x16x32_bf16 v[38:41], v[160:163], v[184:187], v[38:41]
	v_mfma_f32_16x16x32_bf16 v[34:37], v[168:171], v[184:187], v[34:37]
	v_mfma_f32_16x16x32_bf16 v[22:25], v[160:163], v[192:195], v[22:25]
	v_mfma_f32_16x16x32_bf16 v[18:21], v[168:171], v[192:195], v[18:21]
	v_mfma_f32_16x16x32_bf16 v[6:9], v[160:163], v[200:203], v[6:9]
	v_mfma_f32_16x16x32_bf16 v[2:5], v[168:171], v[200:203], v[2:5]
	s_barrier
	s_setprio 1
	s_add_i32 s69, s69, 2
	s_add_u32 s44, s44, 0x100
	s_addc_u32 s45, s45, 0
	s_add_u32 s17, s17, 0x100
	s_addc_u32 s43, s43, 0
	s_cmp_gt_u32 s69, 13
	s_cbranch_scc0 .LBB0_2262
	s_and_b64 vcc, exec, s[12:13]
	s_cbranch_vccz .LBB0_2265
	s_barrier

.LBB0_2428:
	s_add_u32 s8, s4, 0xfffc0080
	s_addc_u32 s9, s5, -1
	s_add_i32 s20, 0, 0x10000
	s_cmp_eq_u32 s70, 12
	s_cselect_b32 s53, s49, s9
	s_cselect_b32 s52, s48, s8
	v_add_u32_e32 v144, s20, v147
	s_cselect_b32 s9, s7, s69
	s_cselect_b32 s8, s47, s68
	s_add_i32 s37, 0, 0x14000
	ds_read_b128 v[140:143], v144
	ds_read_b128 v[150:153], v144 offset:1024
	ds_read_b128 v[154:157], v144 offset:2048
	ds_read_b128 v[158:161], v144 offset:3072
	v_add_u32_e32 v144, s37, v147
	ds_read_b128 v[162:165], v144
	ds_read_b128 v[166:169], v144 offset:1024
	ds_read_b128 v[170:173], v144 offset:2048
	ds_read_b128 v[174:177], v144 offset:3072
	s_add_i32 m0, s57, 0xc000
	ds_read_b128 v[178:181], v149
	ds_read_b128 v[182:185], v149 offset:1024
	ds_read_b128 v[186:189], v149 offset:2048
	ds_read_b128 v[190:193], v149 offset:3072
	ds_read_b128 v[194:197], v149 offset:4096
	ds_read_b128 v[198:201], v149 offset:5120
	ds_read_b128 v[202:205], v149 offset:6144
	ds_read_b128 v[206:209], v149 offset:7168
	global_load_lds_dwordx4 v136, s[4:5]
	s_add_i32 m0, s57, 0xe000
	s_nop 0
	global_load_lds_dwordx4 v138, s[4:5]
	s_setprio 0
	s_waitcnt vmcnt(8)
	s_waitcnt lgkmcnt(0)
	s_barrier
	s_waitcnt lgkmcnt(0)
	v_mfma_f32_16x16x32_bf16 v[126:129], v[140:143], v[178:181], v[126:129]
	v_mfma_f32_16x16x32_bf16 v[122:125], v[154:157], v[178:181], v[122:125]
	v_mfma_f32_16x16x32_bf16 v[110:113], v[140:143], v[186:189], v[110:113]
	v_mfma_f32_16x16x32_bf16 v[106:109], v[154:157], v[186:189], v[106:109]
	v_mfma_f32_16x16x32_bf16 v[94:97], v[140:143], v[194:197], v[94:97]
	v_mfma_f32_16x16x32_bf16 v[90:93], v[154:157], v[194:197], v[90:93]
	v_mfma_f32_16x16x32_bf16 v[78:81], v[140:143], v[202:205], v[78:81]
	v_mfma_f32_16x16x32_bf16 v[74:77], v[154:157], v[202:205], v[74:77]
	v_mfma_f32_16x16x32_bf16 v[126:129], v[150:153], v[182:185], v[126:129]
	v_mfma_f32_16x16x32_bf16 v[122:125], v[158:161], v[182:185], v[122:125]
	v_mfma_f32_16x16x32_bf16 v[110:113], v[150:153], v[190:193], v[110:113]
	v_mfma_f32_16x16x32_bf16 v[106:109], v[158:161], v[190:193], v[106:109]
	v_mfma_f32_16x16x32_bf16 v[94:97], v[150:153], v[198:201], v[94:97]
	v_mfma_f32_16x16x32_bf16 v[90:93], v[158:161], v[198:201], v[90:93]
	v_mfma_f32_16x16x32_bf16 v[78:81], v[150:153], v[206:209], v[78:81]
	v_mfma_f32_16x16x32_bf16 v[74:77], v[158:161], v[206:209], v[74:77]
	v_mfma_f32_16x16x32_bf16 v[118:121], v[162:165], v[178:181], v[118:121]
	v_mfma_f32_16x16x32_bf16 v[114:117], v[170:173], v[178:181], v[114:117]
	v_mfma_f32_16x16x32_bf16 v[102:105], v[162:165], v[186:189], v[102:105]
	v_mfma_f32_16x16x32_bf16 v[98:101], v[170:173], v[186:189], v[98:101]
	v_mfma_f32_16x16x32_bf16 v[86:89], v[162:165], v[194:197], v[86:89]
	v_mfma_f32_16x16x32_bf16 v[82:85], v[170:173], v[194:197], v[82:85]
	v_mfma_f32_16x16x32_bf16 v[70:73], v[162:165], v[202:205], v[70:73]
	v_mfma_f32_16x16x32_bf16 v[66:69], v[170:173], v[202:205], v[66:69]
	v_mfma_f32_16x16x32_bf16 v[118:121], v[166:169], v[182:185], v[118:121]
	v_mfma_f32_16x16x32_bf16 v[114:117], v[174:177], v[182:185], v[114:117]
	v_mfma_f32_16x16x32_bf16 v[102:105], v[166:169], v[190:193], v[102:105]
	v_mfma_f32_16x16x32_bf16 v[98:101], v[174:177], v[190:193], v[98:101]
	v_mfma_f32_16x16x32_bf16 v[86:89], v[166:169], v[198:201], v[86:89]
	v_mfma_f32_16x16x32_bf16 v[82:85], v[174:177], v[198:201], v[82:85]
	v_mfma_f32_16x16x32_bf16 v[70:73], v[166:169], v[206:209], v[70:73]
	v_mfma_f32_16x16x32_bf16 v[66:69], v[174:177], v[206:209], v[66:69]
	s_barrier
	s_setprio 1
	s_add_i32 s20, s20, s56
	v_lshl_add_u64 v[144:145], s[8:9], 0, v[0:1]
	s_mov_b32 m0, s20
	ds_read_b128 v[178:181], v149 offset:16384
	ds_read_b128 v[182:185], v149 offset:17408
	ds_read_b128 v[186:189], v149 offset:18432
	ds_read_b128 v[190:193], v149 offset:19456
	ds_read_b128 v[194:197], v149 offset:20480
	ds_read_b128 v[198:201], v149 offset:21504
	ds_read_b128 v[202:205], v149 offset:22528
	ds_read_b128 v[206:209], v149 offset:23552
	global_load_lds_dwordx4 v[144:145], off
	s_add_i32 m0, s20, 0x2000
	s_add_u32 s20, s8, 0x40000
	v_lshl_add_u64 v[210:211], s[8:9], 0, v[134:135]
	s_addc_u32 s21, s9, 0
	s_add_i32 s37, s37, s56
	global_load_lds_dwordx4 v[210:211], off
	s_mov_b32 m0, s37
	v_lshl_add_u64 v[216:217], s[52:53], 0, v[132:133]
	global_load_lds_dwordx4 v0, s[20:21]
	s_add_i32 m0, s37, 0x2000
	s_nop 0
	global_load_lds_dwordx4 v134, s[20:21]
	v_lshl_add_u64 v[214:215], s[52:53], 0, v[130:131]
	s_mov_b32 m0, s57
	s_nop 0
	global_load_lds_dwordx4 v[214:215], off
	s_mov_b32 m0, s58
	s_nop 0
	global_load_lds_dwordx4 v[216:217], off
	s_setprio 0
	s_waitcnt vmcnt(8)
	s_waitcnt lgkmcnt(0)
	s_barrier
	s_waitcnt lgkmcnt(0)
	v_mfma_f32_16x16x32_bf16 v[62:65], v[140:143], v[178:181], v[62:65]
	v_mfma_f32_16x16x32_bf16 v[58:61], v[154:157], v[178:181], v[58:61]
	v_mfma_f32_16x16x32_bf16 v[46:49], v[140:143], v[186:189], v[46:49]
	v_mfma_f32_16x16x32_bf16 v[42:45], v[154:157], v[186:189], v[42:45]
	v_mfma_f32_16x16x32_bf16 v[30:33], v[140:143], v[194:197], v[30:33]
	v_mfma_f32_16x16x32_bf16 v[26:29], v[154:157], v[194:197], v[26:29]
	v_mfma_f32_16x16x32_bf16 v[14:17], v[140:143], v[202:205], v[14:17]
	v_mfma_f32_16x16x32_bf16 v[10:13], v[154:157], v[202:205], v[10:13]
	v_mfma_f32_16x16x32_bf16 v[62:65], v[150:153], v[182:185], v[62:65]
	v_mfma_f32_16x16x32_bf16 v[58:61], v[158:161], v[182:185], v[58:61]
	v_mfma_f32_16x16x32_bf16 v[46:49], v[150:153], v[190:193], v[46:49]
	v_mfma_f32_16x16x32_bf16 v[42:45], v[158:161], v[190:193], v[42:45]
	v_mfma_f32_16x16x32_bf16 v[30:33], v[150:153], v[198:201], v[30:33]
	v_mfma_f32_16x16x32_bf16 v[26:29], v[158:161], v[198:201], v[26:29]
	v_mfma_f32_16x16x32_bf16 v[14:17], v[150:153], v[206:209], v[14:17]
	v_mfma_f32_16x16x32_bf16 v[10:13], v[158:161], v[206:209], v[10:13]
	v_mfma_f32_16x16x32_bf16 v[54:57], v[162:165], v[178:181], v[54:57]
	v_mfma_f32_16x16x32_bf16 v[50:53], v[170:173], v[178:181], v[50:53]
	v_mfma_f32_16x16x32_bf16 v[38:41], v[162:165], v[186:189], v[38:41]
	v_mfma_f32_16x16x32_bf16 v[34:37], v[170:173], v[186:189], v[34:37]
	v_mfma_f32_16x16x32_bf16 v[22:25], v[162:165], v[194:197], v[22:25]
	v_mfma_f32_16x16x32_bf16 v[18:21], v[170:173], v[194:197], v[18:21]
	v_mfma_f32_16x16x32_bf16 v[6:9], v[162:165], v[202:205], v[6:9]
	v_mfma_f32_16x16x32_bf16 v[2:5], v[170:173], v[202:205], v[2:5]
	v_mfma_f32_16x16x32_bf16 v[54:57], v[166:169], v[182:185], v[54:57]
	v_mfma_f32_16x16x32_bf16 v[50:53], v[174:177], v[182:185], v[50:53]
	v_mfma_f32_16x16x32_bf16 v[38:41], v[166:169], v[190:193], v[38:41]
	v_mfma_f32_16x16x32_bf16 v[34:37], v[174:177], v[190:193], v[34:37]
	v_mfma_f32_16x16x32_bf16 v[22:25], v[166:169], v[198:201], v[22:25]
	v_mfma_f32_16x16x32_bf16 v[18:21], v[174:177], v[198:201], v[18:21]
	v_mfma_f32_16x16x32_bf16 v[6:9], v[166:169], v[206:209], v[6:9]
	v_mfma_f32_16x16x32_bf16 v[2:5], v[174:177], v[206:209], v[2:5]
	s_barrier
	s_setprio 1
	s_add_i32 s37, 0, 0x18000
	s_add_i32 s71, 0, 0x1c000
	v_add_u32_e32 v158, s37, v147
	v_add_u32_e32 v174, s71, v147
	ds_read_b128 v[140:143], v158
	ds_read_b128 v[150:153], v158 offset:1024
	ds_read_b128 v[154:157], v158 offset:2048
	ds_read_b128 v[158:161], v158 offset:3072
	ds_read_b128 v[162:165], v174
	ds_read_b128 v[166:169], v174 offset:1024
	ds_read_b128 v[170:173], v174 offset:2048
	ds_read_b128 v[174:177], v174 offset:3072
	s_add_u32 s20, s52, 0x40000
	s_addc_u32 s21, s53, 0
	s_mov_b32 m0, s59
	ds_read_b128 v[178:181], v149 offset:32768
	ds_read_b128 v[182:185], v149 offset:33792
	ds_read_b128 v[186:189], v149 offset:34816
	ds_read_b128 v[190:193], v149 offset:35840
	ds_read_b128 v[194:197], v149 offset:36864
	ds_read_b128 v[198:201], v149 offset:37888
	ds_read_b128 v[202:205], v149 offset:38912
	ds_read_b128 v[206:209], v149 offset:39936
	global_load_lds_dwordx4 v130, s[20:21]
	v_lshl_add_u64 v[218:219], s[20:21], 0, v[132:133]
	s_mov_b32 m0, s60
	s_nop 0
	global_load_lds_dwordx4 v[218:219], off
	s_setprio 0
	s_waitcnt vmcnt(8)
	s_waitcnt lgkmcnt(0)
	s_barrier
	s_waitcnt lgkmcnt(0)
	v_mfma_f32_16x16x32_bf16 v[126:129], v[140:143], v[178:181], v[126:129]
	v_mfma_f32_16x16x32_bf16 v[122:125], v[154:157], v[178:181], v[122:125]
	v_mfma_f32_16x16x32_bf16 v[110:113], v[140:143], v[186:189], v[110:113]
	v_mfma_f32_16x16x32_bf16 v[106:109], v[154:157], v[186:189], v[106:109]
	v_mfma_f32_16x16x32_bf16 v[94:97], v[140:143], v[194:197], v[94:97]
	v_mfma_f32_16x16x32_bf16 v[90:93], v[154:157], v[194:197], v[90:93]
	v_mfma_f32_16x16x32_bf16 v[78:81], v[140:143], v[202:205], v[78:81]
	v_mfma_f32_16x16x32_bf16 v[74:77], v[154:157], v[202:205], v[74:77]
	v_mfma_f32_16x16x32_bf16 v[126:129], v[150:153], v[182:185], v[126:129]
	v_mfma_f32_16x16x32_bf16 v[122:125], v[158:161], v[182:185], v[122:125]
	v_mfma_f32_16x16x32_bf16 v[110:113], v[150:153], v[190:193], v[110:113]
	v_mfma_f32_16x16x32_bf16 v[106:109], v[158:161], v[190:193], v[106:109]
	v_mfma_f32_16x16x32_bf16 v[94:97], v[150:153], v[198:201], v[94:97]
	v_mfma_f32_16x16x32_bf16 v[90:93], v[158:161], v[198:201], v[90:93]
	v_mfma_f32_16x16x32_bf16 v[78:81], v[150:153], v[206:209], v[78:81]
	v_mfma_f32_16x16x32_bf16 v[74:77], v[158:161], v[206:209], v[74:77]
	v_mfma_f32_16x16x32_bf16 v[118:121], v[162:165], v[178:181], v[118:121]
	v_mfma_f32_16x16x32_bf16 v[114:117], v[170:173], v[178:181], v[114:117]
	v_mfma_f32_16x16x32_bf16 v[102:105], v[162:165], v[186:189], v[102:105]
	v_mfma_f32_16x16x32_bf16 v[98:101], v[170:173], v[186:189], v[98:101]
	v_mfma_f32_16x16x32_bf16 v[86:89], v[162:165], v[194:197], v[86:89]
	v_mfma_f32_16x16x32_bf16 v[82:85], v[170:173], v[194:197], v[82:85]
	v_mfma_f32_16x16x32_bf16 v[70:73], v[162:165], v[202:205], v[70:73]
	v_mfma_f32_16x16x32_bf16 v[66:69], v[170:173], v[202:205], v[66:69]
	v_mfma_f32_16x16x32_bf16 v[118:121], v[166:169], v[182:185], v[118:121]
	v_mfma_f32_16x16x32_bf16 v[114:117], v[174:177], v[182:185], v[114:117]
	v_mfma_f32_16x16x32_bf16 v[102:105], v[166:169], v[190:193], v[102:105]
	v_mfma_f32_16x16x32_bf16 v[98:101], v[174:177], v[190:193], v[98:101]
	v_mfma_f32_16x16x32_bf16 v[86:89], v[166:169], v[198:201], v[86:89]
	v_mfma_f32_16x16x32_bf16 v[82:85], v[174:177], v[198:201], v[82:85]
	v_mfma_f32_16x16x32_bf16 v[70:73], v[166:169], v[206:209], v[70:73]
	v_mfma_f32_16x16x32_bf16 v[66:69], v[174:177], v[206:209], v[66:69]
	s_barrier
	s_setprio 1
	s_add_i32 s20, s37, s56
	v_lshl_add_u64 v[144:145], v[144:145], 0, s[24:25]
	s_mov_b32 m0, s20
	ds_read_b128 v[178:181], v149 offset:49152
	ds_read_b128 v[182:185], v149 offset:50176
	ds_read_b128 v[186:189], v149 offset:51200
	ds_read_b128 v[190:193], v149 offset:52224
	ds_read_b128 v[194:197], v149 offset:53248
	ds_read_b128 v[198:201], v149 offset:54272
	ds_read_b128 v[202:205], v149 offset:55296
	ds_read_b128 v[206:209], v149 offset:56320
	global_load_lds_dwordx4 v[144:145], off
	s_add_i32 m0, s20, 0x2000
	s_add_u32 s8, s8, 0x40080
	v_lshl_add_u64 v[144:145], v[210:211], 0, s[24:25]
	s_addc_u32 s9, s9, 0
	s_add_i32 s20, s71, s56
	global_load_lds_dwordx4 v[144:145], off
	s_mov_b32 m0, s20
	s_nop 0
	global_load_lds_dwordx4 v0, s[8:9]
	s_add_i32 m0, s20, 0x2000
	s_nop 0
	global_load_lds_dwordx4 v134, s[8:9]
	v_lshl_add_u64 v[144:145], v[214:215], 0, s[24:25]
	s_mov_b32 m0, s61
	s_nop 0
	global_load_lds_dwordx4 v[144:145], off
	v_lshl_add_u64 v[144:145], v[216:217], 0, s[24:25]
	s_mov_b32 m0, s62
	s_nop 0
	global_load_lds_dwordx4 v[144:145], off
	s_setprio 0
	s_waitcnt vmcnt(8)
	s_waitcnt lgkmcnt(0)
	s_barrier
	s_waitcnt lgkmcnt(0)
	v_mfma_f32_16x16x32_bf16 v[62:65], v[140:143], v[178:181], v[62:65]
	v_mfma_f32_16x16x32_bf16 v[58:61], v[154:157], v[178:181], v[58:61]
	v_mfma_f32_16x16x32_bf16 v[46:49], v[140:143], v[186:189], v[46:49]
	v_mfma_f32_16x16x32_bf16 v[42:45], v[154:157], v[186:189], v[42:45]
	v_mfma_f32_16x16x32_bf16 v[30:33], v[140:143], v[194:197], v[30:33]
	v_mfma_f32_16x16x32_bf16 v[26:29], v[154:157], v[194:197], v[26:29]
	v_mfma_f32_16x16x32_bf16 v[14:17], v[140:143], v[202:205], v[14:17]
	v_mfma_f32_16x16x32_bf16 v[10:13], v[154:157], v[202:205], v[10:13]
	v_mfma_f32_16x16x32_bf16 v[62:65], v[150:153], v[182:185], v[62:65]
	v_mfma_f32_16x16x32_bf16 v[58:61], v[158:161], v[182:185], v[58:61]
	v_mfma_f32_16x16x32_bf16 v[46:49], v[150:153], v[190:193], v[46:49]
	v_mfma_f32_16x16x32_bf16 v[42:45], v[158:161], v[190:193], v[42:45]
	v_mfma_f32_16x16x32_bf16 v[30:33], v[150:153], v[198:201], v[30:33]
	v_mfma_f32_16x16x32_bf16 v[26:29], v[158:161], v[198:201], v[26:29]
	v_mfma_f32_16x16x32_bf16 v[14:17], v[150:153], v[206:209], v[14:17]
	v_mfma_f32_16x16x32_bf16 v[10:13], v[158:161], v[206:209], v[10:13]
	v_mfma_f32_16x16x32_bf16 v[54:57], v[162:165], v[178:181], v[54:57]
	v_mfma_f32_16x16x32_bf16 v[50:53], v[170:173], v[178:181], v[50:53]
	v_mfma_f32_16x16x32_bf16 v[38:41], v[162:165], v[186:189], v[38:41]
	v_mfma_f32_16x16x32_bf16 v[34:37], v[170:173], v[186:189], v[34:37]
	v_mfma_f32_16x16x32_bf16 v[22:25], v[162:165], v[194:197], v[22:25]
	v_mfma_f32_16x16x32_bf16 v[18:21], v[170:173], v[194:197], v[18:21]
	v_mfma_f32_16x16x32_bf16 v[6:9], v[162:165], v[202:205], v[6:9]
	v_mfma_f32_16x16x32_bf16 v[2:5], v[170:173], v[202:205], v[2:5]
	v_mfma_f32_16x16x32_bf16 v[54:57], v[166:169], v[182:185], v[54:57]
	v_mfma_f32_16x16x32_bf16 v[50:53], v[174:177], v[182:185], v[50:53]
	v_mfma_f32_16x16x32_bf16 v[38:41], v[166:169], v[190:193], v[38:41]
	v_mfma_f32_16x16x32_bf16 v[34:37], v[174:177], v[190:193], v[34:37]
	v_mfma_f32_16x16x32_bf16 v[22:25], v[166:169], v[198:201], v[22:25]
	v_mfma_f32_16x16x32_bf16 v[18:21], v[174:177], v[198:201], v[18:21]
	v_mfma_f32_16x16x32_bf16 v[6:9], v[166:169], v[206:209], v[6:9]
	v_mfma_f32_16x16x32_bf16 v[2:5], v[174:177], v[206:209], v[2:5]
	s_barrier
	s_setprio 1
	s_add_i32 s70, s70, 2
	s_add_u32 s4, s4, 0x100
	s_addc_u32 s5, s5, 0
	s_add_u32 s68, s68, 0x100
	s_addc_u32 s69, s69, 0
	s_cmp_gt_u32 s70, 13
	s_cbranch_scc0 .LBB0_2428
	s_and_b64 vcc, exec, s[44:45]
	s_cbranch_vccz .LBB0_2431
	s_barrier

.LBB0_2540:
	s_add_u32 s20, s4, 0xfff00080
	s_addc_u32 s21, s5, -1
	s_add_i32 s37, 0, 0x10000
	s_cmp_eq_u32 s73, 60
	s_cselect_b32 s51, s43, s21
	s_cselect_b32 s50, s42, s20
	s_cselect_b32 s49, s41, s72
	s_cselect_b32 s48, s47, s71
	s_add_i32 s77, 0, 0x14000
	v_add_u32_e32 v152, s37, v142
	v_add_u32_e32 v168, s77, v142
	ds_read_b128 v[136:139], v152
	ds_read_b128 v[144:147], v152 offset:1024
	ds_read_b128 v[148:151], v152 offset:2048
	ds_read_b128 v[152:155], v152 offset:3072
	ds_read_b128 v[156:159], v168
	ds_read_b128 v[160:163], v168 offset:1024
	ds_read_b128 v[164:167], v168 offset:2048
	ds_read_b128 v[168:171], v168 offset:3072
	s_add_i32 m0, s58, 0xc000
	ds_read_b128 v[172:175], v143
	ds_read_b128 v[176:179], v143 offset:1024
	ds_read_b128 v[180:183], v143 offset:2048
	ds_read_b128 v[184:187], v143 offset:3072
	ds_read_b128 v[188:191], v143 offset:4096
	ds_read_b128 v[192:195], v143 offset:5120
	ds_read_b128 v[196:199], v143 offset:6144
	ds_read_b128 v[200:203], v143 offset:7168
	global_load_lds_dwordx4 v132, s[4:5]
	s_add_i32 m0, s58, 0xe000
	s_nop 0
	global_load_lds_dwordx4 v134, s[4:5]
	s_setprio 0
	s_waitcnt vmcnt(8)
	s_waitcnt lgkmcnt(0)
	s_barrier
	s_waitcnt lgkmcnt(0)
	v_mfma_f32_16x16x32_bf16 v[126:129], v[136:139], v[172:175], v[126:129]
	v_mfma_f32_16x16x32_bf16 v[122:125], v[148:151], v[172:175], v[122:125]
	v_mfma_f32_16x16x32_bf16 v[110:113], v[136:139], v[180:183], v[110:113]
	v_mfma_f32_16x16x32_bf16 v[106:109], v[148:151], v[180:183], v[106:109]
	v_mfma_f32_16x16x32_bf16 v[94:97], v[136:139], v[188:191], v[94:97]
	v_mfma_f32_16x16x32_bf16 v[90:93], v[148:151], v[188:191], v[90:93]
	v_mfma_f32_16x16x32_bf16 v[78:81], v[136:139], v[196:199], v[78:81]
	v_mfma_f32_16x16x32_bf16 v[74:77], v[148:151], v[196:199], v[74:77]
	v_mfma_f32_16x16x32_bf16 v[126:129], v[144:147], v[176:179], v[126:129]
	v_mfma_f32_16x16x32_bf16 v[122:125], v[152:155], v[176:179], v[122:125]
	v_mfma_f32_16x16x32_bf16 v[110:113], v[144:147], v[184:187], v[110:113]
	v_mfma_f32_16x16x32_bf16 v[106:109], v[152:155], v[184:187], v[106:109]
	v_mfma_f32_16x16x32_bf16 v[94:97], v[144:147], v[192:195], v[94:97]
	v_mfma_f32_16x16x32_bf16 v[90:93], v[152:155], v[192:195], v[90:93]
	v_mfma_f32_16x16x32_bf16 v[78:81], v[144:147], v[200:203], v[78:81]
	v_mfma_f32_16x16x32_bf16 v[74:77], v[152:155], v[200:203], v[74:77]
	v_mfma_f32_16x16x32_bf16 v[118:121], v[156:159], v[172:175], v[118:121]
	v_mfma_f32_16x16x32_bf16 v[114:117], v[164:167], v[172:175], v[114:117]
	v_mfma_f32_16x16x32_bf16 v[102:105], v[156:159], v[180:183], v[102:105]
	v_mfma_f32_16x16x32_bf16 v[98:101], v[164:167], v[180:183], v[98:101]
	v_mfma_f32_16x16x32_bf16 v[86:89], v[156:159], v[188:191], v[86:89]
	v_mfma_f32_16x16x32_bf16 v[82:85], v[164:167], v[188:191], v[82:85]
	v_mfma_f32_16x16x32_bf16 v[70:73], v[156:159], v[196:199], v[70:73]
	v_mfma_f32_16x16x32_bf16 v[66:69], v[164:167], v[196:199], v[66:69]
	v_mfma_f32_16x16x32_bf16 v[118:121], v[160:163], v[176:179], v[118:121]
	v_mfma_f32_16x16x32_bf16 v[114:117], v[168:171], v[176:179], v[114:117]
	v_mfma_f32_16x16x32_bf16 v[102:105], v[160:163], v[184:187], v[102:105]
	v_mfma_f32_16x16x32_bf16 v[98:101], v[168:171], v[184:187], v[98:101]
	v_mfma_f32_16x16x32_bf16 v[86:89], v[160:163], v[192:195], v[86:89]
	v_mfma_f32_16x16x32_bf16 v[82:85], v[168:171], v[192:195], v[82:85]
	v_mfma_f32_16x16x32_bf16 v[70:73], v[160:163], v[200:203], v[70:73]
	v_mfma_f32_16x16x32_bf16 v[66:69], v[168:171], v[200:203], v[66:69]
	s_barrier
	s_setprio 1
	s_add_i32 s20, s37, s57
	v_lshl_add_u64 v[204:205], s[48:49], 0, v[0:1]
	s_mov_b32 m0, s20
	ds_read_b128 v[172:175], v143 offset:16384
	ds_read_b128 v[176:179], v143 offset:17408
	ds_read_b128 v[180:183], v143 offset:18432
	ds_read_b128 v[184:187], v143 offset:19456
	ds_read_b128 v[188:191], v143 offset:20480
	ds_read_b128 v[192:195], v143 offset:21504
	ds_read_b128 v[196:199], v143 offset:22528
	ds_read_b128 v[200:203], v143 offset:23552
	global_load_lds_dwordx4 v[204:205], off
	s_add_i32 m0, s20, 0x2000
	s_add_u32 s20, s48, 0x100000
	v_lshl_add_u64 v[206:207], s[48:49], 0, v[130:131]
	s_addc_u32 s21, s49, 0
	s_add_i32 s37, s77, s57
	global_load_lds_dwordx4 v[206:207], off
	s_mov_b32 m0, s37
	v_lshl_add_u64 v[210:211], s[50:51], 0, v[130:131]
	global_load_lds_dwordx4 v0, s[20:21]
	s_add_i32 m0, s37, 0x2000
	s_nop 0
	global_load_lds_dwordx4 v130, s[20:21]
	v_lshl_add_u64 v[208:209], s[50:51], 0, v[0:1]
	s_mov_b32 m0, s58
	s_nop 0
	global_load_lds_dwordx4 v[208:209], off
	s_mov_b32 m0, s59
	s_nop 0
	global_load_lds_dwordx4 v[210:211], off
	s_setprio 0
	s_waitcnt vmcnt(8)
	s_waitcnt lgkmcnt(0)
	s_barrier
	s_waitcnt lgkmcnt(0)
	v_mfma_f32_16x16x32_bf16 v[62:65], v[136:139], v[172:175], v[62:65]
	v_mfma_f32_16x16x32_bf16 v[58:61], v[148:151], v[172:175], v[58:61]
	v_mfma_f32_16x16x32_bf16 v[46:49], v[136:139], v[180:183], v[46:49]
	v_mfma_f32_16x16x32_bf16 v[42:45], v[148:151], v[180:183], v[42:45]
	v_mfma_f32_16x16x32_bf16 v[30:33], v[136:139], v[188:191], v[30:33]
	v_mfma_f32_16x16x32_bf16 v[26:29], v[148:151], v[188:191], v[26:29]
	v_mfma_f32_16x16x32_bf16 v[14:17], v[136:139], v[196:199], v[14:17]
	v_mfma_f32_16x16x32_bf16 v[10:13], v[148:151], v[196:199], v[10:13]
	v_mfma_f32_16x16x32_bf16 v[62:65], v[144:147], v[176:179], v[62:65]
	v_mfma_f32_16x16x32_bf16 v[58:61], v[152:155], v[176:179], v[58:61]
	v_mfma_f32_16x16x32_bf16 v[46:49], v[144:147], v[184:187], v[46:49]
	v_mfma_f32_16x16x32_bf16 v[42:45], v[152:155], v[184:187], v[42:45]
	v_mfma_f32_16x16x32_bf16 v[30:33], v[144:147], v[192:195], v[30:33]
	v_mfma_f32_16x16x32_bf16 v[26:29], v[152:155], v[192:195], v[26:29]
	v_mfma_f32_16x16x32_bf16 v[14:17], v[144:147], v[200:203], v[14:17]
	v_mfma_f32_16x16x32_bf16 v[10:13], v[152:155], v[200:203], v[10:13]
	v_mfma_f32_16x16x32_bf16 v[54:57], v[156:159], v[172:175], v[54:57]
	v_mfma_f32_16x16x32_bf16 v[50:53], v[164:167], v[172:175], v[50:53]
	v_mfma_f32_16x16x32_bf16 v[38:41], v[156:159], v[180:183], v[38:41]
	v_mfma_f32_16x16x32_bf16 v[34:37], v[164:167], v[180:183], v[34:37]
	v_mfma_f32_16x16x32_bf16 v[22:25], v[156:159], v[188:191], v[22:25]
	v_mfma_f32_16x16x32_bf16 v[18:21], v[164:167], v[188:191], v[18:21]
	v_mfma_f32_16x16x32_bf16 v[6:9], v[156:159], v[196:199], v[6:9]
	v_mfma_f32_16x16x32_bf16 v[2:5], v[164:167], v[196:199], v[2:5]
	v_mfma_f32_16x16x32_bf16 v[54:57], v[160:163], v[176:179], v[54:57]
	v_mfma_f32_16x16x32_bf16 v[50:53], v[168:171], v[176:179], v[50:53]
	v_mfma_f32_16x16x32_bf16 v[38:41], v[160:163], v[184:187], v[38:41]
	v_mfma_f32_16x16x32_bf16 v[34:37], v[168:171], v[184:187], v[34:37]
	v_mfma_f32_16x16x32_bf16 v[22:25], v[160:163], v[192:195], v[22:25]
	v_mfma_f32_16x16x32_bf16 v[18:21], v[168:171], v[192:195], v[18:21]
	v_mfma_f32_16x16x32_bf16 v[6:9], v[160:163], v[200:203], v[6:9]
	v_mfma_f32_16x16x32_bf16 v[2:5], v[168:171], v[200:203], v[2:5]
	s_barrier
	s_setprio 1
	s_add_i32 s37, 0, 0x18000
	s_add_i32 s77, 0, 0x1c000
	v_add_u32_e32 v152, s37, v142
	v_add_u32_e32 v168, s77, v142
	ds_read_b128 v[136:139], v152
	ds_read_b128 v[144:147], v152 offset:1024
	ds_read_b128 v[148:151], v152 offset:2048
	ds_read_b128 v[152:155], v152 offset:3072
	ds_read_b128 v[156:159], v168
	ds_read_b128 v[160:163], v168 offset:1024
	ds_read_b128 v[164:167], v168 offset:2048
	ds_read_b128 v[168:171], v168 offset:3072
	s_add_u32 s20, s50, 0x100000
	s_addc_u32 s21, s51, 0
	s_mov_b32 m0, s60
	ds_read_b128 v[172:175], v143 offset:32768
	ds_read_b128 v[176:179], v143 offset:33792
	ds_read_b128 v[180:183], v143 offset:34816
	ds_read_b128 v[184:187], v143 offset:35840
	ds_read_b128 v[188:191], v143 offset:36864
	ds_read_b128 v[192:195], v143 offset:37888
	ds_read_b128 v[196:199], v143 offset:38912
	ds_read_b128 v[200:203], v143 offset:39936
	global_load_lds_dwordx4 v0, s[20:21]
	v_lshl_add_u64 v[214:215], s[20:21], 0, v[130:131]
	s_mov_b32 m0, s61
	s_nop 0
	global_load_lds_dwordx4 v[214:215], off
	s_setprio 0
	s_waitcnt vmcnt(8)
	s_waitcnt lgkmcnt(0)
	s_barrier
	s_waitcnt lgkmcnt(0)
	v_mfma_f32_16x16x32_bf16 v[126:129], v[136:139], v[172:175], v[126:129]
	v_mfma_f32_16x16x32_bf16 v[122:125], v[148:151], v[172:175], v[122:125]
	v_mfma_f32_16x16x32_bf16 v[110:113], v[136:139], v[180:183], v[110:113]
	v_mfma_f32_16x16x32_bf16 v[106:109], v[148:151], v[180:183], v[106:109]
	v_mfma_f32_16x16x32_bf16 v[94:97], v[136:139], v[188:191], v[94:97]
	v_mfma_f32_16x16x32_bf16 v[90:93], v[148:151], v[188:191], v[90:93]
	v_mfma_f32_16x16x32_bf16 v[78:81], v[136:139], v[196:199], v[78:81]
	v_mfma_f32_16x16x32_bf16 v[74:77], v[148:151], v[196:199], v[74:77]
	v_mfma_f32_16x16x32_bf16 v[126:129], v[144:147], v[176:179], v[126:129]
	v_mfma_f32_16x16x32_bf16 v[122:125], v[152:155], v[176:179], v[122:125]
	v_mfma_f32_16x16x32_bf16 v[110:113], v[144:147], v[184:187], v[110:113]
	v_mfma_f32_16x16x32_bf16 v[106:109], v[152:155], v[184:187], v[106:109]
	v_mfma_f32_16x16x32_bf16 v[94:97], v[144:147], v[192:195], v[94:97]
	v_mfma_f32_16x16x32_bf16 v[90:93], v[152:155], v[192:195], v[90:93]
	v_mfma_f32_16x16x32_bf16 v[78:81], v[144:147], v[200:203], v[78:81]
	v_mfma_f32_16x16x32_bf16 v[74:77], v[152:155], v[200:203], v[74:77]
	v_mfma_f32_16x16x32_bf16 v[118:121], v[156:159], v[172:175], v[118:121]
	v_mfma_f32_16x16x32_bf16 v[114:117], v[164:167], v[172:175], v[114:117]
	v_mfma_f32_16x16x32_bf16 v[102:105], v[156:159], v[180:183], v[102:105]
	v_mfma_f32_16x16x32_bf16 v[98:101], v[164:167], v[180:183], v[98:101]
	v_mfma_f32_16x16x32_bf16 v[86:89], v[156:159], v[188:191], v[86:89]
	v_mfma_f32_16x16x32_bf16 v[82:85], v[164:167], v[188:191], v[82:85]
	v_mfma_f32_16x16x32_bf16 v[70:73], v[156:159], v[196:199], v[70:73]
	v_mfma_f32_16x16x32_bf16 v[66:69], v[164:167], v[196:199], v[66:69]
	v_mfma_f32_16x16x32_bf16 v[118:121], v[160:163], v[176:179], v[118:121]
	v_mfma_f32_16x16x32_bf16 v[114:117], v[168:171], v[176:179], v[114:117]
	v_mfma_f32_16x16x32_bf16 v[102:105], v[160:163], v[184:187], v[102:105]
	v_mfma_f32_16x16x32_bf16 v[98:101], v[168:171], v[184:187], v[98:101]
	v_mfma_f32_16x16x32_bf16 v[86:89], v[160:163], v[192:195], v[86:89]
	v_mfma_f32_16x16x32_bf16 v[82:85], v[168:171], v[192:195], v[82:85]
	v_mfma_f32_16x16x32_bf16 v[70:73], v[160:163], v[200:203], v[70:73]
	v_mfma_f32_16x16x32_bf16 v[66:69], v[168:171], v[200:203], v[66:69]
	s_barrier
	s_setprio 1
	s_add_i32 s20, s37, s57
	v_lshl_add_u64 v[204:205], v[204:205], 0, s[24:25]
	s_mov_b32 m0, s20
	ds_read_b128 v[172:175], v143 offset:49152
	ds_read_b128 v[176:179], v143 offset:50176
	ds_read_b128 v[180:183], v143 offset:51200
	ds_read_b128 v[184:187], v143 offset:52224
	ds_read_b128 v[188:191], v143 offset:53248
	ds_read_b128 v[192:195], v143 offset:54272
	ds_read_b128 v[196:199], v143 offset:55296
	ds_read_b128 v[200:203], v143 offset:56320
	global_load_lds_dwordx4 v[204:205], off
	s_add_i32 m0, s20, 0x2000
	s_add_u32 s20, s48, 0x100080
	v_lshl_add_u64 v[204:205], v[206:207], 0, s[24:25]
	s_addc_u32 s21, s49, 0
	s_add_i32 s37, s77, s57
	global_load_lds_dwordx4 v[204:205], off
	s_mov_b32 m0, s37
	s_nop 0
	global_load_lds_dwordx4 v0, s[20:21]
	s_add_i32 m0, s37, 0x2000
	s_nop 0
	global_load_lds_dwordx4 v130, s[20:21]
	v_lshl_add_u64 v[204:205], v[208:209], 0, s[24:25]
	s_mov_b32 m0, s65
	s_nop 0
	global_load_lds_dwordx4 v[204:205], off
	v_lshl_add_u64 v[204:205], v[210:211], 0, s[24:25]
	s_mov_b32 m0, s66
	s_nop 0
	global_load_lds_dwordx4 v[204:205], off
	s_setprio 0
	s_waitcnt vmcnt(8)
	s_waitcnt lgkmcnt(0)
	s_barrier
	s_waitcnt lgkmcnt(0)
	v_mfma_f32_16x16x32_bf16 v[62:65], v[136:139], v[172:175], v[62:65]
	v_mfma_f32_16x16x32_bf16 v[58:61], v[148:151], v[172:175], v[58:61]
	v_mfma_f32_16x16x32_bf16 v[46:49], v[136:139], v[180:183], v[46:49]
	v_mfma_f32_16x16x32_bf16 v[42:45], v[148:151], v[180:183], v[42:45]
	v_mfma_f32_16x16x32_bf16 v[30:33], v[136:139], v[188:191], v[30:33]
	v_mfma_f32_16x16x32_bf16 v[26:29], v[148:151], v[188:191], v[26:29]
	v_mfma_f32_16x16x32_bf16 v[14:17], v[136:139], v[196:199], v[14:17]
	v_mfma_f32_16x16x32_bf16 v[10:13], v[148:151], v[196:199], v[10:13]
	v_mfma_f32_16x16x32_bf16 v[62:65], v[144:147], v[176:179], v[62:65]
	v_mfma_f32_16x16x32_bf16 v[58:61], v[152:155], v[176:179], v[58:61]
	v_mfma_f32_16x16x32_bf16 v[46:49], v[144:147], v[184:187], v[46:49]
	v_mfma_f32_16x16x32_bf16 v[42:45], v[152:155], v[184:187], v[42:45]
	v_mfma_f32_16x16x32_bf16 v[30:33], v[144:147], v[192:195], v[30:33]
	v_mfma_f32_16x16x32_bf16 v[26:29], v[152:155], v[192:195], v[26:29]
	v_mfma_f32_16x16x32_bf16 v[14:17], v[144:147], v[200:203], v[14:17]
	v_mfma_f32_16x16x32_bf16 v[10:13], v[152:155], v[200:203], v[10:13]
	v_mfma_f32_16x16x32_bf16 v[54:57], v[156:159], v[172:175], v[54:57]
	v_mfma_f32_16x16x32_bf16 v[50:53], v[164:167], v[172:175], v[50:53]
	v_mfma_f32_16x16x32_bf16 v[38:41], v[156:159], v[180:183], v[38:41]
	v_mfma_f32_16x16x32_bf16 v[34:37], v[164:167], v[180:183], v[34:37]
	v_mfma_f32_16x16x32_bf16 v[22:25], v[156:159], v[188:191], v[22:25]
	v_mfma_f32_16x16x32_bf16 v[18:21], v[164:167], v[188:191], v[18:21]
	v_mfma_f32_16x16x32_bf16 v[6:9], v[156:159], v[196:199], v[6:9]
	v_mfma_f32_16x16x32_bf16 v[2:5], v[164:167], v[196:199], v[2:5]
	v_mfma_f32_16x16x32_bf16 v[54:57], v[160:163], v[176:179], v[54:57]
	v_mfma_f32_16x16x32_bf16 v[50:53], v[168:171], v[176:179], v[50:53]
	v_mfma_f32_16x16x32_bf16 v[38:41], v[160:163], v[184:187], v[38:41]
	v_mfma_f32_16x16x32_bf16 v[34:37], v[168:171], v[184:187], v[34:37]
	v_mfma_f32_16x16x32_bf16 v[22:25], v[160:163], v[192:195], v[22:25]
	v_mfma_f32_16x16x32_bf16 v[18:21], v[168:171], v[192:195], v[18:21]
	v_mfma_f32_16x16x32_bf16 v[6:9], v[160:163], v[200:203], v[6:9]
	v_mfma_f32_16x16x32_bf16 v[2:5], v[168:171], v[200:203], v[2:5]
	s_barrier
	s_setprio 1
	s_add_i32 s73, s73, 2
	s_add_u32 s4, s4, 0x100
	s_addc_u32 s5, s5, 0
	s_add_u32 s71, s71, 0x100
	s_addc_u32 s72, s72, 0
	s_cmp_gt_u32 s73, 61
	s_cbranch_scc0 .LBB0_2540
	s_and_b64 vcc, exec, s[18:19]
	s_cbranch_vccz .LBB0_2543
	s_barrier
